# v21 + K-loop load segments: all fragment ds_read_b128 of a segment issued back to back ahead of the scalar address work (m0 write / DMA wait state kept by ordering)
# baseline (speedup 1.0000x reference)
; #define PG8_STAGE(bufoff, gbase, voff) do { _Pragma("unroll") for (int _i = 0; _i < 2; ++_i) \
;         __builtin_amdgcn_global_load_lds((const unsigned*)((const char*)(gbase) + (voff)[_i]), (PG8_LAS unsigned*)(lds + (bufoff) + ldsw + _i * 8192), 16, 0, 0); } while (0)
; #define PG8_WAIT_V(n) asm volatile("s_waitcnt vmcnt(" #n ")" ::: "memory")
; #define PG8_WAIT_L(n) asm volatile("s_waitcnt lgkmcnt(" #n ")" ::: "memory")
; #define PG8_BAR __builtin_amdgcn_s_barrier()
; #define PG8_SCHED __builtin_amdgcn_sched_barrier(0)
;     __device__ __forceinline__ int nt(const pg8::Unit& u) const { return u.kind == 0 ? ntiles : q_nt(u.kind - 1); }
; template <class Epi, class Sched, bool ALIGN_EPI = true, bool SP2 = true>
; __device__ __forceinline__ void gemm_phase(PG8_LAS unsigned char* lds, const int K  , const Sched& S, const Epi& E) {
;     ...
;         for (int t = 0; t < nt; t += 2) {
;             const bool last = (t == nt - 2);
;             const char* a1 = cA + (size_t)(t + 1) * kstep;
;             const char* a2 = last ? nA : cA + (size_t)(t + 2) * kstep; const char* b2 = last ? nB : cB + (size_t)(t + 2) * kstep;
;             const char* a3 = a2 + kstep; const char* b3 = b2 + kstep;
;             if constexpr (SP2) {
;             PG8_LDB(B0, 0, 0); PG8_LDB(B1, 0, 1); PG8_SCHED; PG8_LDA(At, 0, 0); PG8_STAGE(PG8_SA(1, 1), a1 + hstep, voffA);
;             PG8_WAIT_V(8); PG8_WAIT_L(0); PG8_BAR; PG8_MMA(0, 0, At, B0); PG8_MMA(0, 1, At, B1); PG8_BAR; PG8_SCHED;
;             PG8_LDA(At, 0, 1); PG8_STAGE(PG8_SB(0, 0), b2, voffB); PG8_STAGE(PG8_SB(0, 1), b2 + hstep, voffB); PG8_STAGE(PG8_SA(0, 0), a2, voffA);
.LBB0_219:
	ds_read_b128 v[148:151], v154
	ds_read_b128 v[160:163], v154 offset:1024
	ds_read_b128 v[164:167], v154 offset:2048
	ds_read_b128 v[168:171], v154 offset:3072
	ds_read_b128 v[172:175], v155
	ds_read_b128 v[176:179], v155 offset:1024
	ds_read_b128 v[180:183], v155 offset:2048
	ds_read_b128 v[184:187], v155 offset:3072
	ds_read_b128 v[188:191], v156
	ds_read_b128 v[192:195], v156 offset:1024
	ds_read_b128 v[196:199], v156 offset:2048
	ds_read_b128 v[200:203], v156 offset:3072
	ds_read_b128 v[204:207], v156 offset:4096
	ds_read_b128 v[208:211], v156 offset:5120
	ds_read_b128 v[212:215], v156 offset:6144
	ds_read_b128 v[216:219], v156 offset:7168
	s_add_u32 s22, s20, 0xfff80080
	s_addc_u32 s23, s21, -1
	s_cmp_eq_u32 s48, 28
	s_cselect_b32 s25, s13, s23
	s_cselect_b32 s24, s44, s22
	s_cselect_b32 s23, s11, s47
	s_cselect_b32 s22, s45, s46
	s_add_i32 m0, s19, 0xc000
	v_lshl_add_u64 v[220:221], s[20:21], 0, v[140:141]
	global_load_lds_dwordx4 v[220:221], off
	v_lshl_add_u64 v[220:221], s[20:21], 0, v[142:143]
	s_add_i32 m0, s19, 0xe000
	s_nop 0
	global_load_lds_dwordx4 v[220:221], off
	s_waitcnt vmcnt(8)
	s_waitcnt lgkmcnt(0)
	s_setprio 1
	s_barrier
	v_mfma_f32_16x16x32_bf16 v[126:129], v[148:151], v[188:191], v[126:129]
	v_mfma_f32_16x16x32_bf16 v[118:121], v[164:167], v[188:191], v[118:121]
	v_mfma_f32_16x16x32_bf16 v[110:113], v[148:151], v[196:199], v[110:113]
	v_mfma_f32_16x16x32_bf16 v[102:105], v[164:167], v[196:199], v[102:105]
	v_mfma_f32_16x16x32_bf16 v[94:97], v[148:151], v[204:207], v[94:97]
	v_mfma_f32_16x16x32_bf16 v[86:89], v[164:167], v[204:207], v[86:89]
	v_mfma_f32_16x16x32_bf16 v[78:81], v[148:151], v[212:215], v[78:81]
	v_mfma_f32_16x16x32_bf16 v[70:73], v[164:167], v[212:215], v[70:73]
	v_mfma_f32_16x16x32_bf16 v[126:129], v[160:163], v[192:195], v[126:129]
	v_mfma_f32_16x16x32_bf16 v[118:121], v[168:171], v[192:195], v[118:121]
	v_mfma_f32_16x16x32_bf16 v[110:113], v[160:163], v[200:203], v[110:113]
	v_mfma_f32_16x16x32_bf16 v[102:105], v[168:171], v[200:203], v[102:105]
	v_mfma_f32_16x16x32_bf16 v[94:97], v[160:163], v[208:211], v[94:97]
	v_mfma_f32_16x16x32_bf16 v[86:89], v[168:171], v[208:211], v[86:89]
	v_mfma_f32_16x16x32_bf16 v[78:81], v[160:163], v[216:219], v[78:81]
	v_mfma_f32_16x16x32_bf16 v[70:73], v[168:171], v[216:219], v[70:73]
	s_setprio 0
	s_setprio 1
	v_mfma_f32_16x16x32_bf16 v[122:125], v[172:175], v[188:191], v[122:125]
	v_mfma_f32_16x16x32_bf16 v[114:117], v[180:183], v[188:191], v[114:117]
	v_mfma_f32_16x16x32_bf16 v[106:109], v[172:175], v[196:199], v[106:109]
	v_mfma_f32_16x16x32_bf16 v[98:101], v[180:183], v[196:199], v[98:101]
	v_mfma_f32_16x16x32_bf16 v[90:93], v[172:175], v[204:207], v[90:93]
	v_mfma_f32_16x16x32_bf16 v[82:85], v[180:183], v[204:207], v[82:85]
	v_mfma_f32_16x16x32_bf16 v[74:77], v[172:175], v[212:215], v[74:77]
	v_mfma_f32_16x16x32_bf16 v[66:69], v[180:183], v[212:215], v[66:69]
	v_mfma_f32_16x16x32_bf16 v[122:125], v[176:179], v[192:195], v[122:125]
	v_mfma_f32_16x16x32_bf16 v[114:117], v[184:187], v[192:195], v[114:117]
	v_mfma_f32_16x16x32_bf16 v[106:109], v[176:179], v[200:203], v[106:109]
	v_mfma_f32_16x16x32_bf16 v[98:101], v[184:187], v[200:203], v[98:101]
	v_mfma_f32_16x16x32_bf16 v[90:93], v[176:179], v[208:211], v[90:93]
	v_mfma_f32_16x16x32_bf16 v[82:85], v[184:187], v[208:211], v[82:85]
	v_mfma_f32_16x16x32_bf16 v[74:77], v[176:179], v[216:219], v[74:77]
	v_mfma_f32_16x16x32_bf16 v[66:69], v[184:187], v[216:219], v[66:69]
	s_barrier
	s_setprio 0
	s_add_i32 s49, s39, s29
	v_lshl_add_u64 v[220:221], s[22:23], 0, v[136:137]
	s_mov_b32 m0, s49
	ds_read_b128 v[188:191], v156 offset:16384
	ds_read_b128 v[192:195], v156 offset:17408
	ds_read_b128 v[196:199], v156 offset:18432
	ds_read_b128 v[200:203], v156 offset:19456
	ds_read_b128 v[204:207], v156 offset:20480
	ds_read_b128 v[208:211], v156 offset:21504
	ds_read_b128 v[212:215], v156 offset:22528
	ds_read_b128 v[216:219], v156 offset:23552
	global_load_lds_dwordx4 v[220:221], off
	s_add_i32 m0, s49, 0x2000
	s_add_u32 s50, s22, 0x80000
	v_lshl_add_u64 v[222:223], s[22:23], 0, v[132:133]
	s_addc_u32 s51, s23, 0
	s_add_i32 s49, s40, s29
	global_load_lds_dwordx4 v[222:223], off
	v_lshl_add_u64 v[224:225], s[50:51], 0, v[136:137]
	s_mov_b32 m0, s49
	v_lshl_add_u64 v[226:227], s[24:25], 0, v[134:135]
	global_load_lds_dwordx4 v[224:225], off
	v_lshl_add_u64 v[224:225], s[50:51], 0, v[132:133]
	s_add_i32 m0, s49, 0x2000
	s_nop 0
	global_load_lds_dwordx4 v[224:225], off
	v_lshl_add_u64 v[224:225], s[24:25], 0, v[138:139]
	s_mov_b32 m0, s19
	s_nop 0
	global_load_lds_dwordx4 v[224:225], off
	s_mov_b32 m0, s31
	s_nop 0
	global_load_lds_dwordx4 v[226:227], off
	s_waitcnt vmcnt(8)
	s_waitcnt lgkmcnt(0)
	s_setprio 1
	s_barrier
; #define PG8_STAGE(bufoff, gbase, voff) do { _Pragma("unroll") for (int _i = 0; _i < 2; ++_i) \
;         __builtin_amdgcn_global_load_lds((const unsigned*)((const char*)(gbase) + (voff)[_i]), (PG8_LAS unsigned*)(lds + (bufoff) + ldsw + _i * 8192), 16, 0, 0); } while (0)
; #define PG8_WAIT_V(n) asm volatile("s_waitcnt vmcnt(" #n ")" ::: "memory")
; #define PG8_WAIT_L(n) asm volatile("s_waitcnt lgkmcnt(" #n ")" ::: "memory")
; #define PG8_BAR __builtin_amdgcn_s_barrier()
; #define PG8_SCHED __builtin_amdgcn_sched_barrier(0)
; template <class Epi, class Sched, bool ALIGN_EPI = true, bool SP2 = true>
; __device__ __forceinline__ void gemm_phase(PG8_LAS unsigned char* lds, const int K  , const Sched& S, const Epi& E) {
;     ...
;             PG8_WAIT_V(8); PG8_WAIT_L(0); PG8_BAR; PG8_MMA(1, 0, At, B0); PG8_MMA(1, 1, At, B1); PG8_BAR; PG8_SCHED;
;             PG8_LDB(B0, 1, 0); PG8_LDB(B1, 1, 1); PG8_SCHED; PG8_LDA(At, 1, 0); PG8_STAGE(PG8_SA(0, 1), a2 + hstep, voffA);
;             PG8_WAIT_V(8); PG8_WAIT_L(0); PG8_BAR; PG8_MMA(0, 0, At, B0); PG8_MMA(0, 1, At, B1); PG8_BAR; PG8_SCHED;
	v_mfma_f32_16x16x32_bf16 v[62:65], v[148:151], v[188:191], v[62:65]
	v_mfma_f32_16x16x32_bf16 v[54:57], v[164:167], v[188:191], v[54:57]
	v_mfma_f32_16x16x32_bf16 v[46:49], v[148:151], v[196:199], v[46:49]
	v_mfma_f32_16x16x32_bf16 v[38:41], v[164:167], v[196:199], v[38:41]
	v_mfma_f32_16x16x32_bf16 v[30:33], v[148:151], v[204:207], v[30:33]
	v_mfma_f32_16x16x32_bf16 v[22:25], v[164:167], v[204:207], v[22:25]
	v_mfma_f32_16x16x32_bf16 v[14:17], v[148:151], v[212:215], v[14:17]
	v_mfma_f32_16x16x32_bf16 v[6:9], v[164:167], v[212:215], v[6:9]
	v_mfma_f32_16x16x32_bf16 v[62:65], v[160:163], v[192:195], v[62:65]
	v_mfma_f32_16x16x32_bf16 v[54:57], v[168:171], v[192:195], v[54:57]
	v_mfma_f32_16x16x32_bf16 v[46:49], v[160:163], v[200:203], v[46:49]
	v_mfma_f32_16x16x32_bf16 v[38:41], v[168:171], v[200:203], v[38:41]
	v_mfma_f32_16x16x32_bf16 v[30:33], v[160:163], v[208:211], v[30:33]
	v_mfma_f32_16x16x32_bf16 v[22:25], v[168:171], v[208:211], v[22:25]
	v_mfma_f32_16x16x32_bf16 v[14:17], v[160:163], v[216:219], v[14:17]
	v_mfma_f32_16x16x32_bf16 v[6:9], v[168:171], v[216:219], v[6:9]
	s_setprio 0
	s_setprio 1
	v_mfma_f32_16x16x32_bf16 v[58:61], v[172:175], v[188:191], v[58:61]
	v_mfma_f32_16x16x32_bf16 v[50:53], v[180:183], v[188:191], v[50:53]
	v_mfma_f32_16x16x32_bf16 v[42:45], v[172:175], v[196:199], v[42:45]
	v_mfma_f32_16x16x32_bf16 v[34:37], v[180:183], v[196:199], v[34:37]
	v_mfma_f32_16x16x32_bf16 v[26:29], v[172:175], v[204:207], v[26:29]
	v_mfma_f32_16x16x32_bf16 v[18:21], v[180:183], v[204:207], v[18:21]
	v_mfma_f32_16x16x32_bf16 v[10:13], v[172:175], v[212:215], v[10:13]
	v_mfma_f32_16x16x32_bf16 v[2:5], v[180:183], v[212:215], v[2:5]
	v_mfma_f32_16x16x32_bf16 v[58:61], v[176:179], v[192:195], v[58:61]
	v_mfma_f32_16x16x32_bf16 v[50:53], v[184:187], v[192:195], v[50:53]
	v_mfma_f32_16x16x32_bf16 v[42:45], v[176:179], v[200:203], v[42:45]
	v_mfma_f32_16x16x32_bf16 v[34:37], v[184:187], v[200:203], v[34:37]
	v_mfma_f32_16x16x32_bf16 v[26:29], v[176:179], v[208:211], v[26:29]
	v_mfma_f32_16x16x32_bf16 v[18:21], v[184:187], v[208:211], v[18:21]
	v_mfma_f32_16x16x32_bf16 v[10:13], v[176:179], v[216:219], v[10:13]
	v_mfma_f32_16x16x32_bf16 v[2:5], v[184:187], v[216:219], v[2:5]
	s_barrier
	s_setprio 0
	s_add_i32 s49, 0, 0x18000
	v_add_u32_e32 v159, s49, v152
	s_add_i32 s50, 0, 0x1c000
	ds_read_b128 v[148:151], v159
	ds_read_b128 v[160:163], v159 offset:1024
	ds_read_b128 v[164:167], v159 offset:2048
	ds_read_b128 v[168:171], v159 offset:3072
	v_add_u32_e32 v159, s50, v152
	ds_read_b128 v[172:175], v159
	ds_read_b128 v[176:179], v159 offset:1024
	ds_read_b128 v[180:183], v159 offset:2048
	ds_read_b128 v[184:187], v159 offset:3072
	ds_read_b128 v[188:191], v156 offset:32768
	ds_read_b128 v[192:195], v156 offset:33792
	ds_read_b128 v[196:199], v156 offset:34816
	ds_read_b128 v[200:203], v156 offset:35840
	ds_read_b128 v[204:207], v156 offset:36864
	ds_read_b128 v[208:211], v156 offset:37888
	ds_read_b128 v[212:215], v156 offset:38912
	ds_read_b128 v[216:219], v156 offset:39936
	s_add_u32 s24, s24, 0x80000
	s_addc_u32 s25, s25, 0
	s_mov_b32 m0, s33
	v_lshl_add_u64 v[230:231], s[24:25], 0, v[138:139]
	global_load_lds_dwordx4 v[230:231], off
	v_lshl_add_u64 v[230:231], s[24:25], 0, v[134:135]
	s_mov_b32 m0, s34
	s_nop 0
	global_load_lds_dwordx4 v[230:231], off
	s_waitcnt vmcnt(8)
	s_waitcnt lgkmcnt(0)
	s_setprio 1
	s_barrier
	v_mfma_f32_16x16x32_bf16 v[126:129], v[148:151], v[188:191], v[126:129]
	v_mfma_f32_16x16x32_bf16 v[118:121], v[164:167], v[188:191], v[118:121]
	v_mfma_f32_16x16x32_bf16 v[110:113], v[148:151], v[196:199], v[110:113]
	v_mfma_f32_16x16x32_bf16 v[102:105], v[164:167], v[196:199], v[102:105]
	v_mfma_f32_16x16x32_bf16 v[94:97], v[148:151], v[204:207], v[94:97]
	v_mfma_f32_16x16x32_bf16 v[86:89], v[164:167], v[204:207], v[86:89]
	v_mfma_f32_16x16x32_bf16 v[78:81], v[148:151], v[212:215], v[78:81]
	v_mfma_f32_16x16x32_bf16 v[70:73], v[164:167], v[212:215], v[70:73]
	v_mfma_f32_16x16x32_bf16 v[126:129], v[160:163], v[192:195], v[126:129]
	v_mfma_f32_16x16x32_bf16 v[118:121], v[168:171], v[192:195], v[118:121]
	v_mfma_f32_16x16x32_bf16 v[110:113], v[160:163], v[200:203], v[110:113]
	v_mfma_f32_16x16x32_bf16 v[102:105], v[168:171], v[200:203], v[102:105]
	v_mfma_f32_16x16x32_bf16 v[94:97], v[160:163], v[208:211], v[94:97]
	v_mfma_f32_16x16x32_bf16 v[86:89], v[168:171], v[208:211], v[86:89]
	v_mfma_f32_16x16x32_bf16 v[78:81], v[160:163], v[216:219], v[78:81]
	v_mfma_f32_16x16x32_bf16 v[70:73], v[168:171], v[216:219], v[70:73]
	s_setprio 0
	s_setprio 1
	v_mfma_f32_16x16x32_bf16 v[122:125], v[172:175], v[188:191], v[122:125]
	v_mfma_f32_16x16x32_bf16 v[114:117], v[180:183], v[188:191], v[114:117]
	v_mfma_f32_16x16x32_bf16 v[106:109], v[172:175], v[196:199], v[106:109]
	v_mfma_f32_16x16x32_bf16 v[98:101], v[180:183], v[196:199], v[98:101]
	v_mfma_f32_16x16x32_bf16 v[90:93], v[172:175], v[204:207], v[90:93]
	v_mfma_f32_16x16x32_bf16 v[82:85], v[180:183], v[204:207], v[82:85]
	v_mfma_f32_16x16x32_bf16 v[74:77], v[172:175], v[212:215], v[74:77]
	v_mfma_f32_16x16x32_bf16 v[66:69], v[180:183], v[212:215], v[66:69]
	v_mfma_f32_16x16x32_bf16 v[122:125], v[176:179], v[192:195], v[122:125]
	v_mfma_f32_16x16x32_bf16 v[114:117], v[184:187], v[192:195], v[114:117]
	v_mfma_f32_16x16x32_bf16 v[106:109], v[176:179], v[200:203], v[106:109]
	v_mfma_f32_16x16x32_bf16 v[98:101], v[184:187], v[200:203], v[98:101]
	v_mfma_f32_16x16x32_bf16 v[90:93], v[176:179], v[208:211], v[90:93]
	v_mfma_f32_16x16x32_bf16 v[82:85], v[184:187], v[208:211], v[82:85]
	v_mfma_f32_16x16x32_bf16 v[74:77], v[176:179], v[216:219], v[74:77]
	v_mfma_f32_16x16x32_bf16 v[66:69], v[184:187], v[216:219], v[66:69]
	s_barrier
; #define PG8_STAGE(bufoff, gbase, voff) do { _Pragma("unroll") for (int _i = 0; _i < 2; ++_i) \
;         __builtin_amdgcn_global_load_lds((const unsigned*)((const char*)(gbase) + (voff)[_i]), (PG8_LAS unsigned*)(lds + (bufoff) + ldsw + _i * 8192), 16, 0, 0); } while (0)
; #define PG8_WAIT_V(n) asm volatile("s_waitcnt vmcnt(" #n ")" ::: "memory")
; #define PG8_WAIT_L(n) asm volatile("s_waitcnt lgkmcnt(" #n ")" ::: "memory")
; #define PG8_BAR __builtin_amdgcn_s_barrier()
; #define PG8_SCHED __builtin_amdgcn_sched_barrier(0)
; template <class Epi, class Sched, bool ALIGN_EPI = true, bool SP2 = true>
; __device__ __forceinline__ void gemm_phase(PG8_LAS unsigned char* lds, const int K  , const Sched& S, const Epi& E) {
;     ...
;             PG8_LDA(At, 1, 1); PG8_STAGE(PG8_SB(1, 0), b3, voffB); PG8_STAGE(PG8_SB(1, 1), b3 + hstep, voffB); PG8_STAGE(PG8_SA(1, 0), a3, voffA);
;             PG8_WAIT_V(8); PG8_WAIT_L(0); PG8_BAR; PG8_MMA(1, 0, At, B0); PG8_MMA(1, 1, At, B1); PG8_BAR; PG8_SCHED;
	s_setprio 0
	s_add_i32 s24, s49, s29
	v_lshl_add_u64 v[220:221], v[220:221], 0, s[6:7]
	s_mov_b32 m0, s24
	ds_read_b128 v[188:191], v156 offset:49152
	ds_read_b128 v[192:195], v156 offset:50176
	ds_read_b128 v[196:199], v156 offset:51200
	ds_read_b128 v[200:203], v156 offset:52224
	ds_read_b128 v[204:207], v156 offset:53248
	ds_read_b128 v[208:211], v156 offset:54272
	ds_read_b128 v[212:215], v156 offset:55296
	ds_read_b128 v[216:219], v156 offset:56320
	global_load_lds_dwordx4 v[220:221], off
	s_add_i32 m0, s24, 0x2000
	s_add_u32 s22, s22, 0x80080
	v_lshl_add_u64 v[220:221], v[222:223], 0, s[6:7]
	s_addc_u32 s23, s23, 0
	s_add_i32 s24, s50, s29
	global_load_lds_dwordx4 v[220:221], off
	v_lshl_add_u64 v[220:221], s[22:23], 0, v[136:137]
	s_mov_b32 m0, s24
	s_nop 0
	global_load_lds_dwordx4 v[220:221], off
	v_lshl_add_u64 v[220:221], s[22:23], 0, v[132:133]
	s_add_i32 m0, s24, 0x2000
	s_nop 0
	global_load_lds_dwordx4 v[220:221], off
	v_lshl_add_u64 v[220:221], v[224:225], 0, s[6:7]
	s_mov_b32 m0, s36
	s_nop 0
	global_load_lds_dwordx4 v[220:221], off
	v_lshl_add_u64 v[220:221], v[226:227], 0, s[6:7]
	s_mov_b32 m0, s37
	s_nop 0
	global_load_lds_dwordx4 v[220:221], off
	s_waitcnt vmcnt(8)
	s_waitcnt lgkmcnt(0)
	s_setprio 1
	s_barrier
	v_mfma_f32_16x16x32_bf16 v[62:65], v[148:151], v[188:191], v[62:65]
	v_mfma_f32_16x16x32_bf16 v[54:57], v[164:167], v[188:191], v[54:57]
	v_mfma_f32_16x16x32_bf16 v[46:49], v[148:151], v[196:199], v[46:49]
	v_mfma_f32_16x16x32_bf16 v[38:41], v[164:167], v[196:199], v[38:41]
	v_mfma_f32_16x16x32_bf16 v[30:33], v[148:151], v[204:207], v[30:33]
	v_mfma_f32_16x16x32_bf16 v[22:25], v[164:167], v[204:207], v[22:25]
	v_mfma_f32_16x16x32_bf16 v[14:17], v[148:151], v[212:215], v[14:17]
	v_mfma_f32_16x16x32_bf16 v[6:9], v[164:167], v[212:215], v[6:9]
	v_mfma_f32_16x16x32_bf16 v[62:65], v[160:163], v[192:195], v[62:65]
	v_mfma_f32_16x16x32_bf16 v[54:57], v[168:171], v[192:195], v[54:57]
	v_mfma_f32_16x16x32_bf16 v[46:49], v[160:163], v[200:203], v[46:49]
	v_mfma_f32_16x16x32_bf16 v[38:41], v[168:171], v[200:203], v[38:41]
	v_mfma_f32_16x16x32_bf16 v[30:33], v[160:163], v[208:211], v[30:33]
	v_mfma_f32_16x16x32_bf16 v[22:25], v[168:171], v[208:211], v[22:25]
	v_mfma_f32_16x16x32_bf16 v[14:17], v[160:163], v[216:219], v[14:17]
	v_mfma_f32_16x16x32_bf16 v[6:9], v[168:171], v[216:219], v[6:9]
	s_setprio 0
	s_setprio 1
	v_mfma_f32_16x16x32_bf16 v[58:61], v[172:175], v[188:191], v[58:61]
	v_mfma_f32_16x16x32_bf16 v[50:53], v[180:183], v[188:191], v[50:53]
	v_mfma_f32_16x16x32_bf16 v[42:45], v[172:175], v[196:199], v[42:45]
	v_mfma_f32_16x16x32_bf16 v[34:37], v[180:183], v[196:199], v[34:37]
	v_mfma_f32_16x16x32_bf16 v[26:29], v[172:175], v[204:207], v[26:29]
	v_mfma_f32_16x16x32_bf16 v[18:21], v[180:183], v[204:207], v[18:21]
	v_mfma_f32_16x16x32_bf16 v[10:13], v[172:175], v[212:215], v[10:13]
	v_mfma_f32_16x16x32_bf16 v[2:5], v[180:183], v[212:215], v[2:5]
	v_mfma_f32_16x16x32_bf16 v[58:61], v[176:179], v[192:195], v[58:61]
	v_mfma_f32_16x16x32_bf16 v[50:53], v[184:187], v[192:195], v[50:53]
	v_mfma_f32_16x16x32_bf16 v[42:45], v[176:179], v[200:203], v[42:45]
	v_mfma_f32_16x16x32_bf16 v[34:37], v[184:187], v[200:203], v[34:37]
	v_mfma_f32_16x16x32_bf16 v[26:29], v[176:179], v[208:211], v[26:29]
	v_mfma_f32_16x16x32_bf16 v[18:21], v[184:187], v[208:211], v[18:21]
	v_mfma_f32_16x16x32_bf16 v[10:13], v[176:179], v[216:219], v[10:13]
	v_mfma_f32_16x16x32_bf16 v[2:5], v[184:187], v[216:219], v[2:5]
	s_barrier
	s_setprio 0
	s_add_i32 s48, s48, 2
	s_add_u32 s20, s20, 0x100
	s_addc_u32 s21, s21, 0
	s_add_u32 s46, s46, 0x100
	s_addc_u32 s47, s47, 0
	s_cmp_gt_u32 s48, 29
	s_cbranch_scc0 .LBB0_219
	s_and_b64 vcc, exec, s[8:9]
	s_cbranch_vccz .LBB0_222
	s_barrier

; #define PG8_STAGE(bufoff, gbase, voff) do { _Pragma("unroll") for (int _i = 0; _i < 2; ++_i) \
;         __builtin_amdgcn_global_load_lds((const unsigned*)((const char*)(gbase) + (voff)[_i]), (PG8_LAS unsigned*)(lds + (bufoff) + ldsw + _i * 8192), 16, 0, 0); } while (0)
; #define PG8_WAIT_V(n) asm volatile("s_waitcnt vmcnt(" #n ")" ::: "memory")
; #define PG8_WAIT_L(n) asm volatile("s_waitcnt lgkmcnt(" #n ")" ::: "memory")
; #define PG8_BAR __builtin_amdgcn_s_barrier()
; #define PG8_SCHED __builtin_amdgcn_sched_barrier(0)
;     __device__ __forceinline__ int nt(const pg8::Unit& u) const { return u.kind == 0 ? ntiles : q_nt(u.kind - 1); }
; template <class Epi, class Sched, bool ALIGN_EPI = true, bool SP2 = true>
; __device__ __forceinline__ void gemm_phase(PG8_LAS unsigned char* lds, const int K  , const Sched& S, const Epi& E) {
;     ...
;         for (int t = 0; t < nt; t += 2) {
;             const bool last = (t == nt - 2);
;             const char* a1 = cA + (size_t)(t + 1) * kstep;
;             const char* a2 = last ? nA : cA + (size_t)(t + 2) * kstep; const char* b2 = last ? nB : cB + (size_t)(t + 2) * kstep;
;             const char* a3 = a2 + kstep; const char* b3 = b2 + kstep;
;             if constexpr (SP2) {
;             PG8_LDB(B0, 0, 0); PG8_LDB(B1, 0, 1); PG8_SCHED; PG8_LDA(At, 0, 0); PG8_STAGE(PG8_SA(1, 1), a1 + hstep, voffA);
;             PG8_WAIT_V(8); PG8_WAIT_L(0); PG8_BAR; PG8_MMA(0, 0, At, B0); PG8_MMA(0, 1, At, B1); PG8_BAR; PG8_SCHED;
;             PG8_LDA(At, 0, 1); PG8_STAGE(PG8_SB(0, 0), b2, voffB); PG8_STAGE(PG8_SB(0, 1), b2 + hstep, voffB); PG8_STAGE(PG8_SA(0, 0), a2, voffA);
;             PG8_WAIT_V(8); PG8_WAIT_L(0); PG8_BAR; PG8_MMA(1, 0, At, B0); PG8_MMA(1, 1, At, B1); PG8_BAR; PG8_SCHED;
.LBB0_393:
	ds_read_b128 v[18:21], v190
	ds_read_b128 v[22:25], v190 offset:1024
	ds_read_b128 v[26:29], v190 offset:2048
	ds_read_b128 v[30:33], v190 offset:3072
	ds_read_b128 v[2:5], v191
	ds_read_b128 v[6:9], v191 offset:1024
	ds_read_b128 v[10:13], v191 offset:2048
	ds_read_b128 v[14:17], v191 offset:3072
	ds_read_b128 v[178:181], v192
	ds_read_b128 v[182:185], v192 offset:1024
	ds_read_b128 v[194:197], v192 offset:2048
	ds_read_b128 v[198:201], v192 offset:3072
	ds_read_b128 v[202:205], v192 offset:4096
	ds_read_b128 v[206:209], v192 offset:5120
	ds_read_b128 v[210:213], v192 offset:6144
	ds_read_b128 v[214:217], v192 offset:7168
	s_add_i32 s50, s22, 2
	s_add_u32 s20, s18, 0xfff50080
	s_addc_u32 s21, s19, -1
	s_cmp_eq_u32 s47, s22
	s_cselect_b32 s22, s14, s20
	s_cselect_b32 s23, s15, s21
	s_cselect_b32 s21, s17, s49
	s_cselect_b32 s20, s16, s48
	s_add_i32 m0, s26, 0xc000
	v_lshl_add_u64 v[218:219], s[18:19], 0, v[170:171]
	global_load_lds_dwordx4 v[218:219], off
	v_lshl_add_u64 v[218:219], s[18:19], 0, v[172:173]
	s_add_i32 m0, s26, 0xe000
	s_nop 0
	global_load_lds_dwordx4 v[218:219], off
	s_waitcnt vmcnt(8)
	s_waitcnt lgkmcnt(0)
	s_setprio 1
	s_barrier
	v_mfma_scale_f32_16x16x128_f8f6f4 v[158:161], v[18:25], v[178:185], v[158:161], v186, v186 op_sel_hi:[0,0,0]
	v_mfma_scale_f32_16x16x128_f8f6f4 v[154:157], v[26:33], v[178:185], v[154:157], v186, v186 op_sel_hi:[0,0,0]
	v_mfma_scale_f32_16x16x128_f8f6f4 v[150:153], v[18:25], v[194:201], v[150:153], v186, v186 op_sel_hi:[0,0,0]
	v_mfma_scale_f32_16x16x128_f8f6f4 v[142:145], v[26:33], v[194:201], v[142:145], v186, v186 op_sel_hi:[0,0,0]
	v_mfma_scale_f32_16x16x128_f8f6f4 v[134:137], v[18:25], v[202:209], v[134:137], v186, v186 op_sel_hi:[0,0,0]
	v_mfma_scale_f32_16x16x128_f8f6f4 v[126:129], v[26:33], v[202:209], v[126:129], v186, v186 op_sel_hi:[0,0,0]
	v_mfma_scale_f32_16x16x128_f8f6f4 v[118:121], v[18:25], v[210:217], v[118:121], v186, v186 op_sel_hi:[0,0,0]
	v_mfma_scale_f32_16x16x128_f8f6f4 v[110:113], v[26:33], v[210:217], v[110:113], v186, v186 op_sel_hi:[0,0,0]
	s_setprio 0
	s_setprio 1
	v_mfma_scale_f32_16x16x128_f8f6f4 v[146:149], v[2:9], v[178:185], v[146:149], v186, v186 op_sel_hi:[0,0,0]
	v_mfma_scale_f32_16x16x128_f8f6f4 v[138:141], v[10:17], v[178:185], v[138:141], v186, v186 op_sel_hi:[0,0,0]
	v_mfma_scale_f32_16x16x128_f8f6f4 v[130:133], v[2:9], v[194:201], v[130:133], v186, v186 op_sel_hi:[0,0,0]
	v_mfma_scale_f32_16x16x128_f8f6f4 v[122:125], v[10:17], v[194:201], v[122:125], v186, v186 op_sel_hi:[0,0,0]
	v_mfma_scale_f32_16x16x128_f8f6f4 v[114:117], v[2:9], v[202:209], v[114:117], v186, v186 op_sel_hi:[0,0,0]
	v_mfma_scale_f32_16x16x128_f8f6f4 v[106:109], v[10:17], v[202:209], v[106:109], v186, v186 op_sel_hi:[0,0,0]
	v_mfma_scale_f32_16x16x128_f8f6f4 v[102:105], v[2:9], v[210:217], v[102:105], v186, v186 op_sel_hi:[0,0,0]
	v_mfma_scale_f32_16x16x128_f8f6f4 v[98:101], v[10:17], v[210:217], v[98:101], v186, v186 op_sel_hi:[0,0,0]
	s_barrier
	s_setprio 0
	s_add_i32 s51, s37, s25
	v_lshl_add_u64 v[178:179], s[20:21], 0, v[164:165]
	s_mov_b32 m0, s51
	ds_read_b128 v[194:197], v192 offset:16384
	ds_read_b128 v[198:201], v192 offset:17408
	ds_read_b128 v[202:205], v192 offset:18432
	ds_read_b128 v[206:209], v192 offset:19456
	ds_read_b128 v[210:213], v192 offset:20480
	ds_read_b128 v[214:217], v192 offset:21504
	ds_read_b128 v[218:221], v192 offset:22528
	ds_read_b128 v[222:225], v192 offset:23552
	global_load_lds_dwordx4 v[178:179], off
	s_add_i32 m0, s51, 0x2000
	s_add_u32 s68, s20, 0xb0000
	v_lshl_add_u64 v[180:181], s[20:21], 0, v[168:169]
	s_addc_u32 s69, s21, 0
	s_add_i32 s51, s38, s25
	global_load_lds_dwordx4 v[180:181], off
	v_lshl_add_u64 v[182:183], s[68:69], 0, v[164:165]
	s_mov_b32 m0, s51
	v_lshl_add_u64 v[184:185], s[22:23], 0, v[166:167]
	global_load_lds_dwordx4 v[182:183], off
	v_lshl_add_u64 v[182:183], s[68:69], 0, v[168:169]
	s_add_i32 m0, s51, 0x2000
	s_nop 0
	global_load_lds_dwordx4 v[182:183], off
	v_lshl_add_u64 v[182:183], s[22:23], 0, v[162:163]
	s_mov_b32 m0, s26
	s_nop 0
	global_load_lds_dwordx4 v[182:183], off
	s_mov_b32 m0, s27
	s_nop 0
	global_load_lds_dwordx4 v[184:185], off
	s_waitcnt vmcnt(8)
	s_waitcnt lgkmcnt(0)
	s_setprio 1
	s_barrier
	v_mfma_scale_f32_16x16x128_f8f6f4 v[94:97], v[18:25], v[194:201], v[94:97], v186, v186 op_sel_hi:[0,0,0]
	v_mfma_scale_f32_16x16x128_f8f6f4 v[90:93], v[26:33], v[194:201], v[90:93], v186, v186 op_sel_hi:[0,0,0]
	v_mfma_scale_f32_16x16x128_f8f6f4 v[86:89], v[18:25], v[202:209], v[86:89], v186, v186 op_sel_hi:[0,0,0]
	v_mfma_scale_f32_16x16x128_f8f6f4 v[78:81], v[26:33], v[202:209], v[78:81], v186, v186 op_sel_hi:[0,0,0]
	v_mfma_scale_f32_16x16x128_f8f6f4 v[70:73], v[18:25], v[210:217], v[70:73], v186, v186 op_sel_hi:[0,0,0]
	v_mfma_scale_f32_16x16x128_f8f6f4 v[62:65], v[26:33], v[210:217], v[62:65], v186, v186 op_sel_hi:[0,0,0]
	v_mfma_scale_f32_16x16x128_f8f6f4 v[54:57], v[18:25], v[218:225], v[54:57], v186, v186 op_sel_hi:[0,0,0]
	v_mfma_scale_f32_16x16x128_f8f6f4 v[46:49], v[26:33], v[218:225], v[46:49], v186, v186 op_sel_hi:[0,0,0]
	s_setprio 0
	s_setprio 1
	v_mfma_scale_f32_16x16x128_f8f6f4 v[82:85], v[2:9], v[194:201], v[82:85], v186, v186 op_sel_hi:[0,0,0]
	v_mfma_scale_f32_16x16x128_f8f6f4 v[74:77], v[10:17], v[194:201], v[74:77], v186, v186 op_sel_hi:[0,0,0]
	v_mfma_scale_f32_16x16x128_f8f6f4 v[66:69], v[2:9], v[202:209], v[66:69], v186, v186 op_sel_hi:[0,0,0]
	v_mfma_scale_f32_16x16x128_f8f6f4 v[58:61], v[10:17], v[202:209], v[58:61], v186, v186 op_sel_hi:[0,0,0]
	v_mfma_scale_f32_16x16x128_f8f6f4 v[50:53], v[2:9], v[210:217], v[50:53], v186, v186 op_sel_hi:[0,0,0]
	v_mfma_scale_f32_16x16x128_f8f6f4 v[42:45], v[10:17], v[210:217], v[42:45], v186, v186 op_sel_hi:[0,0,0]
	v_mfma_scale_f32_16x16x128_f8f6f4 v[38:41], v[2:9], v[218:225], v[38:41], v186, v186 op_sel_hi:[0,0,0]
	v_mfma_scale_f32_16x16x128_f8f6f4 v[34:37], v[10:17], v[218:225], v[34:37], v186, v186 op_sel_hi:[0,0,0]
	s_barrier
; #define PG8_STAGE(bufoff, gbase, voff) do { _Pragma("unroll") for (int _i = 0; _i < 2; ++_i) \
;         __builtin_amdgcn_global_load_lds((const unsigned*)((const char*)(gbase) + (voff)[_i]), (PG8_LAS unsigned*)(lds + (bufoff) + ldsw + _i * 8192), 16, 0, 0); } while (0)
; #define PG8_WAIT_V(n) asm volatile("s_waitcnt vmcnt(" #n ")" ::: "memory")
; #define PG8_WAIT_L(n) asm volatile("s_waitcnt lgkmcnt(" #n ")" ::: "memory")
; #define PG8_BAR __builtin_amdgcn_s_barrier()
; #define PG8_SCHED __builtin_amdgcn_sched_barrier(0)
; template <class Epi, class Sched, bool ALIGN_EPI = true, bool SP2 = true>
; __device__ __forceinline__ void gemm_phase(PG8_LAS unsigned char* lds, const int K  , const Sched& S, const Epi& E) {
;     ...
;             PG8_LDB(B0, 1, 0); PG8_LDB(B1, 1, 1); PG8_SCHED; PG8_LDA(At, 1, 0); PG8_STAGE(PG8_SA(0, 1), a2 + hstep, voffA);
;             PG8_WAIT_V(8); PG8_WAIT_L(0); PG8_BAR; PG8_MMA(0, 0, At, B0); PG8_MMA(0, 1, At, B1); PG8_BAR; PG8_SCHED;
;             PG8_LDA(At, 1, 1); PG8_STAGE(PG8_SB(1, 0), b3, voffB); PG8_STAGE(PG8_SB(1, 1), b3 + hstep, voffB); PG8_STAGE(PG8_SA(1, 0), a3, voffA);
;             PG8_WAIT_V(8); PG8_WAIT_L(0); PG8_BAR; PG8_MMA(1, 0, At, B0); PG8_MMA(1, 1, At, B1); PG8_BAR; PG8_SCHED;
;     ...
;         if constexpr (Epi::FP8) asm volatile("s_nop 15\n\ts_nop 15\n\ts_nop 15\n\ts_nop 15\n\ts_nop 15" ::: "memory");
;         if constexpr (ALIGN_EPI) { if (wr == 0) PG8_BAR; }
	s_setprio 0
	s_add_i32 s51, 0, 0x18000
	s_add_i32 s68, 0, 0x1c000
	v_add_u32_e32 v14, s51, v188
	v_add_u32_e32 v30, s68, v188
	ds_read_b128 v[2:5], v14
	ds_read_b128 v[6:9], v14 offset:1024
	ds_read_b128 v[10:13], v14 offset:2048
	ds_read_b128 v[14:17], v14 offset:3072
	ds_read_b128 v[18:21], v30
	ds_read_b128 v[22:25], v30 offset:1024
	ds_read_b128 v[26:29], v30 offset:2048
	ds_read_b128 v[30:33], v30 offset:3072
	ds_read_b128 v[194:197], v192 offset:32768
	ds_read_b128 v[198:201], v192 offset:33792
	ds_read_b128 v[202:205], v192 offset:34816
	ds_read_b128 v[206:209], v192 offset:35840
	ds_read_b128 v[210:213], v192 offset:36864
	ds_read_b128 v[214:217], v192 offset:37888
	ds_read_b128 v[218:221], v192 offset:38912
	ds_read_b128 v[222:225], v192 offset:39936
	s_add_u32 s22, s22, 0xb0000
	s_addc_u32 s23, s23, 0
	s_mov_b32 m0, s28
	v_lshl_add_u64 v[226:227], s[22:23], 0, v[162:163]
	global_load_lds_dwordx4 v[226:227], off
	v_lshl_add_u64 v[226:227], s[22:23], 0, v[166:167]
	s_mov_b32 m0, s29
	s_nop 0
	global_load_lds_dwordx4 v[226:227], off
	s_waitcnt vmcnt(8)
	s_waitcnt lgkmcnt(0)
	s_setprio 1
	s_barrier
	v_mfma_scale_f32_16x16x128_f8f6f4 v[158:161], v[2:9], v[194:201], v[158:161], v186, v186 op_sel_hi:[0,0,0]
	v_mfma_scale_f32_16x16x128_f8f6f4 v[154:157], v[10:17], v[194:201], v[154:157], v186, v186 op_sel_hi:[0,0,0]
	v_mfma_scale_f32_16x16x128_f8f6f4 v[150:153], v[2:9], v[202:209], v[150:153], v186, v186 op_sel_hi:[0,0,0]
	v_mfma_scale_f32_16x16x128_f8f6f4 v[142:145], v[10:17], v[202:209], v[142:145], v186, v186 op_sel_hi:[0,0,0]
	v_mfma_scale_f32_16x16x128_f8f6f4 v[134:137], v[2:9], v[210:217], v[134:137], v186, v186 op_sel_hi:[0,0,0]
	v_mfma_scale_f32_16x16x128_f8f6f4 v[126:129], v[10:17], v[210:217], v[126:129], v186, v186 op_sel_hi:[0,0,0]
	v_mfma_scale_f32_16x16x128_f8f6f4 v[118:121], v[2:9], v[218:225], v[118:121], v186, v186 op_sel_hi:[0,0,0]
	v_mfma_scale_f32_16x16x128_f8f6f4 v[110:113], v[10:17], v[218:225], v[110:113], v186, v186 op_sel_hi:[0,0,0]
	s_setprio 0
	s_setprio 1
	v_mfma_scale_f32_16x16x128_f8f6f4 v[146:149], v[18:25], v[194:201], v[146:149], v186, v186 op_sel_hi:[0,0,0]
	v_mfma_scale_f32_16x16x128_f8f6f4 v[138:141], v[26:33], v[194:201], v[138:141], v186, v186 op_sel_hi:[0,0,0]
	v_mfma_scale_f32_16x16x128_f8f6f4 v[130:133], v[18:25], v[202:209], v[130:133], v186, v186 op_sel_hi:[0,0,0]
	v_mfma_scale_f32_16x16x128_f8f6f4 v[122:125], v[26:33], v[202:209], v[122:125], v186, v186 op_sel_hi:[0,0,0]
	v_mfma_scale_f32_16x16x128_f8f6f4 v[114:117], v[18:25], v[210:217], v[114:117], v186, v186 op_sel_hi:[0,0,0]
	v_mfma_scale_f32_16x16x128_f8f6f4 v[106:109], v[26:33], v[210:217], v[106:109], v186, v186 op_sel_hi:[0,0,0]
	v_mfma_scale_f32_16x16x128_f8f6f4 v[102:105], v[18:25], v[218:225], v[102:105], v186, v186 op_sel_hi:[0,0,0]
	v_mfma_scale_f32_16x16x128_f8f6f4 v[98:101], v[26:33], v[218:225], v[98:101], v186, v186 op_sel_hi:[0,0,0]
	s_barrier
	s_setprio 0
	s_add_i32 s22, s51, s25
	v_lshl_add_u64 v[178:179], v[178:179], 0, s[8:9]
	s_mov_b32 m0, s22
	ds_read_b128 v[194:197], v192 offset:49152
	ds_read_b128 v[198:201], v192 offset:50176
	ds_read_b128 v[202:205], v192 offset:51200
	ds_read_b128 v[206:209], v192 offset:52224
	ds_read_b128 v[210:213], v192 offset:53248
	ds_read_b128 v[214:217], v192 offset:54272
	ds_read_b128 v[218:221], v192 offset:55296
	ds_read_b128 v[222:225], v192 offset:56320
	global_load_lds_dwordx4 v[178:179], off
	s_add_i32 m0, s22, 0x2000
	s_add_u32 s20, s20, 0xb0080
	v_lshl_add_u64 v[178:179], v[180:181], 0, s[8:9]
	s_addc_u32 s21, s21, 0
	s_add_i32 s22, s68, s25
	global_load_lds_dwordx4 v[178:179], off
	v_lshl_add_u64 v[178:179], s[20:21], 0, v[164:165]
	s_mov_b32 m0, s22
	s_nop 0
	global_load_lds_dwordx4 v[178:179], off
	v_lshl_add_u64 v[178:179], s[20:21], 0, v[168:169]
	s_add_i32 m0, s22, 0x2000
	s_nop 0
	global_load_lds_dwordx4 v[178:179], off
	v_lshl_add_u64 v[178:179], v[182:183], 0, s[8:9]
	s_mov_b32 m0, s33
	s_nop 0
	global_load_lds_dwordx4 v[178:179], off
	v_lshl_add_u64 v[178:179], v[184:185], 0, s[8:9]
	s_mov_b32 m0, s34
	s_nop 0
	global_load_lds_dwordx4 v[178:179], off
	s_waitcnt vmcnt(8)
	s_waitcnt lgkmcnt(0)
	s_setprio 1
	s_barrier
	v_mfma_scale_f32_16x16x128_f8f6f4 v[94:97], v[2:9], v[194:201], v[94:97], v186, v186 op_sel_hi:[0,0,0]
	v_mfma_scale_f32_16x16x128_f8f6f4 v[90:93], v[10:17], v[194:201], v[90:93], v186, v186 op_sel_hi:[0,0,0]
	v_mfma_scale_f32_16x16x128_f8f6f4 v[86:89], v[2:9], v[202:209], v[86:89], v186, v186 op_sel_hi:[0,0,0]
	v_mfma_scale_f32_16x16x128_f8f6f4 v[78:81], v[10:17], v[202:209], v[78:81], v186, v186 op_sel_hi:[0,0,0]
	v_mfma_scale_f32_16x16x128_f8f6f4 v[70:73], v[2:9], v[210:217], v[70:73], v186, v186 op_sel_hi:[0,0,0]
	v_mfma_scale_f32_16x16x128_f8f6f4 v[62:65], v[10:17], v[210:217], v[62:65], v186, v186 op_sel_hi:[0,0,0]
	v_mfma_scale_f32_16x16x128_f8f6f4 v[54:57], v[2:9], v[218:225], v[54:57], v186, v186 op_sel_hi:[0,0,0]
	v_mfma_scale_f32_16x16x128_f8f6f4 v[46:49], v[10:17], v[218:225], v[46:49], v186, v186 op_sel_hi:[0,0,0]
	s_setprio 0
	s_setprio 1
	v_mfma_scale_f32_16x16x128_f8f6f4 v[82:85], v[18:25], v[194:201], v[82:85], v186, v186 op_sel_hi:[0,0,0]
	v_mfma_scale_f32_16x16x128_f8f6f4 v[74:77], v[26:33], v[194:201], v[74:77], v186, v186 op_sel_hi:[0,0,0]
	v_mfma_scale_f32_16x16x128_f8f6f4 v[66:69], v[18:25], v[202:209], v[66:69], v186, v186 op_sel_hi:[0,0,0]
	v_mfma_scale_f32_16x16x128_f8f6f4 v[58:61], v[26:33], v[202:209], v[58:61], v186, v186 op_sel_hi:[0,0,0]
	v_mfma_scale_f32_16x16x128_f8f6f4 v[50:53], v[18:25], v[210:217], v[50:53], v186, v186 op_sel_hi:[0,0,0]
	v_mfma_scale_f32_16x16x128_f8f6f4 v[42:45], v[26:33], v[210:217], v[42:45], v186, v186 op_sel_hi:[0,0,0]
	v_mfma_scale_f32_16x16x128_f8f6f4 v[38:41], v[18:25], v[218:225], v[38:41], v186, v186 op_sel_hi:[0,0,0]
	v_mfma_scale_f32_16x16x128_f8f6f4 v[34:37], v[26:33], v[218:225], v[34:37], v186, v186 op_sel_hi:[0,0,0]
	s_barrier
	s_setprio 0
	s_add_u32 s18, s18, 0x100
	s_addc_u32 s19, s19, 0
	s_add_u32 s48, s48, 0x100
	s_addc_u32 s49, s49, 0
	s_cmp_ge_u32 s50, s4
	s_mov_b32 s22, s50
	s_cbranch_scc0 .LBB0_393
	s_nop 15
	s_nop 15
	s_nop 15
	s_nop 15
	s_nop 15
	s_and_b64 vcc, exec, s[10:11]
	s_cbranch_vccz .LBB0_396
	s_barrier

; #define PG8_STAGE(bufoff, gbase, voff) do { _Pragma("unroll") for (int _i = 0; _i < 2; ++_i) \
;         __builtin_amdgcn_global_load_lds((const unsigned*)((const char*)(gbase) + (voff)[_i]), (PG8_LAS unsigned*)(lds + (bufoff) + ldsw + _i * 8192), 16, 0, 0); } while (0)
; #define PG8_WAIT_V(n) asm volatile("s_waitcnt vmcnt(" #n ")" ::: "memory")
; #define PG8_WAIT_L(n) asm volatile("s_waitcnt lgkmcnt(" #n ")" ::: "memory")
; #define PG8_BAR __builtin_amdgcn_s_barrier()
; #define PG8_SCHED __builtin_amdgcn_sched_barrier(0)
;     __device__ __forceinline__ int nt(const pg8::Unit& u) const { return u.kind == 0 ? ntiles : q_nt(u.kind - 1); }
; template <class Epi, class Sched, bool ALIGN_EPI = true, bool SP2 = true>
; __device__ __forceinline__ void gemm_phase(PG8_LAS unsigned char* lds, const int K  , const Sched& S, const Epi& E) {
;     ...
;         for (int t = 0; t < nt; t += 2) {
;             const bool last = (t == nt - 2);
;             const char* a1 = cA + (size_t)(t + 1) * kstep;
;             const char* a2 = last ? nA : cA + (size_t)(t + 2) * kstep; const char* b2 = last ? nB : cB + (size_t)(t + 2) * kstep;
;             const char* a3 = a2 + kstep; const char* b3 = b2 + kstep;
;             if constexpr (SP2) {
;             PG8_LDB(B0, 0, 0); PG8_LDB(B1, 0, 1); PG8_SCHED; PG8_LDA(At, 0, 0); PG8_STAGE(PG8_SA(1, 1), a1 + hstep, voffA);
;             PG8_WAIT_V(8); PG8_WAIT_L(0); PG8_BAR; PG8_MMA(0, 0, At, B0); PG8_MMA(0, 1, At, B1); PG8_BAR; PG8_SCHED;
;             PG8_LDA(At, 0, 1); PG8_STAGE(PG8_SB(0, 0), b2, voffB); PG8_STAGE(PG8_SB(0, 1), b2 + hstep, voffB); PG8_STAGE(PG8_SA(0, 0), a2, voffA);
.LBB0_537:
	ds_read_b128 v[150:153], v156
	ds_read_b128 v[160:163], v156 offset:1024
	ds_read_b128 v[164:167], v156 offset:2048
	ds_read_b128 v[168:171], v156 offset:3072
	ds_read_b128 v[172:175], v157
	ds_read_b128 v[176:179], v157 offset:1024
	ds_read_b128 v[180:183], v157 offset:2048
	ds_read_b128 v[184:187], v157 offset:3072
	ds_read_b128 v[188:191], v158
	ds_read_b128 v[192:195], v158 offset:1024
	ds_read_b128 v[196:199], v158 offset:2048
	ds_read_b128 v[200:203], v158 offset:3072
	ds_read_b128 v[204:207], v158 offset:4096
	ds_read_b128 v[208:211], v158 offset:5120
	ds_read_b128 v[212:215], v158 offset:6144
	ds_read_b128 v[216:219], v158 offset:7168
	s_add_u32 s22, s20, 0xfff80080
	s_addc_u32 s23, s21, -1
	s_cmp_eq_u32 s47, 28
	s_cselect_b32 s25, s13, s23
	s_cselect_b32 s24, s19, s22
	s_cselect_b32 s23, s11, s46
	s_cselect_b32 s22, s44, s45
	s_add_i32 m0, s31, 0xc000
	v_lshl_add_u64 v[220:221], s[20:21], 0, v[142:143]
	global_load_lds_dwordx4 v[220:221], off
	v_lshl_add_u64 v[220:221], s[20:21], 0, v[144:145]
	s_add_i32 m0, s31, 0xe000
	s_nop 0
	global_load_lds_dwordx4 v[220:221], off
	s_waitcnt vmcnt(8)
	s_waitcnt lgkmcnt(0)
	s_setprio 1
	s_barrier
	v_mfma_f32_16x16x32_bf16 v[126:129], v[150:153], v[188:191], v[126:129]
	v_mfma_f32_16x16x32_bf16 v[122:125], v[164:167], v[188:191], v[122:125]
	v_mfma_f32_16x16x32_bf16 v[118:121], v[150:153], v[196:199], v[118:121]
	v_mfma_f32_16x16x32_bf16 v[110:113], v[164:167], v[196:199], v[110:113]
	v_mfma_f32_16x16x32_bf16 v[102:105], v[150:153], v[204:207], v[102:105]
	v_mfma_f32_16x16x32_bf16 v[94:97], v[164:167], v[204:207], v[94:97]
	v_mfma_f32_16x16x32_bf16 v[86:89], v[150:153], v[212:215], v[86:89]
	v_mfma_f32_16x16x32_bf16 v[78:81], v[164:167], v[212:215], v[78:81]
	v_mfma_f32_16x16x32_bf16 v[126:129], v[160:163], v[192:195], v[126:129]
	v_mfma_f32_16x16x32_bf16 v[122:125], v[168:171], v[192:195], v[122:125]
	v_mfma_f32_16x16x32_bf16 v[118:121], v[160:163], v[200:203], v[118:121]
	v_mfma_f32_16x16x32_bf16 v[110:113], v[168:171], v[200:203], v[110:113]
	v_mfma_f32_16x16x32_bf16 v[102:105], v[160:163], v[208:211], v[102:105]
	v_mfma_f32_16x16x32_bf16 v[94:97], v[168:171], v[208:211], v[94:97]
	v_mfma_f32_16x16x32_bf16 v[86:89], v[160:163], v[216:219], v[86:89]
	v_mfma_f32_16x16x32_bf16 v[78:81], v[168:171], v[216:219], v[78:81]
	s_setprio 0
	s_setprio 1
	v_mfma_f32_16x16x32_bf16 v[114:117], v[172:175], v[188:191], v[114:117]
	v_mfma_f32_16x16x32_bf16 v[106:109], v[180:183], v[188:191], v[106:109]
	v_mfma_f32_16x16x32_bf16 v[98:101], v[172:175], v[196:199], v[98:101]
	v_mfma_f32_16x16x32_bf16 v[90:93], v[180:183], v[196:199], v[90:93]
	v_mfma_f32_16x16x32_bf16 v[82:85], v[172:175], v[204:207], v[82:85]
	v_mfma_f32_16x16x32_bf16 v[74:77], v[180:183], v[204:207], v[74:77]
	v_mfma_f32_16x16x32_bf16 v[70:73], v[172:175], v[212:215], v[70:73]
	v_mfma_f32_16x16x32_bf16 v[66:69], v[180:183], v[212:215], v[66:69]
	v_mfma_f32_16x16x32_bf16 v[114:117], v[176:179], v[192:195], v[114:117]
	v_mfma_f32_16x16x32_bf16 v[106:109], v[184:187], v[192:195], v[106:109]
	v_mfma_f32_16x16x32_bf16 v[98:101], v[176:179], v[200:203], v[98:101]
	v_mfma_f32_16x16x32_bf16 v[90:93], v[184:187], v[200:203], v[90:93]
	v_mfma_f32_16x16x32_bf16 v[82:85], v[176:179], v[208:211], v[82:85]
	v_mfma_f32_16x16x32_bf16 v[74:77], v[184:187], v[208:211], v[74:77]
	v_mfma_f32_16x16x32_bf16 v[70:73], v[176:179], v[216:219], v[70:73]
	v_mfma_f32_16x16x32_bf16 v[66:69], v[184:187], v[216:219], v[66:69]
	s_barrier
	s_setprio 0
	s_add_i32 s48, s40, s29
	v_lshl_add_u64 v[220:221], s[22:23], 0, v[136:137]
	s_mov_b32 m0, s48
	ds_read_b128 v[188:191], v158 offset:16384
	ds_read_b128 v[192:195], v158 offset:17408
	ds_read_b128 v[196:199], v158 offset:18432
	ds_read_b128 v[200:203], v158 offset:19456
	ds_read_b128 v[204:207], v158 offset:20480
	ds_read_b128 v[208:211], v158 offset:21504
	ds_read_b128 v[212:215], v158 offset:22528
	ds_read_b128 v[216:219], v158 offset:23552
	global_load_lds_dwordx4 v[220:221], off
	s_add_i32 m0, s48, 0x2000
	s_add_u32 s48, s22, 0x80000
	v_lshl_add_u64 v[222:223], s[22:23], 0, v[132:133]
	s_addc_u32 s49, s23, 0
	s_add_i32 s50, s41, s29
	global_load_lds_dwordx4 v[222:223], off
	v_lshl_add_u64 v[224:225], s[48:49], 0, v[136:137]
	s_mov_b32 m0, s50
	v_lshl_add_u64 v[226:227], s[24:25], 0, v[134:135]
	global_load_lds_dwordx4 v[224:225], off
	v_lshl_add_u64 v[224:225], s[48:49], 0, v[132:133]
	s_add_i32 m0, s50, 0x2000
	s_nop 0
	global_load_lds_dwordx4 v[224:225], off
	v_lshl_add_u64 v[224:225], s[24:25], 0, v[138:139]
	s_mov_b32 m0, s31
	s_nop 0
	global_load_lds_dwordx4 v[224:225], off
	s_mov_b32 m0, s33
	s_nop 0
	global_load_lds_dwordx4 v[226:227], off
	s_waitcnt vmcnt(8)
	s_waitcnt lgkmcnt(0)
	s_setprio 1
	s_barrier
; #define PG8_STAGE(bufoff, gbase, voff) do { _Pragma("unroll") for (int _i = 0; _i < 2; ++_i) \
;         __builtin_amdgcn_global_load_lds((const unsigned*)((const char*)(gbase) + (voff)[_i]), (PG8_LAS unsigned*)(lds + (bufoff) + ldsw + _i * 8192), 16, 0, 0); } while (0)
; #define PG8_WAIT_V(n) asm volatile("s_waitcnt vmcnt(" #n ")" ::: "memory")
; #define PG8_WAIT_L(n) asm volatile("s_waitcnt lgkmcnt(" #n ")" ::: "memory")
; #define PG8_BAR __builtin_amdgcn_s_barrier()
; #define PG8_SCHED __builtin_amdgcn_sched_barrier(0)
; template <class Epi, class Sched, bool ALIGN_EPI = true, bool SP2 = true>
; __device__ __forceinline__ void gemm_phase(PG8_LAS unsigned char* lds, const int K  , const Sched& S, const Epi& E) {
;     ...
;             PG8_WAIT_V(8); PG8_WAIT_L(0); PG8_BAR; PG8_MMA(1, 0, At, B0); PG8_MMA(1, 1, At, B1); PG8_BAR; PG8_SCHED;
;             PG8_LDB(B0, 1, 0); PG8_LDB(B1, 1, 1); PG8_SCHED; PG8_LDA(At, 1, 0); PG8_STAGE(PG8_SA(0, 1), a2 + hstep, voffA);
;             PG8_WAIT_V(8); PG8_WAIT_L(0); PG8_BAR; PG8_MMA(0, 0, At, B0); PG8_MMA(0, 1, At, B1); PG8_BAR; PG8_SCHED;
	v_mfma_f32_16x16x32_bf16 v[62:65], v[150:153], v[188:191], v[62:65]
	v_mfma_f32_16x16x32_bf16 v[58:61], v[164:167], v[188:191], v[58:61]
	v_mfma_f32_16x16x32_bf16 v[54:57], v[150:153], v[196:199], v[54:57]
	v_mfma_f32_16x16x32_bf16 v[46:49], v[164:167], v[196:199], v[46:49]
	v_mfma_f32_16x16x32_bf16 v[38:41], v[150:153], v[204:207], v[38:41]
	v_mfma_f32_16x16x32_bf16 v[30:33], v[164:167], v[204:207], v[30:33]
	v_mfma_f32_16x16x32_bf16 v[22:25], v[150:153], v[212:215], v[22:25]
	v_mfma_f32_16x16x32_bf16 v[14:17], v[164:167], v[212:215], v[14:17]
	v_mfma_f32_16x16x32_bf16 v[62:65], v[160:163], v[192:195], v[62:65]
	v_mfma_f32_16x16x32_bf16 v[58:61], v[168:171], v[192:195], v[58:61]
	v_mfma_f32_16x16x32_bf16 v[54:57], v[160:163], v[200:203], v[54:57]
	v_mfma_f32_16x16x32_bf16 v[46:49], v[168:171], v[200:203], v[46:49]
	v_mfma_f32_16x16x32_bf16 v[38:41], v[160:163], v[208:211], v[38:41]
	v_mfma_f32_16x16x32_bf16 v[30:33], v[168:171], v[208:211], v[30:33]
	v_mfma_f32_16x16x32_bf16 v[22:25], v[160:163], v[216:219], v[22:25]
	v_mfma_f32_16x16x32_bf16 v[14:17], v[168:171], v[216:219], v[14:17]
	s_setprio 0
	s_setprio 1
	v_mfma_f32_16x16x32_bf16 v[50:53], v[172:175], v[188:191], v[50:53]
	v_mfma_f32_16x16x32_bf16 v[42:45], v[180:183], v[188:191], v[42:45]
	v_mfma_f32_16x16x32_bf16 v[34:37], v[172:175], v[196:199], v[34:37]
	v_mfma_f32_16x16x32_bf16 v[26:29], v[180:183], v[196:199], v[26:29]
	v_mfma_f32_16x16x32_bf16 v[18:21], v[172:175], v[204:207], v[18:21]
	v_mfma_f32_16x16x32_bf16 v[10:13], v[180:183], v[204:207], v[10:13]
	v_mfma_f32_16x16x32_bf16 v[6:9], v[172:175], v[212:215], v[6:9]
	v_mfma_f32_16x16x32_bf16 v[2:5], v[180:183], v[212:215], v[2:5]
	v_mfma_f32_16x16x32_bf16 v[50:53], v[176:179], v[192:195], v[50:53]
	v_mfma_f32_16x16x32_bf16 v[42:45], v[184:187], v[192:195], v[42:45]
	v_mfma_f32_16x16x32_bf16 v[34:37], v[176:179], v[200:203], v[34:37]
	v_mfma_f32_16x16x32_bf16 v[26:29], v[184:187], v[200:203], v[26:29]
	v_mfma_f32_16x16x32_bf16 v[18:21], v[176:179], v[208:211], v[18:21]
	v_mfma_f32_16x16x32_bf16 v[10:13], v[184:187], v[208:211], v[10:13]
	v_mfma_f32_16x16x32_bf16 v[6:9], v[176:179], v[216:219], v[6:9]
	v_mfma_f32_16x16x32_bf16 v[2:5], v[184:187], v[216:219], v[2:5]
	s_barrier
	s_setprio 0
	s_add_i32 s48, 0, 0x18000
	v_add_u32_e32 v140, s48, v154
	s_add_i32 s49, 0, 0x1c000
	ds_read_b128 v[150:153], v140
	ds_read_b128 v[160:163], v140 offset:1024
	ds_read_b128 v[164:167], v140 offset:2048
	ds_read_b128 v[168:171], v140 offset:3072
	v_add_u32_e32 v140, s49, v154
	ds_read_b128 v[172:175], v140
	ds_read_b128 v[176:179], v140 offset:1024
	ds_read_b128 v[180:183], v140 offset:2048
	ds_read_b128 v[184:187], v140 offset:3072
	ds_read_b128 v[188:191], v158 offset:32768
	ds_read_b128 v[192:195], v158 offset:33792
	ds_read_b128 v[196:199], v158 offset:34816
	ds_read_b128 v[200:203], v158 offset:35840
	ds_read_b128 v[204:207], v158 offset:36864
	ds_read_b128 v[208:211], v158 offset:37888
	ds_read_b128 v[212:215], v158 offset:38912
	ds_read_b128 v[216:219], v158 offset:39936
	s_add_u32 s24, s24, 0x80000
	s_addc_u32 s25, s25, 0
	s_mov_b32 m0, s34
	v_lshl_add_u64 v[230:231], s[24:25], 0, v[138:139]
	global_load_lds_dwordx4 v[230:231], off
	v_lshl_add_u64 v[230:231], s[24:25], 0, v[134:135]
	s_mov_b32 m0, s35
	s_nop 0
	global_load_lds_dwordx4 v[230:231], off
	s_waitcnt vmcnt(8)
	s_waitcnt lgkmcnt(0)
	s_setprio 1
	s_barrier
	v_mfma_f32_16x16x32_bf16 v[126:129], v[150:153], v[188:191], v[126:129]
	v_mfma_f32_16x16x32_bf16 v[122:125], v[164:167], v[188:191], v[122:125]
	v_mfma_f32_16x16x32_bf16 v[118:121], v[150:153], v[196:199], v[118:121]
	v_mfma_f32_16x16x32_bf16 v[110:113], v[164:167], v[196:199], v[110:113]
	v_mfma_f32_16x16x32_bf16 v[102:105], v[150:153], v[204:207], v[102:105]
	v_mfma_f32_16x16x32_bf16 v[94:97], v[164:167], v[204:207], v[94:97]
	v_mfma_f32_16x16x32_bf16 v[86:89], v[150:153], v[212:215], v[86:89]
	v_mfma_f32_16x16x32_bf16 v[78:81], v[164:167], v[212:215], v[78:81]
	v_mfma_f32_16x16x32_bf16 v[126:129], v[160:163], v[192:195], v[126:129]
	v_mfma_f32_16x16x32_bf16 v[122:125], v[168:171], v[192:195], v[122:125]
	v_mfma_f32_16x16x32_bf16 v[118:121], v[160:163], v[200:203], v[118:121]
	v_mfma_f32_16x16x32_bf16 v[110:113], v[168:171], v[200:203], v[110:113]
	v_mfma_f32_16x16x32_bf16 v[102:105], v[160:163], v[208:211], v[102:105]
	v_mfma_f32_16x16x32_bf16 v[94:97], v[168:171], v[208:211], v[94:97]
	v_mfma_f32_16x16x32_bf16 v[86:89], v[160:163], v[216:219], v[86:89]
	v_mfma_f32_16x16x32_bf16 v[78:81], v[168:171], v[216:219], v[78:81]
	s_setprio 0
	s_setprio 1
	v_mfma_f32_16x16x32_bf16 v[114:117], v[172:175], v[188:191], v[114:117]
	v_mfma_f32_16x16x32_bf16 v[106:109], v[180:183], v[188:191], v[106:109]
	v_mfma_f32_16x16x32_bf16 v[98:101], v[172:175], v[196:199], v[98:101]
	v_mfma_f32_16x16x32_bf16 v[90:93], v[180:183], v[196:199], v[90:93]
	v_mfma_f32_16x16x32_bf16 v[82:85], v[172:175], v[204:207], v[82:85]
	v_mfma_f32_16x16x32_bf16 v[74:77], v[180:183], v[204:207], v[74:77]
	v_mfma_f32_16x16x32_bf16 v[70:73], v[172:175], v[212:215], v[70:73]
	v_mfma_f32_16x16x32_bf16 v[66:69], v[180:183], v[212:215], v[66:69]
	v_mfma_f32_16x16x32_bf16 v[114:117], v[176:179], v[192:195], v[114:117]
	v_mfma_f32_16x16x32_bf16 v[106:109], v[184:187], v[192:195], v[106:109]
	v_mfma_f32_16x16x32_bf16 v[98:101], v[176:179], v[200:203], v[98:101]
	v_mfma_f32_16x16x32_bf16 v[90:93], v[184:187], v[200:203], v[90:93]
	v_mfma_f32_16x16x32_bf16 v[82:85], v[176:179], v[208:211], v[82:85]
	v_mfma_f32_16x16x32_bf16 v[74:77], v[184:187], v[208:211], v[74:77]
	v_mfma_f32_16x16x32_bf16 v[70:73], v[176:179], v[216:219], v[70:73]
	v_mfma_f32_16x16x32_bf16 v[66:69], v[184:187], v[216:219], v[66:69]
	s_barrier
; #define PG8_STAGE(bufoff, gbase, voff) do { _Pragma("unroll") for (int _i = 0; _i < 2; ++_i) \
;         __builtin_amdgcn_global_load_lds((const unsigned*)((const char*)(gbase) + (voff)[_i]), (PG8_LAS unsigned*)(lds + (bufoff) + ldsw + _i * 8192), 16, 0, 0); } while (0)
; #define PG8_WAIT_V(n) asm volatile("s_waitcnt vmcnt(" #n ")" ::: "memory")
; #define PG8_WAIT_L(n) asm volatile("s_waitcnt lgkmcnt(" #n ")" ::: "memory")
; #define PG8_BAR __builtin_amdgcn_s_barrier()
; #define PG8_SCHED __builtin_amdgcn_sched_barrier(0)
; template <class Epi, class Sched, bool ALIGN_EPI = true, bool SP2 = true>
; __device__ __forceinline__ void gemm_phase(PG8_LAS unsigned char* lds, const int K  , const Sched& S, const Epi& E) {
;     ...
;             PG8_LDA(At, 1, 1); PG8_STAGE(PG8_SB(1, 0), b3, voffB); PG8_STAGE(PG8_SB(1, 1), b3 + hstep, voffB); PG8_STAGE(PG8_SA(1, 0), a3, voffA);
;             PG8_WAIT_V(8); PG8_WAIT_L(0); PG8_BAR; PG8_MMA(1, 0, At, B0); PG8_MMA(1, 1, At, B1); PG8_BAR; PG8_SCHED;
	s_setprio 0
	s_add_i32 s24, s48, s29
	v_lshl_add_u64 v[220:221], v[220:221], 0, s[6:7]
	s_mov_b32 m0, s24
	ds_read_b128 v[188:191], v158 offset:49152
	ds_read_b128 v[192:195], v158 offset:50176
	ds_read_b128 v[196:199], v158 offset:51200
	ds_read_b128 v[200:203], v158 offset:52224
	ds_read_b128 v[204:207], v158 offset:53248
	ds_read_b128 v[208:211], v158 offset:54272
	ds_read_b128 v[212:215], v158 offset:55296
	ds_read_b128 v[216:219], v158 offset:56320
	global_load_lds_dwordx4 v[220:221], off
	s_add_i32 m0, s24, 0x2000
	s_add_u32 s22, s22, 0x80080
	v_lshl_add_u64 v[220:221], v[222:223], 0, s[6:7]
	s_addc_u32 s23, s23, 0
	s_add_i32 s24, s49, s29
	global_load_lds_dwordx4 v[220:221], off
	v_lshl_add_u64 v[220:221], s[22:23], 0, v[136:137]
	s_mov_b32 m0, s24
	s_nop 0
	global_load_lds_dwordx4 v[220:221], off
	v_lshl_add_u64 v[220:221], s[22:23], 0, v[132:133]
	s_add_i32 m0, s24, 0x2000
	s_nop 0
	global_load_lds_dwordx4 v[220:221], off
	v_lshl_add_u64 v[220:221], v[224:225], 0, s[6:7]
	s_mov_b32 m0, s37
	s_nop 0
	global_load_lds_dwordx4 v[220:221], off
	v_lshl_add_u64 v[220:221], v[226:227], 0, s[6:7]
	s_mov_b32 m0, s38
	s_nop 0
	global_load_lds_dwordx4 v[220:221], off
	s_waitcnt vmcnt(8)
	s_waitcnt lgkmcnt(0)
	s_setprio 1
	s_barrier
	v_mfma_f32_16x16x32_bf16 v[62:65], v[150:153], v[188:191], v[62:65]
	v_mfma_f32_16x16x32_bf16 v[58:61], v[164:167], v[188:191], v[58:61]
	v_mfma_f32_16x16x32_bf16 v[54:57], v[150:153], v[196:199], v[54:57]
	v_mfma_f32_16x16x32_bf16 v[46:49], v[164:167], v[196:199], v[46:49]
	v_mfma_f32_16x16x32_bf16 v[38:41], v[150:153], v[204:207], v[38:41]
	v_mfma_f32_16x16x32_bf16 v[30:33], v[164:167], v[204:207], v[30:33]
	v_mfma_f32_16x16x32_bf16 v[22:25], v[150:153], v[212:215], v[22:25]
	v_mfma_f32_16x16x32_bf16 v[14:17], v[164:167], v[212:215], v[14:17]
	v_mfma_f32_16x16x32_bf16 v[62:65], v[160:163], v[192:195], v[62:65]
	v_mfma_f32_16x16x32_bf16 v[58:61], v[168:171], v[192:195], v[58:61]
	v_mfma_f32_16x16x32_bf16 v[54:57], v[160:163], v[200:203], v[54:57]
	v_mfma_f32_16x16x32_bf16 v[46:49], v[168:171], v[200:203], v[46:49]
	v_mfma_f32_16x16x32_bf16 v[38:41], v[160:163], v[208:211], v[38:41]
	v_mfma_f32_16x16x32_bf16 v[30:33], v[168:171], v[208:211], v[30:33]
	v_mfma_f32_16x16x32_bf16 v[22:25], v[160:163], v[216:219], v[22:25]
	v_mfma_f32_16x16x32_bf16 v[14:17], v[168:171], v[216:219], v[14:17]
	s_setprio 0
	s_setprio 1
	v_mfma_f32_16x16x32_bf16 v[50:53], v[172:175], v[188:191], v[50:53]
	v_mfma_f32_16x16x32_bf16 v[42:45], v[180:183], v[188:191], v[42:45]
	v_mfma_f32_16x16x32_bf16 v[34:37], v[172:175], v[196:199], v[34:37]
	v_mfma_f32_16x16x32_bf16 v[26:29], v[180:183], v[196:199], v[26:29]
	v_mfma_f32_16x16x32_bf16 v[18:21], v[172:175], v[204:207], v[18:21]
	v_mfma_f32_16x16x32_bf16 v[10:13], v[180:183], v[204:207], v[10:13]
	v_mfma_f32_16x16x32_bf16 v[6:9], v[172:175], v[212:215], v[6:9]
	v_mfma_f32_16x16x32_bf16 v[2:5], v[180:183], v[212:215], v[2:5]
	v_mfma_f32_16x16x32_bf16 v[50:53], v[176:179], v[192:195], v[50:53]
	v_mfma_f32_16x16x32_bf16 v[42:45], v[184:187], v[192:195], v[42:45]
	v_mfma_f32_16x16x32_bf16 v[34:37], v[176:179], v[200:203], v[34:37]
	v_mfma_f32_16x16x32_bf16 v[26:29], v[184:187], v[200:203], v[26:29]
	v_mfma_f32_16x16x32_bf16 v[18:21], v[176:179], v[208:211], v[18:21]
	v_mfma_f32_16x16x32_bf16 v[10:13], v[184:187], v[208:211], v[10:13]
	v_mfma_f32_16x16x32_bf16 v[6:9], v[176:179], v[216:219], v[6:9]
	v_mfma_f32_16x16x32_bf16 v[2:5], v[184:187], v[216:219], v[2:5]
	s_barrier
	s_setprio 0
	s_add_i32 s47, s47, 2
	s_add_u32 s20, s20, 0x100
	s_addc_u32 s21, s21, 0
	s_add_u32 s45, s45, 0x100
	s_addc_u32 s46, s46, 0
	s_cmp_gt_u32 s47, 29
	s_cbranch_scc0 .LBB0_537
	s_and_b64 vcc, exec, s[8:9]
	s_cbranch_vccz .LBB0_540
	s_barrier

; #define PG8_STAGE(bufoff, gbase, voff) do { _Pragma("unroll") for (int _i = 0; _i < 2; ++_i) \
;         __builtin_amdgcn_global_load_lds((const unsigned*)((const char*)(gbase) + (voff)[_i]), (PG8_LAS unsigned*)(lds + (bufoff) + ldsw + _i * 8192), 16, 0, 0); } while (0)
; #define PG8_WAIT_V(n) asm volatile("s_waitcnt vmcnt(" #n ")" ::: "memory")
; #define PG8_WAIT_L(n) asm volatile("s_waitcnt lgkmcnt(" #n ")" ::: "memory")
; #define PG8_BAR __builtin_amdgcn_s_barrier()
; #define PG8_SCHED __builtin_amdgcn_sched_barrier(0)
;     __device__ __forceinline__ int nt(const pg8::Unit& u) const { return u.kind == 0 ? ntiles : q_nt(u.kind - 1); }
; template <class Epi, class Sched, bool ALIGN_EPI = true, bool SP2 = true>
; __device__ __forceinline__ void gemm_phase(PG8_LAS unsigned char* lds, const int K  , const Sched& S, const Epi& E) {
;     ...
;         for (int t = 0; t < nt; t += 2) {
;             const bool last = (t == nt - 2);
;             const char* a1 = cA + (size_t)(t + 1) * kstep;
;             const char* a2 = last ? nA : cA + (size_t)(t + 2) * kstep; const char* b2 = last ? nB : cB + (size_t)(t + 2) * kstep;
;             const char* a3 = a2 + kstep; const char* b3 = b2 + kstep;
;             if constexpr (SP2) {
;             PG8_LDB(B0, 0, 0); PG8_LDB(B1, 0, 1); PG8_SCHED; PG8_LDA(At, 0, 0); PG8_STAGE(PG8_SA(1, 1), a1 + hstep, voffA);
;             PG8_WAIT_V(8); PG8_WAIT_L(0); PG8_BAR; PG8_MMA(0, 0, At, B0); PG8_MMA(0, 1, At, B1); PG8_BAR; PG8_SCHED;
;             PG8_LDA(At, 0, 1); PG8_STAGE(PG8_SB(0, 0), b2, voffB); PG8_STAGE(PG8_SB(0, 1), b2 + hstep, voffB); PG8_STAGE(PG8_SA(0, 0), a2, voffA);
.LBB0_955:
	s_waitcnt vmcnt(0)
	ds_read_b128 v[130:133], v232
	ds_read_b128 v[134:137], v232 offset:1024
	ds_read_b128 v[138:141], v232 offset:2048
	ds_read_b128 v[142:145], v232 offset:3072
	ds_read_b128 v[146:149], v233
	ds_read_b128 v[150:153], v233 offset:1024
	ds_read_b128 v[154:157], v233 offset:2048
	ds_read_b128 v[158:161], v233 offset:3072
	ds_read_b128 v[162:165], v234
	ds_read_b128 v[166:169], v234 offset:1024
	ds_read_b128 v[170:173], v234 offset:2048
	ds_read_b128 v[174:177], v234 offset:3072
	ds_read_b128 v[178:181], v234 offset:4096
	ds_read_b128 v[182:185], v234 offset:5120
	ds_read_b128 v[186:189], v234 offset:6144
	ds_read_b128 v[190:193], v234 offset:7168
	s_add_i32 s73, s28, 2
	s_add_u32 s26, s24, 0xfff80080
	s_addc_u32 s27, s25, -1
	s_cmp_eq_u32 s13, s28
	s_cselect_b32 s28, s16, s26
	s_cselect_b32 s29, s17, s27
	s_cselect_b32 s27, s19, s21
	s_cselect_b32 s26, s18, s15
	s_add_i32 m0, s23, 0xc000
	v_lshl_add_u64 v[194:195], s[24:25], 0, v[214:215]
	global_load_lds_dwordx4 v[194:195], off
	v_lshl_add_u64 v[194:195], s[24:25], 0, v[216:217]
	s_add_i32 m0, s23, 0xe000
	s_nop 0
	global_load_lds_dwordx4 v[194:195], off
	s_waitcnt vmcnt(8)
	s_waitcnt lgkmcnt(0)
	s_setprio 1
	s_barrier
	v_mfma_f32_16x16x32_bf16 v[126:129], v[130:133], v[162:165], v[126:129]
	v_mfma_f32_16x16x32_bf16 v[122:125], v[138:141], v[162:165], v[122:125]
	v_mfma_f32_16x16x32_bf16 v[118:121], v[130:133], v[170:173], v[118:121]
	v_mfma_f32_16x16x32_bf16 v[110:113], v[138:141], v[170:173], v[110:113]
	v_mfma_f32_16x16x32_bf16 v[102:105], v[130:133], v[178:181], v[102:105]
	v_mfma_f32_16x16x32_bf16 v[94:97], v[138:141], v[178:181], v[94:97]
	v_mfma_f32_16x16x32_bf16 v[86:89], v[130:133], v[186:189], v[86:89]
	v_mfma_f32_16x16x32_bf16 v[78:81], v[138:141], v[186:189], v[78:81]
	v_mfma_f32_16x16x32_bf16 v[126:129], v[134:137], v[166:169], v[126:129]
	v_mfma_f32_16x16x32_bf16 v[122:125], v[142:145], v[166:169], v[122:125]
	v_mfma_f32_16x16x32_bf16 v[118:121], v[134:137], v[174:177], v[118:121]
	v_mfma_f32_16x16x32_bf16 v[110:113], v[142:145], v[174:177], v[110:113]
	v_mfma_f32_16x16x32_bf16 v[102:105], v[134:137], v[182:185], v[102:105]
	v_mfma_f32_16x16x32_bf16 v[94:97], v[142:145], v[182:185], v[94:97]
	v_mfma_f32_16x16x32_bf16 v[86:89], v[134:137], v[190:193], v[86:89]
	v_mfma_f32_16x16x32_bf16 v[78:81], v[142:145], v[190:193], v[78:81]
	s_setprio 0
	s_setprio 1
	v_mfma_f32_16x16x32_bf16 v[114:117], v[146:149], v[162:165], v[114:117]
	v_mfma_f32_16x16x32_bf16 v[106:109], v[154:157], v[162:165], v[106:109]
	v_mfma_f32_16x16x32_bf16 v[98:101], v[146:149], v[170:173], v[98:101]
	v_mfma_f32_16x16x32_bf16 v[90:93], v[154:157], v[170:173], v[90:93]
	v_mfma_f32_16x16x32_bf16 v[82:85], v[146:149], v[178:181], v[82:85]
	v_mfma_f32_16x16x32_bf16 v[74:77], v[154:157], v[178:181], v[74:77]
	v_mfma_f32_16x16x32_bf16 v[70:73], v[146:149], v[186:189], v[70:73]
	v_mfma_f32_16x16x32_bf16 v[66:69], v[154:157], v[186:189], v[66:69]
	v_mfma_f32_16x16x32_bf16 v[114:117], v[150:153], v[166:169], v[114:117]
	v_mfma_f32_16x16x32_bf16 v[106:109], v[158:161], v[166:169], v[106:109]
	v_mfma_f32_16x16x32_bf16 v[98:101], v[150:153], v[174:177], v[98:101]
	v_mfma_f32_16x16x32_bf16 v[90:93], v[158:161], v[174:177], v[90:93]
	v_mfma_f32_16x16x32_bf16 v[82:85], v[150:153], v[182:185], v[82:85]
	v_mfma_f32_16x16x32_bf16 v[74:77], v[158:161], v[182:185], v[74:77]
	v_mfma_f32_16x16x32_bf16 v[70:73], v[150:153], v[190:193], v[70:73]
	v_mfma_f32_16x16x32_bf16 v[66:69], v[158:161], v[190:193], v[66:69]
	s_barrier
	s_setprio 0
	s_add_i32 s74, s47, s33
	v_lshl_add_u64 v[194:195], s[26:27], 0, v[208:209]
	s_mov_b32 m0, s74
	ds_read_b128 v[162:165], v234 offset:16384
	ds_read_b128 v[166:169], v234 offset:17408
	ds_read_b128 v[170:173], v234 offset:18432
	ds_read_b128 v[174:177], v234 offset:19456
	ds_read_b128 v[178:181], v234 offset:20480
	ds_read_b128 v[182:185], v234 offset:21504
	ds_read_b128 v[186:189], v234 offset:22528
	ds_read_b128 v[190:193], v234 offset:23552
	global_load_lds_dwordx4 v[194:195], off
	s_add_i32 m0, s74, 0x2000
	s_add_u32 s74, s26, 0x80000
	v_lshl_add_u64 v[196:197], s[26:27], 0, v[212:213]
	s_addc_u32 s75, s27, 0
	s_add_i32 s76, s48, s33
	global_load_lds_dwordx4 v[196:197], off
	v_lshl_add_u64 v[198:199], s[74:75], 0, v[208:209]
	s_mov_b32 m0, s76
	v_lshl_add_u64 v[200:201], s[28:29], 0, v[210:211]
	global_load_lds_dwordx4 v[198:199], off
	v_lshl_add_u64 v[198:199], s[74:75], 0, v[212:213]
	s_add_i32 m0, s76, 0x2000
	s_nop 0
	global_load_lds_dwordx4 v[198:199], off
	v_lshl_add_u64 v[198:199], s[28:29], 0, v[206:207]
	s_mov_b32 m0, s23
	s_nop 0
	global_load_lds_dwordx4 v[198:199], off
	s_mov_b32 m0, s34
	s_nop 0
	global_load_lds_dwordx4 v[200:201], off
	s_waitcnt vmcnt(8)
	s_waitcnt lgkmcnt(0)
	s_setprio 1
	s_barrier
; #define PG8_STAGE(bufoff, gbase, voff) do { _Pragma("unroll") for (int _i = 0; _i < 2; ++_i) \
;         __builtin_amdgcn_global_load_lds((const unsigned*)((const char*)(gbase) + (voff)[_i]), (PG8_LAS unsigned*)(lds + (bufoff) + ldsw + _i * 8192), 16, 0, 0); } while (0)
; #define PG8_WAIT_V(n) asm volatile("s_waitcnt vmcnt(" #n ")" ::: "memory")
; #define PG8_WAIT_L(n) asm volatile("s_waitcnt lgkmcnt(" #n ")" ::: "memory")
; #define PG8_BAR __builtin_amdgcn_s_barrier()
; #define PG8_SCHED __builtin_amdgcn_sched_barrier(0)
; template <class Epi, class Sched, bool ALIGN_EPI = true, bool SP2 = true>
; __device__ __forceinline__ void gemm_phase(PG8_LAS unsigned char* lds, const int K  , const Sched& S, const Epi& E) {
;     ...
;             PG8_WAIT_V(8); PG8_WAIT_L(0); PG8_BAR; PG8_MMA(1, 0, At, B0); PG8_MMA(1, 1, At, B1); PG8_BAR; PG8_SCHED;
;             PG8_LDB(B0, 1, 0); PG8_LDB(B1, 1, 1); PG8_SCHED; PG8_LDA(At, 1, 0); PG8_STAGE(PG8_SA(0, 1), a2 + hstep, voffA);
;             PG8_WAIT_V(8); PG8_WAIT_L(0); PG8_BAR; PG8_MMA(0, 0, At, B0); PG8_MMA(0, 1, At, B1); PG8_BAR; PG8_SCHED;
	v_mfma_f32_16x16x32_bf16 v[62:65], v[130:133], v[162:165], v[62:65]
	v_mfma_f32_16x16x32_bf16 v[58:61], v[138:141], v[162:165], v[58:61]
	v_mfma_f32_16x16x32_bf16 v[54:57], v[130:133], v[170:173], v[54:57]
	v_mfma_f32_16x16x32_bf16 v[46:49], v[138:141], v[170:173], v[46:49]
	v_mfma_f32_16x16x32_bf16 v[38:41], v[130:133], v[178:181], v[38:41]
	v_mfma_f32_16x16x32_bf16 v[30:33], v[138:141], v[178:181], v[30:33]
	v_mfma_f32_16x16x32_bf16 v[22:25], v[130:133], v[186:189], v[22:25]
	v_mfma_f32_16x16x32_bf16 v[14:17], v[138:141], v[186:189], v[14:17]
	v_mfma_f32_16x16x32_bf16 v[62:65], v[134:137], v[166:169], v[62:65]
	v_mfma_f32_16x16x32_bf16 v[58:61], v[142:145], v[166:169], v[58:61]
	v_mfma_f32_16x16x32_bf16 v[54:57], v[134:137], v[174:177], v[54:57]
	v_mfma_f32_16x16x32_bf16 v[46:49], v[142:145], v[174:177], v[46:49]
	v_mfma_f32_16x16x32_bf16 v[38:41], v[134:137], v[182:185], v[38:41]
	v_mfma_f32_16x16x32_bf16 v[30:33], v[142:145], v[182:185], v[30:33]
	v_mfma_f32_16x16x32_bf16 v[22:25], v[134:137], v[190:193], v[22:25]
	v_mfma_f32_16x16x32_bf16 v[14:17], v[142:145], v[190:193], v[14:17]
	s_setprio 0
	s_setprio 1
	v_mfma_f32_16x16x32_bf16 v[50:53], v[146:149], v[162:165], v[50:53]
	v_mfma_f32_16x16x32_bf16 v[42:45], v[154:157], v[162:165], v[42:45]
	v_mfma_f32_16x16x32_bf16 v[34:37], v[146:149], v[170:173], v[34:37]
	v_mfma_f32_16x16x32_bf16 v[26:29], v[154:157], v[170:173], v[26:29]
	v_mfma_f32_16x16x32_bf16 v[18:21], v[146:149], v[178:181], v[18:21]
	v_mfma_f32_16x16x32_bf16 v[10:13], v[154:157], v[178:181], v[10:13]
	v_mfma_f32_16x16x32_bf16 v[6:9], v[146:149], v[186:189], v[6:9]
	v_mfma_f32_16x16x32_bf16 v[2:5], v[154:157], v[186:189], v[2:5]
	v_mfma_f32_16x16x32_bf16 v[50:53], v[150:153], v[166:169], v[50:53]
	v_mfma_f32_16x16x32_bf16 v[42:45], v[158:161], v[166:169], v[42:45]
	v_mfma_f32_16x16x32_bf16 v[34:37], v[150:153], v[174:177], v[34:37]
	v_mfma_f32_16x16x32_bf16 v[26:29], v[158:161], v[174:177], v[26:29]
	v_mfma_f32_16x16x32_bf16 v[18:21], v[150:153], v[182:185], v[18:21]
	v_mfma_f32_16x16x32_bf16 v[10:13], v[158:161], v[182:185], v[10:13]
	v_mfma_f32_16x16x32_bf16 v[6:9], v[150:153], v[190:193], v[6:9]
	v_mfma_f32_16x16x32_bf16 v[2:5], v[158:161], v[190:193], v[2:5]
	s_barrier
	s_setprio 0
	s_add_i32 s74, 0, 0x18000
	s_add_i32 s75, 0, 0x1c000
	v_add_u32_e32 v142, s74, v230
	v_add_u32_e32 v158, s75, v230
	ds_read_b128 v[130:133], v142
	ds_read_b128 v[134:137], v142 offset:1024
	ds_read_b128 v[138:141], v142 offset:2048
	ds_read_b128 v[142:145], v142 offset:3072
	ds_read_b128 v[146:149], v158
	ds_read_b128 v[150:153], v158 offset:1024
	ds_read_b128 v[154:157], v158 offset:2048
	ds_read_b128 v[158:161], v158 offset:3072
	ds_read_b128 v[162:165], v234 offset:32768
	ds_read_b128 v[166:169], v234 offset:33792
	ds_read_b128 v[170:173], v234 offset:34816
	ds_read_b128 v[174:177], v234 offset:35840
	ds_read_b128 v[178:181], v234 offset:36864
	ds_read_b128 v[182:185], v234 offset:37888
	ds_read_b128 v[186:189], v234 offset:38912
	ds_read_b128 v[190:193], v234 offset:39936
	s_add_u32 s28, s28, 0x80000
	s_addc_u32 s29, s29, 0
	s_mov_b32 m0, s35
	v_lshl_add_u64 v[202:203], s[28:29], 0, v[206:207]
	global_load_lds_dwordx4 v[202:203], off
	v_lshl_add_u64 v[202:203], s[28:29], 0, v[210:211]
	s_mov_b32 m0, s36
	s_nop 0
	global_load_lds_dwordx4 v[202:203], off
	s_waitcnt vmcnt(8)
	s_waitcnt lgkmcnt(0)
	s_setprio 1
	s_barrier
	v_mfma_f32_16x16x32_bf16 v[126:129], v[130:133], v[162:165], v[126:129]
	v_mfma_f32_16x16x32_bf16 v[122:125], v[138:141], v[162:165], v[122:125]
	v_mfma_f32_16x16x32_bf16 v[118:121], v[130:133], v[170:173], v[118:121]
	v_mfma_f32_16x16x32_bf16 v[110:113], v[138:141], v[170:173], v[110:113]
	v_mfma_f32_16x16x32_bf16 v[102:105], v[130:133], v[178:181], v[102:105]
	v_mfma_f32_16x16x32_bf16 v[94:97], v[138:141], v[178:181], v[94:97]
	v_mfma_f32_16x16x32_bf16 v[86:89], v[130:133], v[186:189], v[86:89]
	v_mfma_f32_16x16x32_bf16 v[78:81], v[138:141], v[186:189], v[78:81]
	v_mfma_f32_16x16x32_bf16 v[126:129], v[134:137], v[166:169], v[126:129]
	v_mfma_f32_16x16x32_bf16 v[122:125], v[142:145], v[166:169], v[122:125]
	v_mfma_f32_16x16x32_bf16 v[118:121], v[134:137], v[174:177], v[118:121]
	v_mfma_f32_16x16x32_bf16 v[110:113], v[142:145], v[174:177], v[110:113]
	v_mfma_f32_16x16x32_bf16 v[102:105], v[134:137], v[182:185], v[102:105]
	v_mfma_f32_16x16x32_bf16 v[94:97], v[142:145], v[182:185], v[94:97]
	v_mfma_f32_16x16x32_bf16 v[86:89], v[134:137], v[190:193], v[86:89]
	v_mfma_f32_16x16x32_bf16 v[78:81], v[142:145], v[190:193], v[78:81]
	s_setprio 0
	s_setprio 1
	v_mfma_f32_16x16x32_bf16 v[114:117], v[146:149], v[162:165], v[114:117]
	v_mfma_f32_16x16x32_bf16 v[106:109], v[154:157], v[162:165], v[106:109]
	v_mfma_f32_16x16x32_bf16 v[98:101], v[146:149], v[170:173], v[98:101]
	v_mfma_f32_16x16x32_bf16 v[90:93], v[154:157], v[170:173], v[90:93]
	v_mfma_f32_16x16x32_bf16 v[82:85], v[146:149], v[178:181], v[82:85]
	v_mfma_f32_16x16x32_bf16 v[74:77], v[154:157], v[178:181], v[74:77]
	v_mfma_f32_16x16x32_bf16 v[70:73], v[146:149], v[186:189], v[70:73]
	v_mfma_f32_16x16x32_bf16 v[66:69], v[154:157], v[186:189], v[66:69]
	v_mfma_f32_16x16x32_bf16 v[114:117], v[150:153], v[166:169], v[114:117]
	v_mfma_f32_16x16x32_bf16 v[106:109], v[158:161], v[166:169], v[106:109]
	v_mfma_f32_16x16x32_bf16 v[98:101], v[150:153], v[174:177], v[98:101]
	v_mfma_f32_16x16x32_bf16 v[90:93], v[158:161], v[174:177], v[90:93]
	v_mfma_f32_16x16x32_bf16 v[82:85], v[150:153], v[182:185], v[82:85]
	v_mfma_f32_16x16x32_bf16 v[74:77], v[158:161], v[182:185], v[74:77]
	v_mfma_f32_16x16x32_bf16 v[70:73], v[150:153], v[190:193], v[70:73]
	v_mfma_f32_16x16x32_bf16 v[66:69], v[158:161], v[190:193], v[66:69]
	s_barrier
; #define PG8_STAGE(bufoff, gbase, voff) do { _Pragma("unroll") for (int _i = 0; _i < 2; ++_i) \
;         __builtin_amdgcn_global_load_lds((const unsigned*)((const char*)(gbase) + (voff)[_i]), (PG8_LAS unsigned*)(lds + (bufoff) + ldsw + _i * 8192), 16, 0, 0); } while (0)
; #define PG8_WAIT_V(n) asm volatile("s_waitcnt vmcnt(" #n ")" ::: "memory")
; #define PG8_WAIT_L(n) asm volatile("s_waitcnt lgkmcnt(" #n ")" ::: "memory")
; #define PG8_BAR __builtin_amdgcn_s_barrier()
; #define PG8_SCHED __builtin_amdgcn_sched_barrier(0)
; template <class Epi, class Sched, bool ALIGN_EPI = true, bool SP2 = true>
; __device__ __forceinline__ void gemm_phase(PG8_LAS unsigned char* lds, const int K  , const Sched& S, const Epi& E) {
;     ...
;             PG8_LDA(At, 1, 1); PG8_STAGE(PG8_SB(1, 0), b3, voffB); PG8_STAGE(PG8_SB(1, 1), b3 + hstep, voffB); PG8_STAGE(PG8_SA(1, 0), a3, voffA);
;             PG8_WAIT_V(8); PG8_WAIT_L(0); PG8_BAR; PG8_MMA(1, 0, At, B0); PG8_MMA(1, 1, At, B1); PG8_BAR; PG8_SCHED;
	s_setprio 0
	s_add_i32 s28, s74, s33
	v_lshl_add_u64 v[194:195], v[194:195], 0, s[8:9]
	s_mov_b32 m0, s28
	ds_read_b128 v[162:165], v234 offset:49152
	ds_read_b128 v[166:169], v234 offset:50176
	ds_read_b128 v[170:173], v234 offset:51200
	ds_read_b128 v[174:177], v234 offset:52224
	ds_read_b128 v[178:181], v234 offset:53248
	ds_read_b128 v[182:185], v234 offset:54272
	ds_read_b128 v[186:189], v234 offset:55296
	ds_read_b128 v[190:193], v234 offset:56320
	global_load_lds_dwordx4 v[194:195], off
	s_add_i32 m0, s28, 0x2000
	s_add_u32 s26, s26, 0x80080
	v_lshl_add_u64 v[194:195], v[196:197], 0, s[8:9]
	s_addc_u32 s27, s27, 0
	s_add_i32 s28, s75, s33
	global_load_lds_dwordx4 v[194:195], off
	v_lshl_add_u64 v[194:195], s[26:27], 0, v[208:209]
	s_mov_b32 m0, s28
	s_nop 0
	global_load_lds_dwordx4 v[194:195], off
	v_lshl_add_u64 v[194:195], s[26:27], 0, v[212:213]
	s_add_i32 m0, s28, 0x2000
	s_nop 0
	global_load_lds_dwordx4 v[194:195], off
	v_lshl_add_u64 v[194:195], v[198:199], 0, s[8:9]
	s_mov_b32 m0, s42
	s_nop 0
	global_load_lds_dwordx4 v[194:195], off
	v_lshl_add_u64 v[194:195], v[200:201], 0, s[8:9]
	s_mov_b32 m0, s43
	s_nop 0
	global_load_lds_dwordx4 v[194:195], off
	s_waitcnt vmcnt(8)
	s_waitcnt lgkmcnt(0)
	s_setprio 1
	s_barrier
	v_mfma_f32_16x16x32_bf16 v[62:65], v[130:133], v[162:165], v[62:65]
	v_mfma_f32_16x16x32_bf16 v[58:61], v[138:141], v[162:165], v[58:61]
	v_mfma_f32_16x16x32_bf16 v[54:57], v[130:133], v[170:173], v[54:57]
	v_mfma_f32_16x16x32_bf16 v[46:49], v[138:141], v[170:173], v[46:49]
	v_mfma_f32_16x16x32_bf16 v[38:41], v[130:133], v[178:181], v[38:41]
	v_mfma_f32_16x16x32_bf16 v[30:33], v[138:141], v[178:181], v[30:33]
	v_mfma_f32_16x16x32_bf16 v[22:25], v[130:133], v[186:189], v[22:25]
	v_mfma_f32_16x16x32_bf16 v[14:17], v[138:141], v[186:189], v[14:17]
	v_mfma_f32_16x16x32_bf16 v[62:65], v[134:137], v[166:169], v[62:65]
	v_mfma_f32_16x16x32_bf16 v[58:61], v[142:145], v[166:169], v[58:61]
	v_mfma_f32_16x16x32_bf16 v[54:57], v[134:137], v[174:177], v[54:57]
	v_mfma_f32_16x16x32_bf16 v[46:49], v[142:145], v[174:177], v[46:49]
	v_mfma_f32_16x16x32_bf16 v[38:41], v[134:137], v[182:185], v[38:41]
	v_mfma_f32_16x16x32_bf16 v[30:33], v[142:145], v[182:185], v[30:33]
	v_mfma_f32_16x16x32_bf16 v[22:25], v[134:137], v[190:193], v[22:25]
	v_mfma_f32_16x16x32_bf16 v[14:17], v[142:145], v[190:193], v[14:17]
	s_setprio 0
	s_setprio 1
	v_mfma_f32_16x16x32_bf16 v[50:53], v[146:149], v[162:165], v[50:53]
	v_mfma_f32_16x16x32_bf16 v[42:45], v[154:157], v[162:165], v[42:45]
	v_mfma_f32_16x16x32_bf16 v[34:37], v[146:149], v[170:173], v[34:37]
	v_mfma_f32_16x16x32_bf16 v[26:29], v[154:157], v[170:173], v[26:29]
	v_mfma_f32_16x16x32_bf16 v[18:21], v[146:149], v[178:181], v[18:21]
	v_mfma_f32_16x16x32_bf16 v[10:13], v[154:157], v[178:181], v[10:13]
	v_mfma_f32_16x16x32_bf16 v[6:9], v[146:149], v[186:189], v[6:9]
	v_mfma_f32_16x16x32_bf16 v[2:5], v[154:157], v[186:189], v[2:5]
	v_mfma_f32_16x16x32_bf16 v[50:53], v[150:153], v[166:169], v[50:53]
	v_mfma_f32_16x16x32_bf16 v[42:45], v[158:161], v[166:169], v[42:45]
	v_mfma_f32_16x16x32_bf16 v[34:37], v[150:153], v[174:177], v[34:37]
	v_mfma_f32_16x16x32_bf16 v[26:29], v[158:161], v[174:177], v[26:29]
	v_mfma_f32_16x16x32_bf16 v[18:21], v[150:153], v[182:185], v[18:21]
	v_mfma_f32_16x16x32_bf16 v[10:13], v[158:161], v[182:185], v[10:13]
	v_mfma_f32_16x16x32_bf16 v[6:9], v[150:153], v[190:193], v[6:9]
	v_mfma_f32_16x16x32_bf16 v[2:5], v[158:161], v[190:193], v[2:5]
	s_barrier
	s_setprio 0
	s_add_u32 s24, s24, 0x100
	s_addc_u32 s25, s25, 0
	s_add_u32 s15, s15, 0x100
	s_addc_u32 s21, s21, 0
	s_cmp_ge_u32 s73, s4
	s_mov_b32 s28, s73
	s_cbranch_scc0 .LBB0_955
	s_and_b64 vcc, exec, s[10:11]
	s_cbranch_vccz .LBB0_958
	s_barrier

; #define PG8_STAGE(bufoff, gbase, voff) do { _Pragma("unroll") for (int _i = 0; _i < 2; ++_i) \
;         __builtin_amdgcn_global_load_lds((const unsigned*)((const char*)(gbase) + (voff)[_i]), (PG8_LAS unsigned*)(lds + (bufoff) + ldsw + _i * 8192), 16, 0, 0); } while (0)
; #define PG8_WAIT_V(n) asm volatile("s_waitcnt vmcnt(" #n ")" ::: "memory")
; #define PG8_WAIT_L(n) asm volatile("s_waitcnt lgkmcnt(" #n ")" ::: "memory")
; #define PG8_BAR __builtin_amdgcn_s_barrier()
; #define PG8_SCHED __builtin_amdgcn_sched_barrier(0)
;     __device__ __forceinline__ int nt(const pg8::Unit& u) const { return u.kind == 0 ? ntiles : q_nt(u.kind - 1); }
; template <class Epi, class Sched, bool ALIGN_EPI = true, bool SP2 = true>
; __device__ __forceinline__ void gemm_phase(PG8_LAS unsigned char* lds, const int K  , const Sched& S, const Epi& E) {
;     ...
;         for (int t = 0; t < nt; t += 2) {
;             const bool last = (t == nt - 2);
;             const char* a1 = cA + (size_t)(t + 1) * kstep;
;             const char* a2 = last ? nA : cA + (size_t)(t + 2) * kstep; const char* b2 = last ? nB : cB + (size_t)(t + 2) * kstep;
;             const char* a3 = a2 + kstep; const char* b3 = b2 + kstep;
;             if constexpr (SP2) {
;             PG8_LDB(B0, 0, 0); PG8_LDB(B1, 0, 1); PG8_SCHED; PG8_LDA(At, 0, 0); PG8_STAGE(PG8_SA(1, 1), a1 + hstep, voffA);
;             PG8_WAIT_V(8); PG8_WAIT_L(0); PG8_BAR; PG8_MMA(0, 0, At, B0); PG8_MMA(0, 1, At, B1); PG8_BAR; PG8_SCHED;
;             PG8_LDA(At, 0, 1); PG8_STAGE(PG8_SB(0, 0), b2, voffB); PG8_STAGE(PG8_SB(0, 1), b2 + hstep, voffB); PG8_STAGE(PG8_SA(0, 0), a2, voffA);
.LBB0_1099:
	ds_read_b128 v[148:151], v154
	ds_read_b128 v[160:163], v154 offset:1024
	ds_read_b128 v[164:167], v154 offset:2048
	ds_read_b128 v[168:171], v154 offset:3072
	ds_read_b128 v[172:175], v155
	ds_read_b128 v[176:179], v155 offset:1024
	ds_read_b128 v[180:183], v155 offset:2048
	ds_read_b128 v[184:187], v155 offset:3072
	ds_read_b128 v[188:191], v156
	ds_read_b128 v[192:195], v156 offset:1024
	ds_read_b128 v[196:199], v156 offset:2048
	ds_read_b128 v[200:203], v156 offset:3072
	ds_read_b128 v[204:207], v156 offset:4096
	ds_read_b128 v[208:211], v156 offset:5120
	ds_read_b128 v[212:215], v156 offset:6144
	ds_read_b128 v[216:219], v156 offset:7168
	s_add_u32 s24, s22, 0xfff80080
	s_addc_u32 s25, s23, -1
	s_cmp_eq_u32 s48, 28
	s_cselect_b32 s27, s15, s25
	s_cselect_b32 s26, s44, s24
	s_cselect_b32 s25, s11, s47
	s_cselect_b32 s24, s45, s46
	s_add_i32 m0, s21, 0xc000
	v_lshl_add_u64 v[220:221], s[22:23], 0, v[140:141]
	global_load_lds_dwordx4 v[220:221], off
	v_lshl_add_u64 v[220:221], s[22:23], 0, v[142:143]
	s_add_i32 m0, s21, 0xe000
	s_nop 0
	global_load_lds_dwordx4 v[220:221], off
	s_waitcnt vmcnt(8)
	s_waitcnt lgkmcnt(0)
	s_setprio 1
	s_barrier
	v_mfma_f32_16x16x32_bf16 v[126:129], v[148:151], v[188:191], v[126:129]
	v_mfma_f32_16x16x32_bf16 v[118:121], v[164:167], v[188:191], v[118:121]
	v_mfma_f32_16x16x32_bf16 v[110:113], v[148:151], v[196:199], v[110:113]
	v_mfma_f32_16x16x32_bf16 v[102:105], v[164:167], v[196:199], v[102:105]
	v_mfma_f32_16x16x32_bf16 v[94:97], v[148:151], v[204:207], v[94:97]
	v_mfma_f32_16x16x32_bf16 v[86:89], v[164:167], v[204:207], v[86:89]
	v_mfma_f32_16x16x32_bf16 v[78:81], v[148:151], v[212:215], v[78:81]
	v_mfma_f32_16x16x32_bf16 v[70:73], v[164:167], v[212:215], v[70:73]
	v_mfma_f32_16x16x32_bf16 v[126:129], v[160:163], v[192:195], v[126:129]
	v_mfma_f32_16x16x32_bf16 v[118:121], v[168:171], v[192:195], v[118:121]
	v_mfma_f32_16x16x32_bf16 v[110:113], v[160:163], v[200:203], v[110:113]
	v_mfma_f32_16x16x32_bf16 v[102:105], v[168:171], v[200:203], v[102:105]
	v_mfma_f32_16x16x32_bf16 v[94:97], v[160:163], v[208:211], v[94:97]
	v_mfma_f32_16x16x32_bf16 v[86:89], v[168:171], v[208:211], v[86:89]
	v_mfma_f32_16x16x32_bf16 v[78:81], v[160:163], v[216:219], v[78:81]
	v_mfma_f32_16x16x32_bf16 v[70:73], v[168:171], v[216:219], v[70:73]
	s_setprio 0
	s_setprio 1
	v_mfma_f32_16x16x32_bf16 v[122:125], v[172:175], v[188:191], v[122:125]
	v_mfma_f32_16x16x32_bf16 v[114:117], v[180:183], v[188:191], v[114:117]
	v_mfma_f32_16x16x32_bf16 v[106:109], v[172:175], v[196:199], v[106:109]
	v_mfma_f32_16x16x32_bf16 v[98:101], v[180:183], v[196:199], v[98:101]
	v_mfma_f32_16x16x32_bf16 v[90:93], v[172:175], v[204:207], v[90:93]
	v_mfma_f32_16x16x32_bf16 v[82:85], v[180:183], v[204:207], v[82:85]
	v_mfma_f32_16x16x32_bf16 v[74:77], v[172:175], v[212:215], v[74:77]
	v_mfma_f32_16x16x32_bf16 v[66:69], v[180:183], v[212:215], v[66:69]
	v_mfma_f32_16x16x32_bf16 v[122:125], v[176:179], v[192:195], v[122:125]
	v_mfma_f32_16x16x32_bf16 v[114:117], v[184:187], v[192:195], v[114:117]
	v_mfma_f32_16x16x32_bf16 v[106:109], v[176:179], v[200:203], v[106:109]
	v_mfma_f32_16x16x32_bf16 v[98:101], v[184:187], v[200:203], v[98:101]
	v_mfma_f32_16x16x32_bf16 v[90:93], v[176:179], v[208:211], v[90:93]
	v_mfma_f32_16x16x32_bf16 v[82:85], v[184:187], v[208:211], v[82:85]
	v_mfma_f32_16x16x32_bf16 v[74:77], v[176:179], v[216:219], v[74:77]
	v_mfma_f32_16x16x32_bf16 v[66:69], v[184:187], v[216:219], v[66:69]
	s_barrier
	s_setprio 0
	s_add_i32 s49, s39, s29
	v_lshl_add_u64 v[220:221], s[24:25], 0, v[136:137]
	s_mov_b32 m0, s49
	ds_read_b128 v[188:191], v156 offset:16384
	ds_read_b128 v[192:195], v156 offset:17408
	ds_read_b128 v[196:199], v156 offset:18432
	ds_read_b128 v[200:203], v156 offset:19456
	ds_read_b128 v[204:207], v156 offset:20480
	ds_read_b128 v[208:211], v156 offset:21504
	ds_read_b128 v[212:215], v156 offset:22528
	ds_read_b128 v[216:219], v156 offset:23552
	global_load_lds_dwordx4 v[220:221], off
	s_add_i32 m0, s49, 0x2000
	s_add_u32 s50, s24, 0x80000
	v_lshl_add_u64 v[222:223], s[24:25], 0, v[132:133]
	s_addc_u32 s51, s25, 0
	s_add_i32 s49, s40, s29
	global_load_lds_dwordx4 v[222:223], off
	v_lshl_add_u64 v[224:225], s[50:51], 0, v[136:137]
	s_mov_b32 m0, s49
	v_lshl_add_u64 v[226:227], s[26:27], 0, v[134:135]
	global_load_lds_dwordx4 v[224:225], off
	v_lshl_add_u64 v[224:225], s[50:51], 0, v[132:133]
	s_add_i32 m0, s49, 0x2000
	s_nop 0
	global_load_lds_dwordx4 v[224:225], off
	v_lshl_add_u64 v[224:225], s[26:27], 0, v[138:139]
	s_mov_b32 m0, s21
	s_nop 0
	global_load_lds_dwordx4 v[224:225], off
	s_mov_b32 m0, s31
	s_nop 0
	global_load_lds_dwordx4 v[226:227], off
	s_waitcnt vmcnt(8)
	s_waitcnt lgkmcnt(0)
	s_setprio 1
	s_barrier
; #define PG8_STAGE(bufoff, gbase, voff) do { _Pragma("unroll") for (int _i = 0; _i < 2; ++_i) \
;         __builtin_amdgcn_global_load_lds((const unsigned*)((const char*)(gbase) + (voff)[_i]), (PG8_LAS unsigned*)(lds + (bufoff) + ldsw + _i * 8192), 16, 0, 0); } while (0)
; #define PG8_WAIT_V(n) asm volatile("s_waitcnt vmcnt(" #n ")" ::: "memory")
; #define PG8_WAIT_L(n) asm volatile("s_waitcnt lgkmcnt(" #n ")" ::: "memory")
; #define PG8_BAR __builtin_amdgcn_s_barrier()
; #define PG8_SCHED __builtin_amdgcn_sched_barrier(0)
; template <class Epi, class Sched, bool ALIGN_EPI = true, bool SP2 = true>
; __device__ __forceinline__ void gemm_phase(PG8_LAS unsigned char* lds, const int K  , const Sched& S, const Epi& E) {
;     ...
;             PG8_WAIT_V(8); PG8_WAIT_L(0); PG8_BAR; PG8_MMA(1, 0, At, B0); PG8_MMA(1, 1, At, B1); PG8_BAR; PG8_SCHED;
;             PG8_LDB(B0, 1, 0); PG8_LDB(B1, 1, 1); PG8_SCHED; PG8_LDA(At, 1, 0); PG8_STAGE(PG8_SA(0, 1), a2 + hstep, voffA);
;             PG8_WAIT_V(8); PG8_WAIT_L(0); PG8_BAR; PG8_MMA(0, 0, At, B0); PG8_MMA(0, 1, At, B1); PG8_BAR; PG8_SCHED;
	v_mfma_f32_16x16x32_bf16 v[62:65], v[148:151], v[188:191], v[62:65]
	v_mfma_f32_16x16x32_bf16 v[54:57], v[164:167], v[188:191], v[54:57]
	v_mfma_f32_16x16x32_bf16 v[46:49], v[148:151], v[196:199], v[46:49]
	v_mfma_f32_16x16x32_bf16 v[38:41], v[164:167], v[196:199], v[38:41]
	v_mfma_f32_16x16x32_bf16 v[30:33], v[148:151], v[204:207], v[30:33]
	v_mfma_f32_16x16x32_bf16 v[22:25], v[164:167], v[204:207], v[22:25]
	v_mfma_f32_16x16x32_bf16 v[14:17], v[148:151], v[212:215], v[14:17]
	v_mfma_f32_16x16x32_bf16 v[6:9], v[164:167], v[212:215], v[6:9]
	v_mfma_f32_16x16x32_bf16 v[62:65], v[160:163], v[192:195], v[62:65]
	v_mfma_f32_16x16x32_bf16 v[54:57], v[168:171], v[192:195], v[54:57]
	v_mfma_f32_16x16x32_bf16 v[46:49], v[160:163], v[200:203], v[46:49]
	v_mfma_f32_16x16x32_bf16 v[38:41], v[168:171], v[200:203], v[38:41]
	v_mfma_f32_16x16x32_bf16 v[30:33], v[160:163], v[208:211], v[30:33]
	v_mfma_f32_16x16x32_bf16 v[22:25], v[168:171], v[208:211], v[22:25]
	v_mfma_f32_16x16x32_bf16 v[14:17], v[160:163], v[216:219], v[14:17]
	v_mfma_f32_16x16x32_bf16 v[6:9], v[168:171], v[216:219], v[6:9]
	s_setprio 0
	s_setprio 1
	v_mfma_f32_16x16x32_bf16 v[58:61], v[172:175], v[188:191], v[58:61]
	v_mfma_f32_16x16x32_bf16 v[50:53], v[180:183], v[188:191], v[50:53]
	v_mfma_f32_16x16x32_bf16 v[42:45], v[172:175], v[196:199], v[42:45]
	v_mfma_f32_16x16x32_bf16 v[34:37], v[180:183], v[196:199], v[34:37]
	v_mfma_f32_16x16x32_bf16 v[26:29], v[172:175], v[204:207], v[26:29]
	v_mfma_f32_16x16x32_bf16 v[18:21], v[180:183], v[204:207], v[18:21]
	v_mfma_f32_16x16x32_bf16 v[10:13], v[172:175], v[212:215], v[10:13]
	v_mfma_f32_16x16x32_bf16 v[2:5], v[180:183], v[212:215], v[2:5]
	v_mfma_f32_16x16x32_bf16 v[58:61], v[176:179], v[192:195], v[58:61]
	v_mfma_f32_16x16x32_bf16 v[50:53], v[184:187], v[192:195], v[50:53]
	v_mfma_f32_16x16x32_bf16 v[42:45], v[176:179], v[200:203], v[42:45]
	v_mfma_f32_16x16x32_bf16 v[34:37], v[184:187], v[200:203], v[34:37]
	v_mfma_f32_16x16x32_bf16 v[26:29], v[176:179], v[208:211], v[26:29]
	v_mfma_f32_16x16x32_bf16 v[18:21], v[184:187], v[208:211], v[18:21]
	v_mfma_f32_16x16x32_bf16 v[10:13], v[176:179], v[216:219], v[10:13]
	v_mfma_f32_16x16x32_bf16 v[2:5], v[184:187], v[216:219], v[2:5]
	s_barrier
	s_setprio 0
	s_add_i32 s49, 0, 0x18000
	v_add_u32_e32 v159, s49, v152
	s_add_i32 s50, 0, 0x1c000
	ds_read_b128 v[148:151], v159
	ds_read_b128 v[160:163], v159 offset:1024
	ds_read_b128 v[164:167], v159 offset:2048
	ds_read_b128 v[168:171], v159 offset:3072
	v_add_u32_e32 v159, s50, v152
	ds_read_b128 v[172:175], v159
	ds_read_b128 v[176:179], v159 offset:1024
	ds_read_b128 v[180:183], v159 offset:2048
	ds_read_b128 v[184:187], v159 offset:3072
	ds_read_b128 v[188:191], v156 offset:32768
	ds_read_b128 v[192:195], v156 offset:33792
	ds_read_b128 v[196:199], v156 offset:34816
	ds_read_b128 v[200:203], v156 offset:35840
	ds_read_b128 v[204:207], v156 offset:36864
	ds_read_b128 v[208:211], v156 offset:37888
	ds_read_b128 v[212:215], v156 offset:38912
	ds_read_b128 v[216:219], v156 offset:39936
	s_add_u32 s26, s26, 0x80000
	s_addc_u32 s27, s27, 0
	s_mov_b32 m0, s33
	v_lshl_add_u64 v[230:231], s[26:27], 0, v[138:139]
	global_load_lds_dwordx4 v[230:231], off
	v_lshl_add_u64 v[230:231], s[26:27], 0, v[134:135]
	s_mov_b32 m0, s34
	s_nop 0
	global_load_lds_dwordx4 v[230:231], off
	s_waitcnt vmcnt(8)
	s_waitcnt lgkmcnt(0)
	s_setprio 1
	s_barrier
	v_mfma_f32_16x16x32_bf16 v[126:129], v[148:151], v[188:191], v[126:129]
	v_mfma_f32_16x16x32_bf16 v[118:121], v[164:167], v[188:191], v[118:121]
	v_mfma_f32_16x16x32_bf16 v[110:113], v[148:151], v[196:199], v[110:113]
	v_mfma_f32_16x16x32_bf16 v[102:105], v[164:167], v[196:199], v[102:105]
	v_mfma_f32_16x16x32_bf16 v[94:97], v[148:151], v[204:207], v[94:97]
	v_mfma_f32_16x16x32_bf16 v[86:89], v[164:167], v[204:207], v[86:89]
	v_mfma_f32_16x16x32_bf16 v[78:81], v[148:151], v[212:215], v[78:81]
	v_mfma_f32_16x16x32_bf16 v[70:73], v[164:167], v[212:215], v[70:73]
	v_mfma_f32_16x16x32_bf16 v[126:129], v[160:163], v[192:195], v[126:129]
	v_mfma_f32_16x16x32_bf16 v[118:121], v[168:171], v[192:195], v[118:121]
	v_mfma_f32_16x16x32_bf16 v[110:113], v[160:163], v[200:203], v[110:113]
	v_mfma_f32_16x16x32_bf16 v[102:105], v[168:171], v[200:203], v[102:105]
	v_mfma_f32_16x16x32_bf16 v[94:97], v[160:163], v[208:211], v[94:97]
	v_mfma_f32_16x16x32_bf16 v[86:89], v[168:171], v[208:211], v[86:89]
	v_mfma_f32_16x16x32_bf16 v[78:81], v[160:163], v[216:219], v[78:81]
	v_mfma_f32_16x16x32_bf16 v[70:73], v[168:171], v[216:219], v[70:73]
	s_setprio 0
	s_setprio 1
	v_mfma_f32_16x16x32_bf16 v[122:125], v[172:175], v[188:191], v[122:125]
	v_mfma_f32_16x16x32_bf16 v[114:117], v[180:183], v[188:191], v[114:117]
	v_mfma_f32_16x16x32_bf16 v[106:109], v[172:175], v[196:199], v[106:109]
	v_mfma_f32_16x16x32_bf16 v[98:101], v[180:183], v[196:199], v[98:101]
	v_mfma_f32_16x16x32_bf16 v[90:93], v[172:175], v[204:207], v[90:93]
	v_mfma_f32_16x16x32_bf16 v[82:85], v[180:183], v[204:207], v[82:85]
	v_mfma_f32_16x16x32_bf16 v[74:77], v[172:175], v[212:215], v[74:77]
	v_mfma_f32_16x16x32_bf16 v[66:69], v[180:183], v[212:215], v[66:69]
	v_mfma_f32_16x16x32_bf16 v[122:125], v[176:179], v[192:195], v[122:125]
	v_mfma_f32_16x16x32_bf16 v[114:117], v[184:187], v[192:195], v[114:117]
	v_mfma_f32_16x16x32_bf16 v[106:109], v[176:179], v[200:203], v[106:109]
	v_mfma_f32_16x16x32_bf16 v[98:101], v[184:187], v[200:203], v[98:101]
	v_mfma_f32_16x16x32_bf16 v[90:93], v[176:179], v[208:211], v[90:93]
	v_mfma_f32_16x16x32_bf16 v[82:85], v[184:187], v[208:211], v[82:85]
	v_mfma_f32_16x16x32_bf16 v[74:77], v[176:179], v[216:219], v[74:77]
	v_mfma_f32_16x16x32_bf16 v[66:69], v[184:187], v[216:219], v[66:69]
	s_barrier
; #define PG8_STAGE(bufoff, gbase, voff) do { _Pragma("unroll") for (int _i = 0; _i < 2; ++_i) \
;         __builtin_amdgcn_global_load_lds((const unsigned*)((const char*)(gbase) + (voff)[_i]), (PG8_LAS unsigned*)(lds + (bufoff) + ldsw + _i * 8192), 16, 0, 0); } while (0)
; #define PG8_WAIT_V(n) asm volatile("s_waitcnt vmcnt(" #n ")" ::: "memory")
; #define PG8_WAIT_L(n) asm volatile("s_waitcnt lgkmcnt(" #n ")" ::: "memory")
; #define PG8_BAR __builtin_amdgcn_s_barrier()
; #define PG8_SCHED __builtin_amdgcn_sched_barrier(0)
; template <class Epi, class Sched, bool ALIGN_EPI = true, bool SP2 = true>
; __device__ __forceinline__ void gemm_phase(PG8_LAS unsigned char* lds, const int K  , const Sched& S, const Epi& E) {
;     ...
;             PG8_LDA(At, 1, 1); PG8_STAGE(PG8_SB(1, 0), b3, voffB); PG8_STAGE(PG8_SB(1, 1), b3 + hstep, voffB); PG8_STAGE(PG8_SA(1, 0), a3, voffA);
;             PG8_WAIT_V(8); PG8_WAIT_L(0); PG8_BAR; PG8_MMA(1, 0, At, B0); PG8_MMA(1, 1, At, B1); PG8_BAR; PG8_SCHED;
	s_setprio 0
	s_add_i32 s26, s49, s29
	v_lshl_add_u64 v[220:221], v[220:221], 0, s[4:5]
	s_mov_b32 m0, s26
	ds_read_b128 v[188:191], v156 offset:49152
	ds_read_b128 v[192:195], v156 offset:50176
	ds_read_b128 v[196:199], v156 offset:51200
	ds_read_b128 v[200:203], v156 offset:52224
	ds_read_b128 v[204:207], v156 offset:53248
	ds_read_b128 v[208:211], v156 offset:54272
	ds_read_b128 v[212:215], v156 offset:55296
	ds_read_b128 v[216:219], v156 offset:56320
	global_load_lds_dwordx4 v[220:221], off
	s_add_i32 m0, s26, 0x2000
	s_add_u32 s24, s24, 0x80080
	v_lshl_add_u64 v[220:221], v[222:223], 0, s[4:5]
	s_addc_u32 s25, s25, 0
	s_add_i32 s26, s50, s29
	global_load_lds_dwordx4 v[220:221], off
	v_lshl_add_u64 v[220:221], s[24:25], 0, v[136:137]
	s_mov_b32 m0, s26
	s_nop 0
	global_load_lds_dwordx4 v[220:221], off
	v_lshl_add_u64 v[220:221], s[24:25], 0, v[132:133]
	s_add_i32 m0, s26, 0x2000
	s_nop 0
	global_load_lds_dwordx4 v[220:221], off
	v_lshl_add_u64 v[220:221], v[224:225], 0, s[4:5]
	s_mov_b32 m0, s36
	s_nop 0
	global_load_lds_dwordx4 v[220:221], off
	v_lshl_add_u64 v[220:221], v[226:227], 0, s[4:5]
	s_mov_b32 m0, s37
	s_nop 0
	global_load_lds_dwordx4 v[220:221], off
	s_waitcnt vmcnt(8)
	s_waitcnt lgkmcnt(0)
	s_setprio 1
	s_barrier
	v_mfma_f32_16x16x32_bf16 v[62:65], v[148:151], v[188:191], v[62:65]
	v_mfma_f32_16x16x32_bf16 v[54:57], v[164:167], v[188:191], v[54:57]
	v_mfma_f32_16x16x32_bf16 v[46:49], v[148:151], v[196:199], v[46:49]
	v_mfma_f32_16x16x32_bf16 v[38:41], v[164:167], v[196:199], v[38:41]
	v_mfma_f32_16x16x32_bf16 v[30:33], v[148:151], v[204:207], v[30:33]
	v_mfma_f32_16x16x32_bf16 v[22:25], v[164:167], v[204:207], v[22:25]
	v_mfma_f32_16x16x32_bf16 v[14:17], v[148:151], v[212:215], v[14:17]
	v_mfma_f32_16x16x32_bf16 v[6:9], v[164:167], v[212:215], v[6:9]
	v_mfma_f32_16x16x32_bf16 v[62:65], v[160:163], v[192:195], v[62:65]
	v_mfma_f32_16x16x32_bf16 v[54:57], v[168:171], v[192:195], v[54:57]
	v_mfma_f32_16x16x32_bf16 v[46:49], v[160:163], v[200:203], v[46:49]
	v_mfma_f32_16x16x32_bf16 v[38:41], v[168:171], v[200:203], v[38:41]
	v_mfma_f32_16x16x32_bf16 v[30:33], v[160:163], v[208:211], v[30:33]
	v_mfma_f32_16x16x32_bf16 v[22:25], v[168:171], v[208:211], v[22:25]
	v_mfma_f32_16x16x32_bf16 v[14:17], v[160:163], v[216:219], v[14:17]
	v_mfma_f32_16x16x32_bf16 v[6:9], v[168:171], v[216:219], v[6:9]
	s_setprio 0
	s_setprio 1
	v_mfma_f32_16x16x32_bf16 v[58:61], v[172:175], v[188:191], v[58:61]
	v_mfma_f32_16x16x32_bf16 v[50:53], v[180:183], v[188:191], v[50:53]
	v_mfma_f32_16x16x32_bf16 v[42:45], v[172:175], v[196:199], v[42:45]
	v_mfma_f32_16x16x32_bf16 v[34:37], v[180:183], v[196:199], v[34:37]
	v_mfma_f32_16x16x32_bf16 v[26:29], v[172:175], v[204:207], v[26:29]
	v_mfma_f32_16x16x32_bf16 v[18:21], v[180:183], v[204:207], v[18:21]
	v_mfma_f32_16x16x32_bf16 v[10:13], v[172:175], v[212:215], v[10:13]
	v_mfma_f32_16x16x32_bf16 v[2:5], v[180:183], v[212:215], v[2:5]
	v_mfma_f32_16x16x32_bf16 v[58:61], v[176:179], v[192:195], v[58:61]
	v_mfma_f32_16x16x32_bf16 v[50:53], v[184:187], v[192:195], v[50:53]
	v_mfma_f32_16x16x32_bf16 v[42:45], v[176:179], v[200:203], v[42:45]
	v_mfma_f32_16x16x32_bf16 v[34:37], v[184:187], v[200:203], v[34:37]
	v_mfma_f32_16x16x32_bf16 v[26:29], v[176:179], v[208:211], v[26:29]
	v_mfma_f32_16x16x32_bf16 v[18:21], v[184:187], v[208:211], v[18:21]
	v_mfma_f32_16x16x32_bf16 v[10:13], v[176:179], v[216:219], v[10:13]
	v_mfma_f32_16x16x32_bf16 v[2:5], v[184:187], v[216:219], v[2:5]
	s_barrier
	s_setprio 0
	s_add_i32 s48, s48, 2
	s_add_u32 s22, s22, 0x100
	s_addc_u32 s23, s23, 0
	s_add_u32 s46, s46, 0x100
	s_addc_u32 s47, s47, 0
	s_cmp_gt_u32 s48, 29
	s_cbranch_scc0 .LBB0_1099
	s_and_b64 vcc, exec, s[8:9]
	s_cbranch_vccz .LBB0_1102
	s_barrier

; #define PG8_STAGE(bufoff, gbase, voff) do { _Pragma("unroll") for (int _i = 0; _i < 2; ++_i) \
;         __builtin_amdgcn_global_load_lds((const unsigned*)((const char*)(gbase) + (voff)[_i]), (PG8_LAS unsigned*)(lds + (bufoff) + ldsw + _i * 8192), 16, 0, 0); } while (0)
; #define PG8_WAIT_V(n) asm volatile("s_waitcnt vmcnt(" #n ")" ::: "memory")
; #define PG8_WAIT_L(n) asm volatile("s_waitcnt lgkmcnt(" #n ")" ::: "memory")
; #define PG8_BAR __builtin_amdgcn_s_barrier()
; #define PG8_SCHED __builtin_amdgcn_sched_barrier(0)
;     __device__ __forceinline__ int nt(const pg8::Unit& u) const { return u.kind == 0 ? ntiles : q_nt(u.kind - 1); }
; template <class Epi, class Sched, bool ALIGN_EPI = true, bool SP2 = true>
; __device__ __forceinline__ void gemm_phase(PG8_LAS unsigned char* lds, const int K  , const Sched& S, const Epi& E) {
;     ...
;         for (int t = 0; t < nt; t += 2) {
;             const bool last = (t == nt - 2);
;             const char* a1 = cA + (size_t)(t + 1) * kstep;
;             const char* a2 = last ? nA : cA + (size_t)(t + 2) * kstep; const char* b2 = last ? nB : cB + (size_t)(t + 2) * kstep;
;             const char* a3 = a2 + kstep; const char* b3 = b2 + kstep;
;             if constexpr (SP2) {
;             PG8_LDB(B0, 0, 0); PG8_LDB(B1, 0, 1); PG8_SCHED; PG8_LDA(At, 0, 0); PG8_STAGE(PG8_SA(1, 1), a1 + hstep, voffA);
;             PG8_WAIT_V(8); PG8_WAIT_L(0); PG8_BAR; PG8_MMA(0, 0, At, B0); PG8_MMA(0, 1, At, B1); PG8_BAR; PG8_SCHED;
;             PG8_LDA(At, 0, 1); PG8_STAGE(PG8_SB(0, 0), b2, voffB); PG8_STAGE(PG8_SB(0, 1), b2 + hstep, voffB); PG8_STAGE(PG8_SA(0, 0), a2, voffA);
;             PG8_WAIT_V(8); PG8_WAIT_L(0); PG8_BAR; PG8_MMA(1, 0, At, B0); PG8_MMA(1, 1, At, B1); PG8_BAR; PG8_SCHED;
.LBB0_1304:
	ds_read_b128 v[18:21], v233
	ds_read_b128 v[22:25], v233 offset:1024
	ds_read_b128 v[26:29], v233 offset:2048
	ds_read_b128 v[30:33], v233 offset:3072
	ds_read_b128 v[2:5], v234
	ds_read_b128 v[6:9], v234 offset:1024
	ds_read_b128 v[10:13], v234 offset:2048
	ds_read_b128 v[14:17], v234 offset:3072
	ds_read_b128 v[162:165], v235
	ds_read_b128 v[166:169], v235 offset:1024
	ds_read_b128 v[170:173], v235 offset:2048
	ds_read_b128 v[174:177], v235 offset:3072
	ds_read_b128 v[178:181], v235 offset:4096
	ds_read_b128 v[182:185], v235 offset:5120
	ds_read_b128 v[206:209], v235 offset:6144
	ds_read_b128 v[210:213], v235 offset:7168
	s_add_i32 s74, s22, 2
	s_add_u32 s20, s18, 0xfff50080
	s_addc_u32 s21, s19, -1
	s_cmp_eq_u32 s71, s22
	s_cselect_b32 s22, s14, s20
	s_cselect_b32 s23, s15, s21
	s_cselect_b32 s21, s17, s73
	s_cselect_b32 s20, s16, s72
	s_add_i32 m0, s26, 0xc000
	v_lshl_add_u64 v[186:187], s[18:19], 0, v[198:199]
	global_load_lds_dwordx4 v[186:187], off
	v_lshl_add_u64 v[186:187], s[18:19], 0, v[200:201]
	s_add_i32 m0, s26, 0xe000
	s_nop 0
	global_load_lds_dwordx4 v[186:187], off
	s_waitcnt vmcnt(8)
	s_waitcnt lgkmcnt(0)
	s_setprio 1
	s_barrier
	v_mfma_scale_f32_16x16x128_f8f6f4 v[158:161], v[18:25], v[162:169], v[158:161], v229, v229 op_sel_hi:[0,0,0]
	v_mfma_scale_f32_16x16x128_f8f6f4 v[154:157], v[26:33], v[162:169], v[154:157], v229, v229 op_sel_hi:[0,0,0]
	v_mfma_scale_f32_16x16x128_f8f6f4 v[150:153], v[18:25], v[170:177], v[150:153], v229, v229 op_sel_hi:[0,0,0]
	v_mfma_scale_f32_16x16x128_f8f6f4 v[142:145], v[26:33], v[170:177], v[142:145], v229, v229 op_sel_hi:[0,0,0]
	v_mfma_scale_f32_16x16x128_f8f6f4 v[134:137], v[18:25], v[178:185], v[134:137], v229, v229 op_sel_hi:[0,0,0]
	v_mfma_scale_f32_16x16x128_f8f6f4 v[126:129], v[26:33], v[178:185], v[126:129], v229, v229 op_sel_hi:[0,0,0]
	v_mfma_scale_f32_16x16x128_f8f6f4 v[118:121], v[18:25], v[206:213], v[118:121], v229, v229 op_sel_hi:[0,0,0]
	v_mfma_scale_f32_16x16x128_f8f6f4 v[110:113], v[26:33], v[206:213], v[110:113], v229, v229 op_sel_hi:[0,0,0]
	s_setprio 0
	s_setprio 1
	v_mfma_scale_f32_16x16x128_f8f6f4 v[146:149], v[2:9], v[162:169], v[146:149], v229, v229 op_sel_hi:[0,0,0]
	v_mfma_scale_f32_16x16x128_f8f6f4 v[138:141], v[10:17], v[162:169], v[138:141], v229, v229 op_sel_hi:[0,0,0]
	v_mfma_scale_f32_16x16x128_f8f6f4 v[130:133], v[2:9], v[170:177], v[130:133], v229, v229 op_sel_hi:[0,0,0]
	v_mfma_scale_f32_16x16x128_f8f6f4 v[122:125], v[10:17], v[170:177], v[122:125], v229, v229 op_sel_hi:[0,0,0]
	v_mfma_scale_f32_16x16x128_f8f6f4 v[114:117], v[2:9], v[178:185], v[114:117], v229, v229 op_sel_hi:[0,0,0]
	v_mfma_scale_f32_16x16x128_f8f6f4 v[106:109], v[10:17], v[178:185], v[106:109], v229, v229 op_sel_hi:[0,0,0]
	v_mfma_scale_f32_16x16x128_f8f6f4 v[102:105], v[2:9], v[206:213], v[102:105], v229, v229 op_sel_hi:[0,0,0]
	v_mfma_scale_f32_16x16x128_f8f6f4 v[98:101], v[10:17], v[206:213], v[98:101], v229, v229 op_sel_hi:[0,0,0]
	s_barrier
	s_setprio 0
	s_add_i32 s75, s40, s25
	v_lshl_add_u64 v[162:163], s[20:21], 0, v[192:193]
	s_mov_b32 m0, s75
	ds_read_b128 v[170:173], v235 offset:16384
	ds_read_b128 v[174:177], v235 offset:17408
	ds_read_b128 v[178:181], v235 offset:18432
	ds_read_b128 v[182:185], v235 offset:19456
	ds_read_b128 v[206:209], v235 offset:20480
	ds_read_b128 v[210:213], v235 offset:21504
	ds_read_b128 v[214:217], v235 offset:22528
	ds_read_b128 v[218:221], v235 offset:23552
	global_load_lds_dwordx4 v[162:163], off
	s_add_i32 m0, s75, 0x2000
	s_add_u32 s76, s20, 0xb0000
	v_lshl_add_u64 v[164:165], s[20:21], 0, v[196:197]
	s_addc_u32 s77, s21, 0
	s_add_i32 s75, s41, s25
	global_load_lds_dwordx4 v[164:165], off
	v_lshl_add_u64 v[166:167], s[76:77], 0, v[192:193]
	s_mov_b32 m0, s75
	v_lshl_add_u64 v[168:169], s[22:23], 0, v[194:195]
	global_load_lds_dwordx4 v[166:167], off
	v_lshl_add_u64 v[166:167], s[76:77], 0, v[196:197]
	s_add_i32 m0, s75, 0x2000
	s_nop 0
	global_load_lds_dwordx4 v[166:167], off
	v_lshl_add_u64 v[166:167], s[22:23], 0, v[190:191]
	s_mov_b32 m0, s26
	s_nop 0
	global_load_lds_dwordx4 v[166:167], off
	s_mov_b32 m0, s27
	s_nop 0
	global_load_lds_dwordx4 v[168:169], off
	s_waitcnt vmcnt(8)
	s_waitcnt lgkmcnt(0)
	s_setprio 1
	s_barrier
	v_mfma_scale_f32_16x16x128_f8f6f4 v[94:97], v[18:25], v[170:177], v[94:97], v229, v229 op_sel_hi:[0,0,0]
	v_mfma_scale_f32_16x16x128_f8f6f4 v[90:93], v[26:33], v[170:177], v[90:93], v229, v229 op_sel_hi:[0,0,0]
	v_mfma_scale_f32_16x16x128_f8f6f4 v[86:89], v[18:25], v[178:185], v[86:89], v229, v229 op_sel_hi:[0,0,0]
	v_mfma_scale_f32_16x16x128_f8f6f4 v[78:81], v[26:33], v[178:185], v[78:81], v229, v229 op_sel_hi:[0,0,0]
	v_mfma_scale_f32_16x16x128_f8f6f4 v[70:73], v[18:25], v[206:213], v[70:73], v229, v229 op_sel_hi:[0,0,0]
	v_mfma_scale_f32_16x16x128_f8f6f4 v[62:65], v[26:33], v[206:213], v[62:65], v229, v229 op_sel_hi:[0,0,0]
	v_mfma_scale_f32_16x16x128_f8f6f4 v[54:57], v[18:25], v[214:221], v[54:57], v229, v229 op_sel_hi:[0,0,0]
	v_mfma_scale_f32_16x16x128_f8f6f4 v[46:49], v[26:33], v[214:221], v[46:49], v229, v229 op_sel_hi:[0,0,0]
	s_setprio 0
	s_setprio 1
	v_mfma_scale_f32_16x16x128_f8f6f4 v[82:85], v[2:9], v[170:177], v[82:85], v229, v229 op_sel_hi:[0,0,0]
	v_mfma_scale_f32_16x16x128_f8f6f4 v[74:77], v[10:17], v[170:177], v[74:77], v229, v229 op_sel_hi:[0,0,0]
	v_mfma_scale_f32_16x16x128_f8f6f4 v[66:69], v[2:9], v[178:185], v[66:69], v229, v229 op_sel_hi:[0,0,0]
	v_mfma_scale_f32_16x16x128_f8f6f4 v[58:61], v[10:17], v[178:185], v[58:61], v229, v229 op_sel_hi:[0,0,0]
	v_mfma_scale_f32_16x16x128_f8f6f4 v[50:53], v[2:9], v[206:213], v[50:53], v229, v229 op_sel_hi:[0,0,0]
	v_mfma_scale_f32_16x16x128_f8f6f4 v[42:45], v[10:17], v[206:213], v[42:45], v229, v229 op_sel_hi:[0,0,0]
	v_mfma_scale_f32_16x16x128_f8f6f4 v[38:41], v[2:9], v[214:221], v[38:41], v229, v229 op_sel_hi:[0,0,0]
	v_mfma_scale_f32_16x16x128_f8f6f4 v[34:37], v[10:17], v[214:221], v[34:37], v229, v229 op_sel_hi:[0,0,0]
	s_barrier
; #define PG8_STAGE(bufoff, gbase, voff) do { _Pragma("unroll") for (int _i = 0; _i < 2; ++_i) \
;         __builtin_amdgcn_global_load_lds((const unsigned*)((const char*)(gbase) + (voff)[_i]), (PG8_LAS unsigned*)(lds + (bufoff) + ldsw + _i * 8192), 16, 0, 0); } while (0)
; #define PG8_WAIT_V(n) asm volatile("s_waitcnt vmcnt(" #n ")" ::: "memory")
; #define PG8_WAIT_L(n) asm volatile("s_waitcnt lgkmcnt(" #n ")" ::: "memory")
; #define PG8_BAR __builtin_amdgcn_s_barrier()
; #define PG8_SCHED __builtin_amdgcn_sched_barrier(0)
; template <class Epi, class Sched, bool ALIGN_EPI = true, bool SP2 = true>
; __device__ __forceinline__ void gemm_phase(PG8_LAS unsigned char* lds, const int K  , const Sched& S, const Epi& E) {
;     ...
;             PG8_LDB(B0, 1, 0); PG8_LDB(B1, 1, 1); PG8_SCHED; PG8_LDA(At, 1, 0); PG8_STAGE(PG8_SA(0, 1), a2 + hstep, voffA);
;             PG8_WAIT_V(8); PG8_WAIT_L(0); PG8_BAR; PG8_MMA(0, 0, At, B0); PG8_MMA(0, 1, At, B1); PG8_BAR; PG8_SCHED;
;             PG8_LDA(At, 1, 1); PG8_STAGE(PG8_SB(1, 0), b3, voffB); PG8_STAGE(PG8_SB(1, 1), b3 + hstep, voffB); PG8_STAGE(PG8_SA(1, 0), a3, voffA);
;             PG8_WAIT_V(8); PG8_WAIT_L(0); PG8_BAR; PG8_MMA(1, 0, At, B0); PG8_MMA(1, 1, At, B1); PG8_BAR; PG8_SCHED;
;     ...
;         if constexpr (Epi::FP8) asm volatile("s_nop 15\n\ts_nop 15\n\ts_nop 15\n\ts_nop 15\n\ts_nop 15" ::: "memory");
;         if constexpr (ALIGN_EPI) { if (wr == 0) PG8_BAR; }
	s_setprio 0
	s_add_i32 s75, 0, 0x18000
	s_add_i32 s76, 0, 0x1c000
	v_add_u32_e32 v14, s75, v231
	v_add_u32_e32 v30, s76, v231
	ds_read_b128 v[2:5], v14
	ds_read_b128 v[6:9], v14 offset:1024
	ds_read_b128 v[10:13], v14 offset:2048
	ds_read_b128 v[14:17], v14 offset:3072
	ds_read_b128 v[18:21], v30
	ds_read_b128 v[22:25], v30 offset:1024
	ds_read_b128 v[26:29], v30 offset:2048
	ds_read_b128 v[30:33], v30 offset:3072
	ds_read_b128 v[170:173], v235 offset:32768
	ds_read_b128 v[174:177], v235 offset:33792
	ds_read_b128 v[178:181], v235 offset:34816
	ds_read_b128 v[182:185], v235 offset:35840
	ds_read_b128 v[206:209], v235 offset:36864
	ds_read_b128 v[210:213], v235 offset:37888
	ds_read_b128 v[214:217], v235 offset:38912
	ds_read_b128 v[218:221], v235 offset:39936
	s_add_u32 s22, s22, 0xb0000
	s_addc_u32 s23, s23, 0
	s_mov_b32 m0, s28
	v_lshl_add_u64 v[186:187], s[22:23], 0, v[190:191]
	global_load_lds_dwordx4 v[186:187], off
	v_lshl_add_u64 v[186:187], s[22:23], 0, v[194:195]
	s_mov_b32 m0, s29
	s_nop 0
	global_load_lds_dwordx4 v[186:187], off
	s_waitcnt vmcnt(8)
	s_waitcnt lgkmcnt(0)
	s_setprio 1
	s_barrier
	v_mfma_scale_f32_16x16x128_f8f6f4 v[158:161], v[2:9], v[170:177], v[158:161], v229, v229 op_sel_hi:[0,0,0]
	v_mfma_scale_f32_16x16x128_f8f6f4 v[154:157], v[10:17], v[170:177], v[154:157], v229, v229 op_sel_hi:[0,0,0]
	v_mfma_scale_f32_16x16x128_f8f6f4 v[150:153], v[2:9], v[178:185], v[150:153], v229, v229 op_sel_hi:[0,0,0]
	v_mfma_scale_f32_16x16x128_f8f6f4 v[142:145], v[10:17], v[178:185], v[142:145], v229, v229 op_sel_hi:[0,0,0]
	v_mfma_scale_f32_16x16x128_f8f6f4 v[134:137], v[2:9], v[206:213], v[134:137], v229, v229 op_sel_hi:[0,0,0]
	v_mfma_scale_f32_16x16x128_f8f6f4 v[126:129], v[10:17], v[206:213], v[126:129], v229, v229 op_sel_hi:[0,0,0]
	v_mfma_scale_f32_16x16x128_f8f6f4 v[118:121], v[2:9], v[214:221], v[118:121], v229, v229 op_sel_hi:[0,0,0]
	v_mfma_scale_f32_16x16x128_f8f6f4 v[110:113], v[10:17], v[214:221], v[110:113], v229, v229 op_sel_hi:[0,0,0]
	s_setprio 0
	s_setprio 1
	v_mfma_scale_f32_16x16x128_f8f6f4 v[146:149], v[18:25], v[170:177], v[146:149], v229, v229 op_sel_hi:[0,0,0]
	v_mfma_scale_f32_16x16x128_f8f6f4 v[138:141], v[26:33], v[170:177], v[138:141], v229, v229 op_sel_hi:[0,0,0]
	v_mfma_scale_f32_16x16x128_f8f6f4 v[130:133], v[18:25], v[178:185], v[130:133], v229, v229 op_sel_hi:[0,0,0]
	v_mfma_scale_f32_16x16x128_f8f6f4 v[122:125], v[26:33], v[178:185], v[122:125], v229, v229 op_sel_hi:[0,0,0]
	v_mfma_scale_f32_16x16x128_f8f6f4 v[114:117], v[18:25], v[206:213], v[114:117], v229, v229 op_sel_hi:[0,0,0]
	v_mfma_scale_f32_16x16x128_f8f6f4 v[106:109], v[26:33], v[206:213], v[106:109], v229, v229 op_sel_hi:[0,0,0]
	v_mfma_scale_f32_16x16x128_f8f6f4 v[102:105], v[18:25], v[214:221], v[102:105], v229, v229 op_sel_hi:[0,0,0]
	v_mfma_scale_f32_16x16x128_f8f6f4 v[98:101], v[26:33], v[214:221], v[98:101], v229, v229 op_sel_hi:[0,0,0]
	s_barrier
	s_setprio 0
	s_add_i32 s22, s75, s25
	v_lshl_add_u64 v[162:163], v[162:163], 0, s[8:9]
	s_mov_b32 m0, s22
	ds_read_b128 v[170:173], v235 offset:49152
	ds_read_b128 v[174:177], v235 offset:50176
	ds_read_b128 v[178:181], v235 offset:51200
	ds_read_b128 v[182:185], v235 offset:52224
	ds_read_b128 v[206:209], v235 offset:53248
	ds_read_b128 v[210:213], v235 offset:54272
	ds_read_b128 v[214:217], v235 offset:55296
	ds_read_b128 v[218:221], v235 offset:56320
	global_load_lds_dwordx4 v[162:163], off
	s_add_i32 m0, s22, 0x2000
	s_add_u32 s20, s20, 0xb0080
	v_lshl_add_u64 v[162:163], v[164:165], 0, s[8:9]
	s_addc_u32 s21, s21, 0
	s_add_i32 s22, s76, s25
	global_load_lds_dwordx4 v[162:163], off
	v_lshl_add_u64 v[162:163], s[20:21], 0, v[192:193]
	s_mov_b32 m0, s22
	s_nop 0
	global_load_lds_dwordx4 v[162:163], off
	v_lshl_add_u64 v[162:163], s[20:21], 0, v[196:197]
	s_add_i32 m0, s22, 0x2000
	s_nop 0
	global_load_lds_dwordx4 v[162:163], off
	v_lshl_add_u64 v[162:163], v[166:167], 0, s[8:9]
	s_mov_b32 m0, s36
	s_nop 0
	global_load_lds_dwordx4 v[162:163], off
	v_lshl_add_u64 v[162:163], v[168:169], 0, s[8:9]
	s_mov_b32 m0, s37
	s_nop 0
	global_load_lds_dwordx4 v[162:163], off
	s_waitcnt vmcnt(8)
	s_waitcnt lgkmcnt(0)
	s_setprio 1
	s_barrier
	v_mfma_scale_f32_16x16x128_f8f6f4 v[94:97], v[2:9], v[170:177], v[94:97], v229, v229 op_sel_hi:[0,0,0]
	v_mfma_scale_f32_16x16x128_f8f6f4 v[90:93], v[10:17], v[170:177], v[90:93], v229, v229 op_sel_hi:[0,0,0]
	v_mfma_scale_f32_16x16x128_f8f6f4 v[86:89], v[2:9], v[178:185], v[86:89], v229, v229 op_sel_hi:[0,0,0]
	v_mfma_scale_f32_16x16x128_f8f6f4 v[78:81], v[10:17], v[178:185], v[78:81], v229, v229 op_sel_hi:[0,0,0]
	v_mfma_scale_f32_16x16x128_f8f6f4 v[70:73], v[2:9], v[206:213], v[70:73], v229, v229 op_sel_hi:[0,0,0]
	v_mfma_scale_f32_16x16x128_f8f6f4 v[62:65], v[10:17], v[206:213], v[62:65], v229, v229 op_sel_hi:[0,0,0]
	v_mfma_scale_f32_16x16x128_f8f6f4 v[54:57], v[2:9], v[214:221], v[54:57], v229, v229 op_sel_hi:[0,0,0]
	v_mfma_scale_f32_16x16x128_f8f6f4 v[46:49], v[10:17], v[214:221], v[46:49], v229, v229 op_sel_hi:[0,0,0]
	s_setprio 0
	s_setprio 1
	v_mfma_scale_f32_16x16x128_f8f6f4 v[82:85], v[18:25], v[170:177], v[82:85], v229, v229 op_sel_hi:[0,0,0]
	v_mfma_scale_f32_16x16x128_f8f6f4 v[74:77], v[26:33], v[170:177], v[74:77], v229, v229 op_sel_hi:[0,0,0]
	v_mfma_scale_f32_16x16x128_f8f6f4 v[66:69], v[18:25], v[178:185], v[66:69], v229, v229 op_sel_hi:[0,0,0]
	v_mfma_scale_f32_16x16x128_f8f6f4 v[58:61], v[26:33], v[178:185], v[58:61], v229, v229 op_sel_hi:[0,0,0]
	v_mfma_scale_f32_16x16x128_f8f6f4 v[50:53], v[18:25], v[206:213], v[50:53], v229, v229 op_sel_hi:[0,0,0]
	v_mfma_scale_f32_16x16x128_f8f6f4 v[42:45], v[26:33], v[206:213], v[42:45], v229, v229 op_sel_hi:[0,0,0]
	v_mfma_scale_f32_16x16x128_f8f6f4 v[38:41], v[18:25], v[214:221], v[38:41], v229, v229 op_sel_hi:[0,0,0]
	v_mfma_scale_f32_16x16x128_f8f6f4 v[34:37], v[26:33], v[214:221], v[34:37], v229, v229 op_sel_hi:[0,0,0]
	s_barrier
	s_setprio 0
	s_add_u32 s18, s18, 0x100
	s_addc_u32 s19, s19, 0
	s_add_u32 s72, s72, 0x100
	s_addc_u32 s73, s73, 0
	s_cmp_ge_u32 s74, s4
	s_mov_b32 s22, s74
	s_cbranch_scc0 .LBB0_1304
	s_nop 15
	s_nop 15
	s_nop 15
	s_nop 15
	s_nop 15
	s_and_b64 vcc, exec, s[10:11]
	s_cbranch_vccz .LBB0_1307
	s_barrier

; #define PG8_STAGE(bufoff, gbase, voff) do { _Pragma("unroll") for (int _i = 0; _i < 2; ++_i) \
;         __builtin_amdgcn_global_load_lds((const unsigned*)((const char*)(gbase) + (voff)[_i]), (PG8_LAS unsigned*)(lds + (bufoff) + ldsw + _i * 8192), 16, 0, 0); } while (0)
; #define PG8_WAIT_V(n) asm volatile("s_waitcnt vmcnt(" #n ")" ::: "memory")
; #define PG8_WAIT_L(n) asm volatile("s_waitcnt lgkmcnt(" #n ")" ::: "memory")
; #define PG8_BAR __builtin_amdgcn_s_barrier()
; #define PG8_SCHED __builtin_amdgcn_sched_barrier(0)
;     __device__ __forceinline__ int nt(const pg8::Unit& u) const { return u.kind == 0 ? ntiles : q_nt(u.kind - 1); }
; template <class Epi, class Sched, bool ALIGN_EPI = true, bool SP2 = true>
; __device__ __forceinline__ void gemm_phase(PG8_LAS unsigned char* lds, const int K  , const Sched& S, const Epi& E) {
;     ...
;         for (int t = 0; t < nt; t += 2) {
;             const bool last = (t == nt - 2);
;             const char* a1 = cA + (size_t)(t + 1) * kstep;
;             const char* a2 = last ? nA : cA + (size_t)(t + 2) * kstep; const char* b2 = last ? nB : cB + (size_t)(t + 2) * kstep;
;             const char* a3 = a2 + kstep; const char* b3 = b2 + kstep;
;             if constexpr (SP2) {
;             PG8_LDB(B0, 0, 0); PG8_LDB(B1, 0, 1); PG8_SCHED; PG8_LDA(At, 0, 0); PG8_STAGE(PG8_SA(1, 1), a1 + hstep, voffA);
;             PG8_WAIT_V(8); PG8_WAIT_L(0); PG8_BAR; PG8_MMA(0, 0, At, B0); PG8_MMA(0, 1, At, B1); PG8_BAR; PG8_SCHED;
;             PG8_LDA(At, 0, 1); PG8_STAGE(PG8_SB(0, 0), b2, voffB); PG8_STAGE(PG8_SB(0, 1), b2 + hstep, voffB); PG8_STAGE(PG8_SA(0, 0), a2, voffA);
.LBB0_1448:
	ds_read_b128 v[148:151], v154
	ds_read_b128 v[160:163], v154 offset:1024
	ds_read_b128 v[164:167], v154 offset:2048
	ds_read_b128 v[168:171], v154 offset:3072
	ds_read_b128 v[172:175], v155
	ds_read_b128 v[176:179], v155 offset:1024
	ds_read_b128 v[180:183], v155 offset:2048
	ds_read_b128 v[184:187], v155 offset:3072
	ds_read_b128 v[188:191], v156
	ds_read_b128 v[192:195], v156 offset:1024
	ds_read_b128 v[196:199], v156 offset:2048
	ds_read_b128 v[200:203], v156 offset:3072
	ds_read_b128 v[204:207], v156 offset:4096
	ds_read_b128 v[208:211], v156 offset:5120
	ds_read_b128 v[212:215], v156 offset:6144
	ds_read_b128 v[216:219], v156 offset:7168
	s_add_u32 s26, s24, 0xfff80080
	s_addc_u32 s27, s25, -1
	s_cmp_eq_u32 s50, 28
	s_cselect_b32 s29, s17, s27
	s_cselect_b32 s28, s46, s26
	s_cselect_b32 s27, s11, s49
	s_cselect_b32 s26, s47, s48
	s_add_i32 m0, s23, 0xc000
	v_lshl_add_u64 v[220:221], s[24:25], 0, v[140:141]
	global_load_lds_dwordx4 v[220:221], off
	v_lshl_add_u64 v[220:221], s[24:25], 0, v[142:143]
	s_add_i32 m0, s23, 0xe000
	s_nop 0
	global_load_lds_dwordx4 v[220:221], off
	s_waitcnt vmcnt(8)
	s_waitcnt lgkmcnt(0)
	s_setprio 1
	s_barrier
	v_mfma_f32_16x16x32_bf16 v[126:129], v[148:151], v[188:191], v[126:129]
	v_mfma_f32_16x16x32_bf16 v[118:121], v[164:167], v[188:191], v[118:121]
	v_mfma_f32_16x16x32_bf16 v[110:113], v[148:151], v[196:199], v[110:113]
	v_mfma_f32_16x16x32_bf16 v[102:105], v[164:167], v[196:199], v[102:105]
	v_mfma_f32_16x16x32_bf16 v[94:97], v[148:151], v[204:207], v[94:97]
	v_mfma_f32_16x16x32_bf16 v[86:89], v[164:167], v[204:207], v[86:89]
	v_mfma_f32_16x16x32_bf16 v[78:81], v[148:151], v[212:215], v[78:81]
	v_mfma_f32_16x16x32_bf16 v[70:73], v[164:167], v[212:215], v[70:73]
	v_mfma_f32_16x16x32_bf16 v[126:129], v[160:163], v[192:195], v[126:129]
	v_mfma_f32_16x16x32_bf16 v[118:121], v[168:171], v[192:195], v[118:121]
	v_mfma_f32_16x16x32_bf16 v[110:113], v[160:163], v[200:203], v[110:113]
	v_mfma_f32_16x16x32_bf16 v[102:105], v[168:171], v[200:203], v[102:105]
	v_mfma_f32_16x16x32_bf16 v[94:97], v[160:163], v[208:211], v[94:97]
	v_mfma_f32_16x16x32_bf16 v[86:89], v[168:171], v[208:211], v[86:89]
	v_mfma_f32_16x16x32_bf16 v[78:81], v[160:163], v[216:219], v[78:81]
	v_mfma_f32_16x16x32_bf16 v[70:73], v[168:171], v[216:219], v[70:73]
	s_setprio 0
	s_setprio 1
	v_mfma_f32_16x16x32_bf16 v[122:125], v[172:175], v[188:191], v[122:125]
	v_mfma_f32_16x16x32_bf16 v[114:117], v[180:183], v[188:191], v[114:117]
	v_mfma_f32_16x16x32_bf16 v[106:109], v[172:175], v[196:199], v[106:109]
	v_mfma_f32_16x16x32_bf16 v[98:101], v[180:183], v[196:199], v[98:101]
	v_mfma_f32_16x16x32_bf16 v[90:93], v[172:175], v[204:207], v[90:93]
	v_mfma_f32_16x16x32_bf16 v[82:85], v[180:183], v[204:207], v[82:85]
	v_mfma_f32_16x16x32_bf16 v[74:77], v[172:175], v[212:215], v[74:77]
	v_mfma_f32_16x16x32_bf16 v[66:69], v[180:183], v[212:215], v[66:69]
	v_mfma_f32_16x16x32_bf16 v[122:125], v[176:179], v[192:195], v[122:125]
	v_mfma_f32_16x16x32_bf16 v[114:117], v[184:187], v[192:195], v[114:117]
	v_mfma_f32_16x16x32_bf16 v[106:109], v[176:179], v[200:203], v[106:109]
	v_mfma_f32_16x16x32_bf16 v[98:101], v[184:187], v[200:203], v[98:101]
	v_mfma_f32_16x16x32_bf16 v[90:93], v[176:179], v[208:211], v[90:93]
	v_mfma_f32_16x16x32_bf16 v[82:85], v[184:187], v[208:211], v[82:85]
	v_mfma_f32_16x16x32_bf16 v[74:77], v[176:179], v[216:219], v[74:77]
	v_mfma_f32_16x16x32_bf16 v[66:69], v[184:187], v[216:219], v[66:69]
	s_barrier
	s_setprio 0
	s_add_i32 s51, s41, s31
	v_lshl_add_u64 v[220:221], s[26:27], 0, v[136:137]
	s_mov_b32 m0, s51
	ds_read_b128 v[188:191], v156 offset:16384
	ds_read_b128 v[192:195], v156 offset:17408
	ds_read_b128 v[196:199], v156 offset:18432
	ds_read_b128 v[200:203], v156 offset:19456
	ds_read_b128 v[204:207], v156 offset:20480
	ds_read_b128 v[208:211], v156 offset:21504
	ds_read_b128 v[212:215], v156 offset:22528
	ds_read_b128 v[216:219], v156 offset:23552
	global_load_lds_dwordx4 v[220:221], off
	s_add_i32 m0, s51, 0x2000
	s_add_u32 s68, s26, 0x80000
	v_lshl_add_u64 v[222:223], s[26:27], 0, v[132:133]
	s_addc_u32 s69, s27, 0
	s_add_i32 s51, s42, s31
	global_load_lds_dwordx4 v[222:223], off
	v_lshl_add_u64 v[224:225], s[68:69], 0, v[136:137]
	s_mov_b32 m0, s51
	v_lshl_add_u64 v[226:227], s[28:29], 0, v[134:135]
	global_load_lds_dwordx4 v[224:225], off
	v_lshl_add_u64 v[224:225], s[68:69], 0, v[132:133]
	s_add_i32 m0, s51, 0x2000
	s_nop 0
	global_load_lds_dwordx4 v[224:225], off
	v_lshl_add_u64 v[224:225], s[28:29], 0, v[138:139]
	s_mov_b32 m0, s23
	s_nop 0
	global_load_lds_dwordx4 v[224:225], off
	s_mov_b32 m0, s34
	s_nop 0
	global_load_lds_dwordx4 v[226:227], off
	s_waitcnt vmcnt(8)
	s_waitcnt lgkmcnt(0)
	s_setprio 1
	s_barrier
; #define PG8_STAGE(bufoff, gbase, voff) do { _Pragma("unroll") for (int _i = 0; _i < 2; ++_i) \
;         __builtin_amdgcn_global_load_lds((const unsigned*)((const char*)(gbase) + (voff)[_i]), (PG8_LAS unsigned*)(lds + (bufoff) + ldsw + _i * 8192), 16, 0, 0); } while (0)
; #define PG8_WAIT_V(n) asm volatile("s_waitcnt vmcnt(" #n ")" ::: "memory")
; #define PG8_WAIT_L(n) asm volatile("s_waitcnt lgkmcnt(" #n ")" ::: "memory")
; #define PG8_BAR __builtin_amdgcn_s_barrier()
; #define PG8_SCHED __builtin_amdgcn_sched_barrier(0)
; template <class Epi, class Sched, bool ALIGN_EPI = true, bool SP2 = true>
; __device__ __forceinline__ void gemm_phase(PG8_LAS unsigned char* lds, const int K  , const Sched& S, const Epi& E) {
;     ...
;             PG8_WAIT_V(8); PG8_WAIT_L(0); PG8_BAR; PG8_MMA(1, 0, At, B0); PG8_MMA(1, 1, At, B1); PG8_BAR; PG8_SCHED;
;             PG8_LDB(B0, 1, 0); PG8_LDB(B1, 1, 1); PG8_SCHED; PG8_LDA(At, 1, 0); PG8_STAGE(PG8_SA(0, 1), a2 + hstep, voffA);
;             PG8_WAIT_V(8); PG8_WAIT_L(0); PG8_BAR; PG8_MMA(0, 0, At, B0); PG8_MMA(0, 1, At, B1); PG8_BAR; PG8_SCHED;
	v_mfma_f32_16x16x32_bf16 v[62:65], v[148:151], v[188:191], v[62:65]
	v_mfma_f32_16x16x32_bf16 v[54:57], v[164:167], v[188:191], v[54:57]
	v_mfma_f32_16x16x32_bf16 v[46:49], v[148:151], v[196:199], v[46:49]
	v_mfma_f32_16x16x32_bf16 v[38:41], v[164:167], v[196:199], v[38:41]
	v_mfma_f32_16x16x32_bf16 v[30:33], v[148:151], v[204:207], v[30:33]
	v_mfma_f32_16x16x32_bf16 v[22:25], v[164:167], v[204:207], v[22:25]
	v_mfma_f32_16x16x32_bf16 v[14:17], v[148:151], v[212:215], v[14:17]
	v_mfma_f32_16x16x32_bf16 v[6:9], v[164:167], v[212:215], v[6:9]
	v_mfma_f32_16x16x32_bf16 v[62:65], v[160:163], v[192:195], v[62:65]
	v_mfma_f32_16x16x32_bf16 v[54:57], v[168:171], v[192:195], v[54:57]
	v_mfma_f32_16x16x32_bf16 v[46:49], v[160:163], v[200:203], v[46:49]
	v_mfma_f32_16x16x32_bf16 v[38:41], v[168:171], v[200:203], v[38:41]
	v_mfma_f32_16x16x32_bf16 v[30:33], v[160:163], v[208:211], v[30:33]
	v_mfma_f32_16x16x32_bf16 v[22:25], v[168:171], v[208:211], v[22:25]
	v_mfma_f32_16x16x32_bf16 v[14:17], v[160:163], v[216:219], v[14:17]
	v_mfma_f32_16x16x32_bf16 v[6:9], v[168:171], v[216:219], v[6:9]
	s_setprio 0
	s_setprio 1
	v_mfma_f32_16x16x32_bf16 v[58:61], v[172:175], v[188:191], v[58:61]
	v_mfma_f32_16x16x32_bf16 v[50:53], v[180:183], v[188:191], v[50:53]
	v_mfma_f32_16x16x32_bf16 v[42:45], v[172:175], v[196:199], v[42:45]
	v_mfma_f32_16x16x32_bf16 v[34:37], v[180:183], v[196:199], v[34:37]
	v_mfma_f32_16x16x32_bf16 v[26:29], v[172:175], v[204:207], v[26:29]
	v_mfma_f32_16x16x32_bf16 v[18:21], v[180:183], v[204:207], v[18:21]
	v_mfma_f32_16x16x32_bf16 v[10:13], v[172:175], v[212:215], v[10:13]
	v_mfma_f32_16x16x32_bf16 v[2:5], v[180:183], v[212:215], v[2:5]
	v_mfma_f32_16x16x32_bf16 v[58:61], v[176:179], v[192:195], v[58:61]
	v_mfma_f32_16x16x32_bf16 v[50:53], v[184:187], v[192:195], v[50:53]
	v_mfma_f32_16x16x32_bf16 v[42:45], v[176:179], v[200:203], v[42:45]
	v_mfma_f32_16x16x32_bf16 v[34:37], v[184:187], v[200:203], v[34:37]
	v_mfma_f32_16x16x32_bf16 v[26:29], v[176:179], v[208:211], v[26:29]
	v_mfma_f32_16x16x32_bf16 v[18:21], v[184:187], v[208:211], v[18:21]
	v_mfma_f32_16x16x32_bf16 v[10:13], v[176:179], v[216:219], v[10:13]
	v_mfma_f32_16x16x32_bf16 v[2:5], v[184:187], v[216:219], v[2:5]
	s_barrier
	s_setprio 0
	s_add_i32 s51, 0, 0x18000
	v_add_u32_e32 v159, s51, v152
	s_add_i32 s68, 0, 0x1c000
	ds_read_b128 v[148:151], v159
	ds_read_b128 v[160:163], v159 offset:1024
	ds_read_b128 v[164:167], v159 offset:2048
	ds_read_b128 v[168:171], v159 offset:3072
	v_add_u32_e32 v159, s68, v152
	ds_read_b128 v[172:175], v159
	ds_read_b128 v[176:179], v159 offset:1024
	ds_read_b128 v[180:183], v159 offset:2048
	ds_read_b128 v[184:187], v159 offset:3072
	ds_read_b128 v[188:191], v156 offset:32768
	ds_read_b128 v[192:195], v156 offset:33792
	ds_read_b128 v[196:199], v156 offset:34816
	ds_read_b128 v[200:203], v156 offset:35840
	ds_read_b128 v[204:207], v156 offset:36864
	ds_read_b128 v[208:211], v156 offset:37888
	ds_read_b128 v[212:215], v156 offset:38912
	ds_read_b128 v[216:219], v156 offset:39936
	s_add_u32 s28, s28, 0x80000
	s_addc_u32 s29, s29, 0
	s_mov_b32 m0, s35
	v_lshl_add_u64 v[230:231], s[28:29], 0, v[138:139]
	global_load_lds_dwordx4 v[230:231], off
	v_lshl_add_u64 v[230:231], s[28:29], 0, v[134:135]
	s_mov_b32 m0, s36
	s_nop 0
	global_load_lds_dwordx4 v[230:231], off
	s_waitcnt vmcnt(8)
	s_waitcnt lgkmcnt(0)
	s_setprio 1
	s_barrier
	v_mfma_f32_16x16x32_bf16 v[126:129], v[148:151], v[188:191], v[126:129]
	v_mfma_f32_16x16x32_bf16 v[118:121], v[164:167], v[188:191], v[118:121]
	v_mfma_f32_16x16x32_bf16 v[110:113], v[148:151], v[196:199], v[110:113]
	v_mfma_f32_16x16x32_bf16 v[102:105], v[164:167], v[196:199], v[102:105]
	v_mfma_f32_16x16x32_bf16 v[94:97], v[148:151], v[204:207], v[94:97]
	v_mfma_f32_16x16x32_bf16 v[86:89], v[164:167], v[204:207], v[86:89]
	v_mfma_f32_16x16x32_bf16 v[78:81], v[148:151], v[212:215], v[78:81]
	v_mfma_f32_16x16x32_bf16 v[70:73], v[164:167], v[212:215], v[70:73]
	v_mfma_f32_16x16x32_bf16 v[126:129], v[160:163], v[192:195], v[126:129]
	v_mfma_f32_16x16x32_bf16 v[118:121], v[168:171], v[192:195], v[118:121]
	v_mfma_f32_16x16x32_bf16 v[110:113], v[160:163], v[200:203], v[110:113]
	v_mfma_f32_16x16x32_bf16 v[102:105], v[168:171], v[200:203], v[102:105]
	v_mfma_f32_16x16x32_bf16 v[94:97], v[160:163], v[208:211], v[94:97]
	v_mfma_f32_16x16x32_bf16 v[86:89], v[168:171], v[208:211], v[86:89]
	v_mfma_f32_16x16x32_bf16 v[78:81], v[160:163], v[216:219], v[78:81]
	v_mfma_f32_16x16x32_bf16 v[70:73], v[168:171], v[216:219], v[70:73]
	s_setprio 0
	s_setprio 1
	v_mfma_f32_16x16x32_bf16 v[122:125], v[172:175], v[188:191], v[122:125]
	v_mfma_f32_16x16x32_bf16 v[114:117], v[180:183], v[188:191], v[114:117]
	v_mfma_f32_16x16x32_bf16 v[106:109], v[172:175], v[196:199], v[106:109]
	v_mfma_f32_16x16x32_bf16 v[98:101], v[180:183], v[196:199], v[98:101]
	v_mfma_f32_16x16x32_bf16 v[90:93], v[172:175], v[204:207], v[90:93]
	v_mfma_f32_16x16x32_bf16 v[82:85], v[180:183], v[204:207], v[82:85]
	v_mfma_f32_16x16x32_bf16 v[74:77], v[172:175], v[212:215], v[74:77]
	v_mfma_f32_16x16x32_bf16 v[66:69], v[180:183], v[212:215], v[66:69]
	v_mfma_f32_16x16x32_bf16 v[122:125], v[176:179], v[192:195], v[122:125]
	v_mfma_f32_16x16x32_bf16 v[114:117], v[184:187], v[192:195], v[114:117]
	v_mfma_f32_16x16x32_bf16 v[106:109], v[176:179], v[200:203], v[106:109]
	v_mfma_f32_16x16x32_bf16 v[98:101], v[184:187], v[200:203], v[98:101]
	v_mfma_f32_16x16x32_bf16 v[90:93], v[176:179], v[208:211], v[90:93]
	v_mfma_f32_16x16x32_bf16 v[82:85], v[184:187], v[208:211], v[82:85]
	v_mfma_f32_16x16x32_bf16 v[74:77], v[176:179], v[216:219], v[74:77]
	v_mfma_f32_16x16x32_bf16 v[66:69], v[184:187], v[216:219], v[66:69]
	s_barrier
; #define PG8_STAGE(bufoff, gbase, voff) do { _Pragma("unroll") for (int _i = 0; _i < 2; ++_i) \
;         __builtin_amdgcn_global_load_lds((const unsigned*)((const char*)(gbase) + (voff)[_i]), (PG8_LAS unsigned*)(lds + (bufoff) + ldsw + _i * 8192), 16, 0, 0); } while (0)
; #define PG8_WAIT_V(n) asm volatile("s_waitcnt vmcnt(" #n ")" ::: "memory")
; #define PG8_WAIT_L(n) asm volatile("s_waitcnt lgkmcnt(" #n ")" ::: "memory")
; #define PG8_BAR __builtin_amdgcn_s_barrier()
; #define PG8_SCHED __builtin_amdgcn_sched_barrier(0)
; template <class Epi, class Sched, bool ALIGN_EPI = true, bool SP2 = true>
; __device__ __forceinline__ void gemm_phase(PG8_LAS unsigned char* lds, const int K  , const Sched& S, const Epi& E) {
;     ...
;             PG8_LDA(At, 1, 1); PG8_STAGE(PG8_SB(1, 0), b3, voffB); PG8_STAGE(PG8_SB(1, 1), b3 + hstep, voffB); PG8_STAGE(PG8_SA(1, 0), a3, voffA);
;             PG8_WAIT_V(8); PG8_WAIT_L(0); PG8_BAR; PG8_MMA(1, 0, At, B0); PG8_MMA(1, 1, At, B1); PG8_BAR; PG8_SCHED;
	s_setprio 0
	s_add_i32 s28, s51, s31
	v_lshl_add_u64 v[220:221], v[220:221], 0, s[4:5]
	s_mov_b32 m0, s28
	ds_read_b128 v[188:191], v156 offset:49152
	ds_read_b128 v[192:195], v156 offset:50176
	ds_read_b128 v[196:199], v156 offset:51200
	ds_read_b128 v[200:203], v156 offset:52224
	ds_read_b128 v[204:207], v156 offset:53248
	ds_read_b128 v[208:211], v156 offset:54272
	ds_read_b128 v[212:215], v156 offset:55296
	ds_read_b128 v[216:219], v156 offset:56320
	global_load_lds_dwordx4 v[220:221], off
	s_add_i32 m0, s28, 0x2000
	s_add_u32 s26, s26, 0x80080
	v_lshl_add_u64 v[220:221], v[222:223], 0, s[4:5]
	s_addc_u32 s27, s27, 0
	s_add_i32 s28, s68, s31
	global_load_lds_dwordx4 v[220:221], off
	v_lshl_add_u64 v[220:221], s[26:27], 0, v[136:137]
	s_mov_b32 m0, s28
	s_nop 0
	global_load_lds_dwordx4 v[220:221], off
	v_lshl_add_u64 v[220:221], s[26:27], 0, v[132:133]
	s_add_i32 m0, s28, 0x2000
	s_nop 0
	global_load_lds_dwordx4 v[220:221], off
	v_lshl_add_u64 v[220:221], v[224:225], 0, s[4:5]
	s_mov_b32 m0, s38
	s_nop 0
	global_load_lds_dwordx4 v[220:221], off
	v_lshl_add_u64 v[220:221], v[226:227], 0, s[4:5]
	s_mov_b32 m0, s39
	s_nop 0
	global_load_lds_dwordx4 v[220:221], off
	s_waitcnt vmcnt(8)
	s_waitcnt lgkmcnt(0)
	s_setprio 1
	s_barrier
	v_mfma_f32_16x16x32_bf16 v[62:65], v[148:151], v[188:191], v[62:65]
	v_mfma_f32_16x16x32_bf16 v[54:57], v[164:167], v[188:191], v[54:57]
	v_mfma_f32_16x16x32_bf16 v[46:49], v[148:151], v[196:199], v[46:49]
	v_mfma_f32_16x16x32_bf16 v[38:41], v[164:167], v[196:199], v[38:41]
	v_mfma_f32_16x16x32_bf16 v[30:33], v[148:151], v[204:207], v[30:33]
	v_mfma_f32_16x16x32_bf16 v[22:25], v[164:167], v[204:207], v[22:25]
	v_mfma_f32_16x16x32_bf16 v[14:17], v[148:151], v[212:215], v[14:17]
	v_mfma_f32_16x16x32_bf16 v[6:9], v[164:167], v[212:215], v[6:9]
	v_mfma_f32_16x16x32_bf16 v[62:65], v[160:163], v[192:195], v[62:65]
	v_mfma_f32_16x16x32_bf16 v[54:57], v[168:171], v[192:195], v[54:57]
	v_mfma_f32_16x16x32_bf16 v[46:49], v[160:163], v[200:203], v[46:49]
	v_mfma_f32_16x16x32_bf16 v[38:41], v[168:171], v[200:203], v[38:41]
	v_mfma_f32_16x16x32_bf16 v[30:33], v[160:163], v[208:211], v[30:33]
	v_mfma_f32_16x16x32_bf16 v[22:25], v[168:171], v[208:211], v[22:25]
	v_mfma_f32_16x16x32_bf16 v[14:17], v[160:163], v[216:219], v[14:17]
	v_mfma_f32_16x16x32_bf16 v[6:9], v[168:171], v[216:219], v[6:9]
	s_setprio 0
	s_setprio 1
	v_mfma_f32_16x16x32_bf16 v[58:61], v[172:175], v[188:191], v[58:61]
	v_mfma_f32_16x16x32_bf16 v[50:53], v[180:183], v[188:191], v[50:53]
	v_mfma_f32_16x16x32_bf16 v[42:45], v[172:175], v[196:199], v[42:45]
	v_mfma_f32_16x16x32_bf16 v[34:37], v[180:183], v[196:199], v[34:37]
	v_mfma_f32_16x16x32_bf16 v[26:29], v[172:175], v[204:207], v[26:29]
	v_mfma_f32_16x16x32_bf16 v[18:21], v[180:183], v[204:207], v[18:21]
	v_mfma_f32_16x16x32_bf16 v[10:13], v[172:175], v[212:215], v[10:13]
	v_mfma_f32_16x16x32_bf16 v[2:5], v[180:183], v[212:215], v[2:5]
	v_mfma_f32_16x16x32_bf16 v[58:61], v[176:179], v[192:195], v[58:61]
	v_mfma_f32_16x16x32_bf16 v[50:53], v[184:187], v[192:195], v[50:53]
	v_mfma_f32_16x16x32_bf16 v[42:45], v[176:179], v[200:203], v[42:45]
	v_mfma_f32_16x16x32_bf16 v[34:37], v[184:187], v[200:203], v[34:37]
	v_mfma_f32_16x16x32_bf16 v[26:29], v[176:179], v[208:211], v[26:29]
	v_mfma_f32_16x16x32_bf16 v[18:21], v[184:187], v[208:211], v[18:21]
	v_mfma_f32_16x16x32_bf16 v[10:13], v[176:179], v[216:219], v[10:13]
	v_mfma_f32_16x16x32_bf16 v[2:5], v[184:187], v[216:219], v[2:5]
	s_barrier
	s_setprio 0
	s_add_i32 s50, s50, 2
	s_add_u32 s24, s24, 0x100
	s_addc_u32 s25, s25, 0
	s_add_u32 s48, s48, 0x100
	s_addc_u32 s49, s49, 0
	s_cmp_gt_u32 s50, 29
	s_cbranch_scc0 .LBB0_1448
	s_and_b64 vcc, exec, s[8:9]
	s_cbranch_vccz .LBB0_1451
	s_barrier

; #define PG8_STAGE(bufoff, gbase, voff) do { _Pragma("unroll") for (int _i = 0; _i < 2; ++_i) \
;         __builtin_amdgcn_global_load_lds((const unsigned*)((const char*)(gbase) + (voff)[_i]), (PG8_LAS unsigned*)(lds + (bufoff) + ldsw + _i * 8192), 16, 0, 0); } while (0)
; #define PG8_WAIT_V(n) asm volatile("s_waitcnt vmcnt(" #n ")" ::: "memory")
; #define PG8_WAIT_L(n) asm volatile("s_waitcnt lgkmcnt(" #n ")" ::: "memory")
; #define PG8_BAR __builtin_amdgcn_s_barrier()
; #define PG8_SCHED __builtin_amdgcn_sched_barrier(0)
;     __device__ __forceinline__ int nt(const pg8::Unit& u) const { return u.kind == 0 ? ntiles : q_nt(u.kind - 1); }
; template <class Epi, class Sched, bool ALIGN_EPI = true, bool SP2 = true>
; __device__ __forceinline__ void gemm_phase(PG8_LAS unsigned char* lds, const int K  , const Sched& S, const Epi& E) {
;     ...
;         for (int t = 0; t < nt; t += 2) {
;             const bool last = (t == nt - 2);
;             const char* a1 = cA + (size_t)(t + 1) * kstep;
;             const char* a2 = last ? nA : cA + (size_t)(t + 2) * kstep; const char* b2 = last ? nB : cB + (size_t)(t + 2) * kstep;
;             const char* a3 = a2 + kstep; const char* b3 = b2 + kstep;
;             if constexpr (SP2) {
;             PG8_LDB(B0, 0, 0); PG8_LDB(B1, 0, 1); PG8_SCHED; PG8_LDA(At, 0, 0); PG8_STAGE(PG8_SA(1, 1), a1 + hstep, voffA);
;             PG8_WAIT_V(8); PG8_WAIT_L(0); PG8_BAR; PG8_MMA(0, 0, At, B0); PG8_MMA(0, 1, At, B1); PG8_BAR; PG8_SCHED;
;             PG8_LDA(At, 0, 1); PG8_STAGE(PG8_SB(0, 0), b2, voffB); PG8_STAGE(PG8_SB(0, 1), b2 + hstep, voffB); PG8_STAGE(PG8_SA(0, 0), a2, voffA);
;             PG8_WAIT_V(8); PG8_WAIT_L(0); PG8_BAR; PG8_MMA(1, 0, At, B0); PG8_MMA(1, 1, At, B1); PG8_BAR; PG8_SCHED;
.LBB0_1695:
	ds_read_b128 v[18:21], v233
	ds_read_b128 v[22:25], v233 offset:1024
	ds_read_b128 v[26:29], v233 offset:2048
	ds_read_b128 v[30:33], v233 offset:3072
	ds_read_b128 v[2:5], v234
	ds_read_b128 v[6:9], v234 offset:1024
	ds_read_b128 v[10:13], v234 offset:2048
	ds_read_b128 v[14:17], v234 offset:3072
	ds_read_b128 v[162:165], v235
	ds_read_b128 v[166:169], v235 offset:1024
	ds_read_b128 v[170:173], v235 offset:2048
	ds_read_b128 v[174:177], v235 offset:3072
	ds_read_b128 v[178:181], v235 offset:4096
	ds_read_b128 v[182:185], v235 offset:5120
	ds_read_b128 v[206:209], v235 offset:6144
	ds_read_b128 v[210:213], v235 offset:7168
	s_add_i32 s74, s24, 2
	s_add_u32 s22, s20, 0xfff50080
	s_addc_u32 s23, s21, -1
	s_cmp_eq_u32 s71, s24
	s_cselect_b32 s24, s16, s22
	s_cselect_b32 s25, s17, s23
	s_cselect_b32 s23, s19, s73
	s_cselect_b32 s22, s18, s72
	s_add_i32 m0, s28, 0xc000
	v_lshl_add_u64 v[186:187], s[20:21], 0, v[198:199]
	global_load_lds_dwordx4 v[186:187], off
	v_lshl_add_u64 v[186:187], s[20:21], 0, v[200:201]
	s_add_i32 m0, s28, 0xe000
	s_nop 0
	global_load_lds_dwordx4 v[186:187], off
	s_waitcnt vmcnt(8)
	s_waitcnt lgkmcnt(0)
	s_setprio 1
	s_barrier
	v_mfma_scale_f32_16x16x128_f8f6f4 v[158:161], v[18:25], v[162:169], v[158:161], v229, v229 op_sel_hi:[0,0,0]
	v_mfma_scale_f32_16x16x128_f8f6f4 v[154:157], v[26:33], v[162:169], v[154:157], v229, v229 op_sel_hi:[0,0,0]
	v_mfma_scale_f32_16x16x128_f8f6f4 v[150:153], v[18:25], v[170:177], v[150:153], v229, v229 op_sel_hi:[0,0,0]
	v_mfma_scale_f32_16x16x128_f8f6f4 v[142:145], v[26:33], v[170:177], v[142:145], v229, v229 op_sel_hi:[0,0,0]
	v_mfma_scale_f32_16x16x128_f8f6f4 v[134:137], v[18:25], v[178:185], v[134:137], v229, v229 op_sel_hi:[0,0,0]
	v_mfma_scale_f32_16x16x128_f8f6f4 v[126:129], v[26:33], v[178:185], v[126:129], v229, v229 op_sel_hi:[0,0,0]
	v_mfma_scale_f32_16x16x128_f8f6f4 v[118:121], v[18:25], v[206:213], v[118:121], v229, v229 op_sel_hi:[0,0,0]
	v_mfma_scale_f32_16x16x128_f8f6f4 v[110:113], v[26:33], v[206:213], v[110:113], v229, v229 op_sel_hi:[0,0,0]
	s_setprio 0
	s_setprio 1
	v_mfma_scale_f32_16x16x128_f8f6f4 v[146:149], v[2:9], v[162:169], v[146:149], v229, v229 op_sel_hi:[0,0,0]
	v_mfma_scale_f32_16x16x128_f8f6f4 v[138:141], v[10:17], v[162:169], v[138:141], v229, v229 op_sel_hi:[0,0,0]
	v_mfma_scale_f32_16x16x128_f8f6f4 v[130:133], v[2:9], v[170:177], v[130:133], v229, v229 op_sel_hi:[0,0,0]
	v_mfma_scale_f32_16x16x128_f8f6f4 v[122:125], v[10:17], v[170:177], v[122:125], v229, v229 op_sel_hi:[0,0,0]
	v_mfma_scale_f32_16x16x128_f8f6f4 v[114:117], v[2:9], v[178:185], v[114:117], v229, v229 op_sel_hi:[0,0,0]
	v_mfma_scale_f32_16x16x128_f8f6f4 v[106:109], v[10:17], v[178:185], v[106:109], v229, v229 op_sel_hi:[0,0,0]
	v_mfma_scale_f32_16x16x128_f8f6f4 v[102:105], v[2:9], v[206:213], v[102:105], v229, v229 op_sel_hi:[0,0,0]
	v_mfma_scale_f32_16x16x128_f8f6f4 v[98:101], v[10:17], v[206:213], v[98:101], v229, v229 op_sel_hi:[0,0,0]
	s_barrier
	s_setprio 0
	s_add_i32 s75, s40, s27
	v_lshl_add_u64 v[162:163], s[22:23], 0, v[192:193]
	s_mov_b32 m0, s75
	ds_read_b128 v[170:173], v235 offset:16384
	ds_read_b128 v[174:177], v235 offset:17408
	ds_read_b128 v[178:181], v235 offset:18432
	ds_read_b128 v[182:185], v235 offset:19456
	ds_read_b128 v[206:209], v235 offset:20480
	ds_read_b128 v[210:213], v235 offset:21504
	ds_read_b128 v[214:217], v235 offset:22528
	ds_read_b128 v[218:221], v235 offset:23552
	global_load_lds_dwordx4 v[162:163], off
	s_add_i32 m0, s75, 0x2000
	s_add_u32 s78, s22, 0xb0000
	v_lshl_add_u64 v[164:165], s[22:23], 0, v[196:197]
	s_addc_u32 s79, s23, 0
	s_add_i32 s75, s41, s27
	global_load_lds_dwordx4 v[164:165], off
	v_lshl_add_u64 v[166:167], s[78:79], 0, v[192:193]
	s_mov_b32 m0, s75
	v_lshl_add_u64 v[168:169], s[24:25], 0, v[194:195]
	global_load_lds_dwordx4 v[166:167], off
	v_lshl_add_u64 v[166:167], s[78:79], 0, v[196:197]
	s_add_i32 m0, s75, 0x2000
	s_nop 0
	global_load_lds_dwordx4 v[166:167], off
	v_lshl_add_u64 v[166:167], s[24:25], 0, v[190:191]
	s_mov_b32 m0, s28
	s_nop 0
	global_load_lds_dwordx4 v[166:167], off
	s_mov_b32 m0, s29
	s_nop 0
	global_load_lds_dwordx4 v[168:169], off
	s_waitcnt vmcnt(8)
	s_waitcnt lgkmcnt(0)
	s_setprio 1
	s_barrier
	v_mfma_scale_f32_16x16x128_f8f6f4 v[94:97], v[18:25], v[170:177], v[94:97], v229, v229 op_sel_hi:[0,0,0]
	v_mfma_scale_f32_16x16x128_f8f6f4 v[90:93], v[26:33], v[170:177], v[90:93], v229, v229 op_sel_hi:[0,0,0]
	v_mfma_scale_f32_16x16x128_f8f6f4 v[86:89], v[18:25], v[178:185], v[86:89], v229, v229 op_sel_hi:[0,0,0]
	v_mfma_scale_f32_16x16x128_f8f6f4 v[78:81], v[26:33], v[178:185], v[78:81], v229, v229 op_sel_hi:[0,0,0]
	v_mfma_scale_f32_16x16x128_f8f6f4 v[70:73], v[18:25], v[206:213], v[70:73], v229, v229 op_sel_hi:[0,0,0]
	v_mfma_scale_f32_16x16x128_f8f6f4 v[62:65], v[26:33], v[206:213], v[62:65], v229, v229 op_sel_hi:[0,0,0]
	v_mfma_scale_f32_16x16x128_f8f6f4 v[54:57], v[18:25], v[214:221], v[54:57], v229, v229 op_sel_hi:[0,0,0]
	v_mfma_scale_f32_16x16x128_f8f6f4 v[46:49], v[26:33], v[214:221], v[46:49], v229, v229 op_sel_hi:[0,0,0]
	s_setprio 0
	s_setprio 1
	v_mfma_scale_f32_16x16x128_f8f6f4 v[82:85], v[2:9], v[170:177], v[82:85], v229, v229 op_sel_hi:[0,0,0]
	v_mfma_scale_f32_16x16x128_f8f6f4 v[74:77], v[10:17], v[170:177], v[74:77], v229, v229 op_sel_hi:[0,0,0]
	v_mfma_scale_f32_16x16x128_f8f6f4 v[66:69], v[2:9], v[178:185], v[66:69], v229, v229 op_sel_hi:[0,0,0]
	v_mfma_scale_f32_16x16x128_f8f6f4 v[58:61], v[10:17], v[178:185], v[58:61], v229, v229 op_sel_hi:[0,0,0]
	v_mfma_scale_f32_16x16x128_f8f6f4 v[50:53], v[2:9], v[206:213], v[50:53], v229, v229 op_sel_hi:[0,0,0]
	v_mfma_scale_f32_16x16x128_f8f6f4 v[42:45], v[10:17], v[206:213], v[42:45], v229, v229 op_sel_hi:[0,0,0]
	v_mfma_scale_f32_16x16x128_f8f6f4 v[38:41], v[2:9], v[214:221], v[38:41], v229, v229 op_sel_hi:[0,0,0]
	v_mfma_scale_f32_16x16x128_f8f6f4 v[34:37], v[10:17], v[214:221], v[34:37], v229, v229 op_sel_hi:[0,0,0]
	s_barrier
; #define PG8_STAGE(bufoff, gbase, voff) do { _Pragma("unroll") for (int _i = 0; _i < 2; ++_i) \
;         __builtin_amdgcn_global_load_lds((const unsigned*)((const char*)(gbase) + (voff)[_i]), (PG8_LAS unsigned*)(lds + (bufoff) + ldsw + _i * 8192), 16, 0, 0); } while (0)
; #define PG8_WAIT_V(n) asm volatile("s_waitcnt vmcnt(" #n ")" ::: "memory")
; #define PG8_WAIT_L(n) asm volatile("s_waitcnt lgkmcnt(" #n ")" ::: "memory")
; #define PG8_BAR __builtin_amdgcn_s_barrier()
; #define PG8_SCHED __builtin_amdgcn_sched_barrier(0)
; template <class Epi, class Sched, bool ALIGN_EPI = true, bool SP2 = true>
; __device__ __forceinline__ void gemm_phase(PG8_LAS unsigned char* lds, const int K  , const Sched& S, const Epi& E) {
;     ...
;             PG8_LDB(B0, 1, 0); PG8_LDB(B1, 1, 1); PG8_SCHED; PG8_LDA(At, 1, 0); PG8_STAGE(PG8_SA(0, 1), a2 + hstep, voffA);
;             PG8_WAIT_V(8); PG8_WAIT_L(0); PG8_BAR; PG8_MMA(0, 0, At, B0); PG8_MMA(0, 1, At, B1); PG8_BAR; PG8_SCHED;
;             PG8_LDA(At, 1, 1); PG8_STAGE(PG8_SB(1, 0), b3, voffB); PG8_STAGE(PG8_SB(1, 1), b3 + hstep, voffB); PG8_STAGE(PG8_SA(1, 0), a3, voffA);
;             PG8_WAIT_V(8); PG8_WAIT_L(0); PG8_BAR; PG8_MMA(1, 0, At, B0); PG8_MMA(1, 1, At, B1); PG8_BAR; PG8_SCHED;
;     ...
;         if constexpr (Epi::FP8) asm volatile("s_nop 15\n\ts_nop 15\n\ts_nop 15\n\ts_nop 15\n\ts_nop 15" ::: "memory");
;         if constexpr (ALIGN_EPI) { if (wr == 0) PG8_BAR; }
	s_setprio 0
	s_add_i32 s75, 0, 0x18000
	s_add_i32 s78, 0, 0x1c000
	v_add_u32_e32 v14, s75, v231
	v_add_u32_e32 v30, s78, v231
	ds_read_b128 v[2:5], v14
	ds_read_b128 v[6:9], v14 offset:1024
	ds_read_b128 v[10:13], v14 offset:2048
	ds_read_b128 v[14:17], v14 offset:3072
	ds_read_b128 v[18:21], v30
	ds_read_b128 v[22:25], v30 offset:1024
	ds_read_b128 v[26:29], v30 offset:2048
	ds_read_b128 v[30:33], v30 offset:3072
	ds_read_b128 v[170:173], v235 offset:32768
	ds_read_b128 v[174:177], v235 offset:33792
	ds_read_b128 v[178:181], v235 offset:34816
	ds_read_b128 v[182:185], v235 offset:35840
	ds_read_b128 v[206:209], v235 offset:36864
	ds_read_b128 v[210:213], v235 offset:37888
	ds_read_b128 v[214:217], v235 offset:38912
	ds_read_b128 v[218:221], v235 offset:39936
	s_add_u32 s24, s24, 0xb0000
	s_addc_u32 s25, s25, 0
	s_mov_b32 m0, s30
	v_lshl_add_u64 v[186:187], s[24:25], 0, v[190:191]
	global_load_lds_dwordx4 v[186:187], off
	v_lshl_add_u64 v[186:187], s[24:25], 0, v[194:195]
	s_mov_b32 m0, s31
	s_nop 0
	global_load_lds_dwordx4 v[186:187], off
	s_waitcnt vmcnt(8)
	s_waitcnt lgkmcnt(0)
	s_setprio 1
	s_barrier
	v_mfma_scale_f32_16x16x128_f8f6f4 v[158:161], v[2:9], v[170:177], v[158:161], v229, v229 op_sel_hi:[0,0,0]
	v_mfma_scale_f32_16x16x128_f8f6f4 v[154:157], v[10:17], v[170:177], v[154:157], v229, v229 op_sel_hi:[0,0,0]
	v_mfma_scale_f32_16x16x128_f8f6f4 v[150:153], v[2:9], v[178:185], v[150:153], v229, v229 op_sel_hi:[0,0,0]
	v_mfma_scale_f32_16x16x128_f8f6f4 v[142:145], v[10:17], v[178:185], v[142:145], v229, v229 op_sel_hi:[0,0,0]
	v_mfma_scale_f32_16x16x128_f8f6f4 v[134:137], v[2:9], v[206:213], v[134:137], v229, v229 op_sel_hi:[0,0,0]
	v_mfma_scale_f32_16x16x128_f8f6f4 v[126:129], v[10:17], v[206:213], v[126:129], v229, v229 op_sel_hi:[0,0,0]
	v_mfma_scale_f32_16x16x128_f8f6f4 v[118:121], v[2:9], v[214:221], v[118:121], v229, v229 op_sel_hi:[0,0,0]
	v_mfma_scale_f32_16x16x128_f8f6f4 v[110:113], v[10:17], v[214:221], v[110:113], v229, v229 op_sel_hi:[0,0,0]
	s_setprio 0
	s_setprio 1
	v_mfma_scale_f32_16x16x128_f8f6f4 v[146:149], v[18:25], v[170:177], v[146:149], v229, v229 op_sel_hi:[0,0,0]
	v_mfma_scale_f32_16x16x128_f8f6f4 v[138:141], v[26:33], v[170:177], v[138:141], v229, v229 op_sel_hi:[0,0,0]
	v_mfma_scale_f32_16x16x128_f8f6f4 v[130:133], v[18:25], v[178:185], v[130:133], v229, v229 op_sel_hi:[0,0,0]
	v_mfma_scale_f32_16x16x128_f8f6f4 v[122:125], v[26:33], v[178:185], v[122:125], v229, v229 op_sel_hi:[0,0,0]
	v_mfma_scale_f32_16x16x128_f8f6f4 v[114:117], v[18:25], v[206:213], v[114:117], v229, v229 op_sel_hi:[0,0,0]
	v_mfma_scale_f32_16x16x128_f8f6f4 v[106:109], v[26:33], v[206:213], v[106:109], v229, v229 op_sel_hi:[0,0,0]
	v_mfma_scale_f32_16x16x128_f8f6f4 v[102:105], v[18:25], v[214:221], v[102:105], v229, v229 op_sel_hi:[0,0,0]
	v_mfma_scale_f32_16x16x128_f8f6f4 v[98:101], v[26:33], v[214:221], v[98:101], v229, v229 op_sel_hi:[0,0,0]
	s_barrier
	s_setprio 0
	s_add_i32 s24, s75, s27
	v_lshl_add_u64 v[162:163], v[162:163], 0, s[10:11]
	s_mov_b32 m0, s24
	ds_read_b128 v[170:173], v235 offset:49152
	ds_read_b128 v[174:177], v235 offset:50176
	ds_read_b128 v[178:181], v235 offset:51200
	ds_read_b128 v[182:185], v235 offset:52224
	ds_read_b128 v[206:209], v235 offset:53248
	ds_read_b128 v[210:213], v235 offset:54272
	ds_read_b128 v[214:217], v235 offset:55296
	ds_read_b128 v[218:221], v235 offset:56320
	global_load_lds_dwordx4 v[162:163], off
	s_add_i32 m0, s24, 0x2000
	s_add_u32 s22, s22, 0xb0080
	v_lshl_add_u64 v[162:163], v[164:165], 0, s[10:11]
	s_addc_u32 s23, s23, 0
	s_add_i32 s24, s78, s27
	global_load_lds_dwordx4 v[162:163], off
	v_lshl_add_u64 v[162:163], s[22:23], 0, v[192:193]
	s_mov_b32 m0, s24
	s_nop 0
	global_load_lds_dwordx4 v[162:163], off
	v_lshl_add_u64 v[162:163], s[22:23], 0, v[196:197]
	s_add_i32 m0, s24, 0x2000
	s_nop 0
	global_load_lds_dwordx4 v[162:163], off
	v_lshl_add_u64 v[162:163], v[166:167], 0, s[10:11]
	s_mov_b32 m0, s36
	s_nop 0
	global_load_lds_dwordx4 v[162:163], off
	v_lshl_add_u64 v[162:163], v[168:169], 0, s[10:11]
	s_mov_b32 m0, s37
	s_nop 0
	global_load_lds_dwordx4 v[162:163], off
	s_waitcnt vmcnt(8)
	s_waitcnt lgkmcnt(0)
	s_setprio 1
	s_barrier
	v_mfma_scale_f32_16x16x128_f8f6f4 v[94:97], v[2:9], v[170:177], v[94:97], v229, v229 op_sel_hi:[0,0,0]
	v_mfma_scale_f32_16x16x128_f8f6f4 v[90:93], v[10:17], v[170:177], v[90:93], v229, v229 op_sel_hi:[0,0,0]
	v_mfma_scale_f32_16x16x128_f8f6f4 v[86:89], v[2:9], v[178:185], v[86:89], v229, v229 op_sel_hi:[0,0,0]
	v_mfma_scale_f32_16x16x128_f8f6f4 v[78:81], v[10:17], v[178:185], v[78:81], v229, v229 op_sel_hi:[0,0,0]
	v_mfma_scale_f32_16x16x128_f8f6f4 v[70:73], v[2:9], v[206:213], v[70:73], v229, v229 op_sel_hi:[0,0,0]
	v_mfma_scale_f32_16x16x128_f8f6f4 v[62:65], v[10:17], v[206:213], v[62:65], v229, v229 op_sel_hi:[0,0,0]
	v_mfma_scale_f32_16x16x128_f8f6f4 v[54:57], v[2:9], v[214:221], v[54:57], v229, v229 op_sel_hi:[0,0,0]
	v_mfma_scale_f32_16x16x128_f8f6f4 v[46:49], v[10:17], v[214:221], v[46:49], v229, v229 op_sel_hi:[0,0,0]
	s_setprio 0
	s_setprio 1
	v_mfma_scale_f32_16x16x128_f8f6f4 v[82:85], v[18:25], v[170:177], v[82:85], v229, v229 op_sel_hi:[0,0,0]
	v_mfma_scale_f32_16x16x128_f8f6f4 v[74:77], v[26:33], v[170:177], v[74:77], v229, v229 op_sel_hi:[0,0,0]
	v_mfma_scale_f32_16x16x128_f8f6f4 v[66:69], v[18:25], v[178:185], v[66:69], v229, v229 op_sel_hi:[0,0,0]
	v_mfma_scale_f32_16x16x128_f8f6f4 v[58:61], v[26:33], v[178:185], v[58:61], v229, v229 op_sel_hi:[0,0,0]
	v_mfma_scale_f32_16x16x128_f8f6f4 v[50:53], v[18:25], v[206:213], v[50:53], v229, v229 op_sel_hi:[0,0,0]
	v_mfma_scale_f32_16x16x128_f8f6f4 v[42:45], v[26:33], v[206:213], v[42:45], v229, v229 op_sel_hi:[0,0,0]
	v_mfma_scale_f32_16x16x128_f8f6f4 v[38:41], v[18:25], v[214:221], v[38:41], v229, v229 op_sel_hi:[0,0,0]
	v_mfma_scale_f32_16x16x128_f8f6f4 v[34:37], v[26:33], v[214:221], v[34:37], v229, v229 op_sel_hi:[0,0,0]
	s_barrier
	s_setprio 0
	s_add_u32 s20, s20, 0x100
	s_addc_u32 s21, s21, 0
	s_add_u32 s72, s72, 0x100
	s_addc_u32 s73, s73, 0
	s_cmp_ge_u32 s74, s4
	s_mov_b32 s24, s74
	s_cbranch_scc0 .LBB0_1695
	s_nop 15
	s_nop 15
	s_nop 15
	s_nop 15
	s_nop 15
	s_and_b64 vcc, exec, s[12:13]
	s_cbranch_vccz .LBB0_1698
	s_barrier

; #define PG8_STAGE(bufoff, gbase, voff) do { _Pragma("unroll") for (int _i = 0; _i < 2; ++_i) \
;         __builtin_amdgcn_global_load_lds((const unsigned*)((const char*)(gbase) + (voff)[_i]), (PG8_LAS unsigned*)(lds + (bufoff) + ldsw + _i * 8192), 16, 0, 0); } while (0)
; #define PG8_WAIT_V(n) asm volatile("s_waitcnt vmcnt(" #n ")" ::: "memory")
; #define PG8_WAIT_L(n) asm volatile("s_waitcnt lgkmcnt(" #n ")" ::: "memory")
; #define PG8_BAR __builtin_amdgcn_s_barrier()
; #define PG8_SCHED __builtin_amdgcn_sched_barrier(0)
;     __device__ __forceinline__ int nt(const pg8::Unit& u) const { return u.kind == 0 ? ntiles : q_nt(u.kind - 1); }
; template <class Epi, class Sched, bool ALIGN_EPI = true, bool SP2 = true>
; __device__ __forceinline__ void gemm_phase(PG8_LAS unsigned char* lds, const int K  , const Sched& S, const Epi& E) {
;     ...
;         for (int t = 0; t < nt; t += 2) {
;             const bool last = (t == nt - 2);
;             const char* a1 = cA + (size_t)(t + 1) * kstep;
;             const char* a2 = last ? nA : cA + (size_t)(t + 2) * kstep; const char* b2 = last ? nB : cB + (size_t)(t + 2) * kstep;
;             const char* a3 = a2 + kstep; const char* b3 = b2 + kstep;
;             if constexpr (SP2) {
;             PG8_LDB(B0, 0, 0); PG8_LDB(B1, 0, 1); PG8_SCHED; PG8_LDA(At, 0, 0); PG8_STAGE(PG8_SA(1, 1), a1 + hstep, voffA);
;             PG8_WAIT_V(8); PG8_WAIT_L(0); PG8_BAR; PG8_MMA(0, 0, At, B0); PG8_MMA(0, 1, At, B1); PG8_BAR; PG8_SCHED;
;             PG8_LDA(At, 0, 1); PG8_STAGE(PG8_SB(0, 0), b2, voffB); PG8_STAGE(PG8_SB(0, 1), b2 + hstep, voffB); PG8_STAGE(PG8_SA(0, 0), a2, voffA);
.LBB0_1847:
	ds_read_b128 v[130:133], v176
	ds_read_b128 v[134:137], v176 offset:1024
	ds_read_b128 v[138:141], v176 offset:2048
	ds_read_b128 v[142:145], v176 offset:3072
	ds_read_b128 v[168:171], v177
	ds_read_b128 v[184:187], v177 offset:1024
	ds_read_b128 v[188:191], v177 offset:2048
	ds_read_b128 v[192:195], v177 offset:3072
	ds_read_b128 v[196:199], v178
	ds_read_b128 v[200:203], v178 offset:1024
	ds_read_b128 v[204:207], v178 offset:2048
	ds_read_b128 v[208:211], v178 offset:3072
	ds_read_b128 v[212:215], v178 offset:4096
	ds_read_b128 v[216:219], v178 offset:5120
	ds_read_b128 v[220:223], v178 offset:6144
	ds_read_b128 v[224:227], v178 offset:7168
	s_add_u32 s22, s0, 0xfff80080
	s_addc_u32 s23, s1, -1
	s_cmp_eq_u32 s51, 28
	s_cselect_b32 s25, s7, s23
	s_cselect_b32 s24, s47, s22
	s_cselect_b32 s23, s11, s50
	s_cselect_b32 s22, s48, s49
	s_add_i32 m0, s27, 0xc000
	v_lshl_add_u64 v[230:231], s[0:1], 0, v[160:161]
	global_load_lds_dwordx4 v[230:231], off
	v_lshl_add_u64 v[230:231], s[0:1], 0, v[162:163]
	s_add_i32 m0, s27, 0xe000
	s_nop 0
	global_load_lds_dwordx4 v[230:231], off
	s_waitcnt vmcnt(8)
	s_waitcnt lgkmcnt(0)
	s_setprio 1
	s_barrier
	v_mfma_f32_16x16x32_bf16 v[126:129], v[130:133], v[196:199], v[126:129]
	v_mfma_f32_16x16x32_bf16 v[122:125], v[138:141], v[196:199], v[122:125]
	v_mfma_f32_16x16x32_bf16 v[110:113], v[130:133], v[204:207], v[110:113]
	v_mfma_f32_16x16x32_bf16 v[106:109], v[138:141], v[204:207], v[106:109]
	v_mfma_f32_16x16x32_bf16 v[94:97], v[130:133], v[212:215], v[94:97]
	v_mfma_f32_16x16x32_bf16 v[90:93], v[138:141], v[212:215], v[90:93]
	v_mfma_f32_16x16x32_bf16 v[78:81], v[130:133], v[220:223], v[78:81]
	v_mfma_f32_16x16x32_bf16 v[74:77], v[138:141], v[220:223], v[74:77]
	v_mfma_f32_16x16x32_bf16 v[126:129], v[134:137], v[200:203], v[126:129]
	v_mfma_f32_16x16x32_bf16 v[122:125], v[142:145], v[200:203], v[122:125]
	v_mfma_f32_16x16x32_bf16 v[110:113], v[134:137], v[208:211], v[110:113]
	v_mfma_f32_16x16x32_bf16 v[106:109], v[142:145], v[208:211], v[106:109]
	v_mfma_f32_16x16x32_bf16 v[94:97], v[134:137], v[216:219], v[94:97]
	v_mfma_f32_16x16x32_bf16 v[90:93], v[142:145], v[216:219], v[90:93]
	v_mfma_f32_16x16x32_bf16 v[78:81], v[134:137], v[224:227], v[78:81]
	v_mfma_f32_16x16x32_bf16 v[74:77], v[142:145], v[224:227], v[74:77]
	s_setprio 0
	s_setprio 1
	v_mfma_f32_16x16x32_bf16 v[118:121], v[168:171], v[196:199], v[118:121]
	v_mfma_f32_16x16x32_bf16 v[114:117], v[188:191], v[196:199], v[114:117]
	v_mfma_f32_16x16x32_bf16 v[102:105], v[168:171], v[204:207], v[102:105]
	v_mfma_f32_16x16x32_bf16 v[98:101], v[188:191], v[204:207], v[98:101]
	v_mfma_f32_16x16x32_bf16 v[86:89], v[168:171], v[212:215], v[86:89]
	v_mfma_f32_16x16x32_bf16 v[82:85], v[188:191], v[212:215], v[82:85]
	v_mfma_f32_16x16x32_bf16 v[70:73], v[168:171], v[220:223], v[70:73]
	v_mfma_f32_16x16x32_bf16 v[66:69], v[188:191], v[220:223], v[66:69]
	v_mfma_f32_16x16x32_bf16 v[118:121], v[184:187], v[200:203], v[118:121]
	v_mfma_f32_16x16x32_bf16 v[114:117], v[192:195], v[200:203], v[114:117]
	v_mfma_f32_16x16x32_bf16 v[102:105], v[184:187], v[208:211], v[102:105]
	v_mfma_f32_16x16x32_bf16 v[98:101], v[192:195], v[208:211], v[98:101]
	v_mfma_f32_16x16x32_bf16 v[86:89], v[184:187], v[216:219], v[86:89]
	v_mfma_f32_16x16x32_bf16 v[82:85], v[192:195], v[216:219], v[82:85]
	v_mfma_f32_16x16x32_bf16 v[70:73], v[184:187], v[224:227], v[70:73]
	v_mfma_f32_16x16x32_bf16 v[66:69], v[192:195], v[224:227], v[66:69]
	s_barrier
	s_setprio 0
	s_add_i32 s68, s39, s26
	v_lshl_add_u64 v[230:231], s[22:23], 0, v[150:151]
	s_mov_b32 m0, s68
	ds_read_b128 v[196:199], v178 offset:16384
	ds_read_b128 v[200:203], v178 offset:17408
	ds_read_b128 v[204:207], v178 offset:18432
	ds_read_b128 v[208:211], v178 offset:19456
	ds_read_b128 v[212:215], v178 offset:20480
	ds_read_b128 v[216:219], v178 offset:21504
	ds_read_b128 v[220:223], v178 offset:22528
	ds_read_b128 v[224:227], v178 offset:23552
	global_load_lds_dwordx4 v[230:231], off
	s_add_i32 m0, s68, 0x2000
	s_add_u32 s68, s22, 0x80000
	v_lshl_add_u64 v[232:233], s[22:23], 0, v[154:155]
	s_addc_u32 s69, s23, 0
	s_add_i32 s70, s40, s26
	global_load_lds_dwordx4 v[232:233], off
	v_lshl_add_u64 v[234:235], s[68:69], 0, v[150:151]
	s_mov_b32 m0, s70
	v_lshl_add_u64 v[236:237], s[24:25], 0, v[152:153]
	global_load_lds_dwordx4 v[234:235], off
	v_lshl_add_u64 v[234:235], s[68:69], 0, v[154:155]
	s_add_i32 m0, s70, 0x2000
	s_nop 0
	global_load_lds_dwordx4 v[234:235], off
	v_lshl_add_u64 v[234:235], s[24:25], 0, v[148:149]
	s_mov_b32 m0, s27
	s_nop 0
	global_load_lds_dwordx4 v[234:235], off
	s_mov_b32 m0, s28
	s_nop 0
	global_load_lds_dwordx4 v[236:237], off
	s_waitcnt vmcnt(8)
	s_waitcnt lgkmcnt(0)
	s_setprio 1
	s_barrier
; #define PG8_STAGE(bufoff, gbase, voff) do { _Pragma("unroll") for (int _i = 0; _i < 2; ++_i) \
;         __builtin_amdgcn_global_load_lds((const unsigned*)((const char*)(gbase) + (voff)[_i]), (PG8_LAS unsigned*)(lds + (bufoff) + ldsw + _i * 8192), 16, 0, 0); } while (0)
; #define PG8_WAIT_V(n) asm volatile("s_waitcnt vmcnt(" #n ")" ::: "memory")
; #define PG8_WAIT_L(n) asm volatile("s_waitcnt lgkmcnt(" #n ")" ::: "memory")
; #define PG8_BAR __builtin_amdgcn_s_barrier()
; #define PG8_SCHED __builtin_amdgcn_sched_barrier(0)
; template <class Epi, class Sched, bool ALIGN_EPI = true, bool SP2 = true>
; __device__ __forceinline__ void gemm_phase(PG8_LAS unsigned char* lds, const int K  , const Sched& S, const Epi& E) {
;     ...
;             PG8_WAIT_V(8); PG8_WAIT_L(0); PG8_BAR; PG8_MMA(1, 0, At, B0); PG8_MMA(1, 1, At, B1); PG8_BAR; PG8_SCHED;
;             PG8_LDB(B0, 1, 0); PG8_LDB(B1, 1, 1); PG8_SCHED; PG8_LDA(At, 1, 0); PG8_STAGE(PG8_SA(0, 1), a2 + hstep, voffA);
;             PG8_WAIT_V(8); PG8_WAIT_L(0); PG8_BAR; PG8_MMA(0, 0, At, B0); PG8_MMA(0, 1, At, B1); PG8_BAR; PG8_SCHED;
	v_mfma_f32_16x16x32_bf16 v[62:65], v[130:133], v[196:199], v[62:65]
	v_mfma_f32_16x16x32_bf16 v[58:61], v[138:141], v[196:199], v[58:61]
	v_mfma_f32_16x16x32_bf16 v[46:49], v[130:133], v[204:207], v[46:49]
	v_mfma_f32_16x16x32_bf16 v[42:45], v[138:141], v[204:207], v[42:45]
	v_mfma_f32_16x16x32_bf16 v[30:33], v[130:133], v[212:215], v[30:33]
	v_mfma_f32_16x16x32_bf16 v[26:29], v[138:141], v[212:215], v[26:29]
	v_mfma_f32_16x16x32_bf16 v[14:17], v[130:133], v[220:223], v[14:17]
	v_mfma_f32_16x16x32_bf16 v[10:13], v[138:141], v[220:223], v[10:13]
	v_mfma_f32_16x16x32_bf16 v[62:65], v[134:137], v[200:203], v[62:65]
	v_mfma_f32_16x16x32_bf16 v[58:61], v[142:145], v[200:203], v[58:61]
	v_mfma_f32_16x16x32_bf16 v[46:49], v[134:137], v[208:211], v[46:49]
	v_mfma_f32_16x16x32_bf16 v[42:45], v[142:145], v[208:211], v[42:45]
	v_mfma_f32_16x16x32_bf16 v[30:33], v[134:137], v[216:219], v[30:33]
	v_mfma_f32_16x16x32_bf16 v[26:29], v[142:145], v[216:219], v[26:29]
	v_mfma_f32_16x16x32_bf16 v[14:17], v[134:137], v[224:227], v[14:17]
	v_mfma_f32_16x16x32_bf16 v[10:13], v[142:145], v[224:227], v[10:13]
	s_setprio 0
	s_setprio 1
	v_mfma_f32_16x16x32_bf16 v[54:57], v[168:171], v[196:199], v[54:57]
	v_mfma_f32_16x16x32_bf16 v[50:53], v[188:191], v[196:199], v[50:53]
	v_mfma_f32_16x16x32_bf16 v[38:41], v[168:171], v[204:207], v[38:41]
	v_mfma_f32_16x16x32_bf16 v[34:37], v[188:191], v[204:207], v[34:37]
	v_mfma_f32_16x16x32_bf16 v[22:25], v[168:171], v[212:215], v[22:25]
	v_mfma_f32_16x16x32_bf16 v[18:21], v[188:191], v[212:215], v[18:21]
	v_mfma_f32_16x16x32_bf16 v[6:9], v[168:171], v[220:223], v[6:9]
	v_mfma_f32_16x16x32_bf16 v[2:5], v[188:191], v[220:223], v[2:5]
	v_mfma_f32_16x16x32_bf16 v[54:57], v[184:187], v[200:203], v[54:57]
	v_mfma_f32_16x16x32_bf16 v[50:53], v[192:195], v[200:203], v[50:53]
	v_mfma_f32_16x16x32_bf16 v[38:41], v[184:187], v[208:211], v[38:41]
	v_mfma_f32_16x16x32_bf16 v[34:37], v[192:195], v[208:211], v[34:37]
	v_mfma_f32_16x16x32_bf16 v[22:25], v[184:187], v[216:219], v[22:25]
	v_mfma_f32_16x16x32_bf16 v[18:21], v[192:195], v[216:219], v[18:21]
	v_mfma_f32_16x16x32_bf16 v[6:9], v[184:187], v[224:227], v[6:9]
	v_mfma_f32_16x16x32_bf16 v[2:5], v[192:195], v[224:227], v[2:5]
	s_barrier
	s_setprio 0
	s_add_i32 s68, 0, 0x18000
	s_add_i32 s69, 0, 0x1c000
	v_add_u32_e32 v142, s68, v172
	v_add_u32_e32 v192, s69, v172
	ds_read_b128 v[130:133], v142
	ds_read_b128 v[134:137], v142 offset:1024
	ds_read_b128 v[138:141], v142 offset:2048
	ds_read_b128 v[142:145], v142 offset:3072
	ds_read_b128 v[168:171], v192
	ds_read_b128 v[184:187], v192 offset:1024
	ds_read_b128 v[188:191], v192 offset:2048
	ds_read_b128 v[192:195], v192 offset:3072
	ds_read_b128 v[196:199], v178 offset:32768
	ds_read_b128 v[200:203], v178 offset:33792
	ds_read_b128 v[204:207], v178 offset:34816
	ds_read_b128 v[208:211], v178 offset:35840
	ds_read_b128 v[212:215], v178 offset:36864
	ds_read_b128 v[216:219], v178 offset:37888
	ds_read_b128 v[220:223], v178 offset:38912
	ds_read_b128 v[224:227], v178 offset:39936
	s_add_u32 s24, s24, 0x80000
	s_addc_u32 s25, s25, 0
	s_mov_b32 m0, s29
	v_lshl_add_u64 v[238:239], s[24:25], 0, v[148:149]
	global_load_lds_dwordx4 v[238:239], off
	v_lshl_add_u64 v[238:239], s[24:25], 0, v[152:153]
	s_mov_b32 m0, s30
	s_nop 0
	global_load_lds_dwordx4 v[238:239], off
	s_waitcnt vmcnt(8)
	s_waitcnt lgkmcnt(0)
	s_setprio 1
	s_barrier
	v_mfma_f32_16x16x32_bf16 v[126:129], v[130:133], v[196:199], v[126:129]
	v_mfma_f32_16x16x32_bf16 v[122:125], v[138:141], v[196:199], v[122:125]
	v_mfma_f32_16x16x32_bf16 v[110:113], v[130:133], v[204:207], v[110:113]
	v_mfma_f32_16x16x32_bf16 v[106:109], v[138:141], v[204:207], v[106:109]
	v_mfma_f32_16x16x32_bf16 v[94:97], v[130:133], v[212:215], v[94:97]
	v_mfma_f32_16x16x32_bf16 v[90:93], v[138:141], v[212:215], v[90:93]
	v_mfma_f32_16x16x32_bf16 v[78:81], v[130:133], v[220:223], v[78:81]
	v_mfma_f32_16x16x32_bf16 v[74:77], v[138:141], v[220:223], v[74:77]
	v_mfma_f32_16x16x32_bf16 v[126:129], v[134:137], v[200:203], v[126:129]
	v_mfma_f32_16x16x32_bf16 v[122:125], v[142:145], v[200:203], v[122:125]
	v_mfma_f32_16x16x32_bf16 v[110:113], v[134:137], v[208:211], v[110:113]
	v_mfma_f32_16x16x32_bf16 v[106:109], v[142:145], v[208:211], v[106:109]
	v_mfma_f32_16x16x32_bf16 v[94:97], v[134:137], v[216:219], v[94:97]
	v_mfma_f32_16x16x32_bf16 v[90:93], v[142:145], v[216:219], v[90:93]
	v_mfma_f32_16x16x32_bf16 v[78:81], v[134:137], v[224:227], v[78:81]
	v_mfma_f32_16x16x32_bf16 v[74:77], v[142:145], v[224:227], v[74:77]
	s_setprio 0
	s_setprio 1
	v_mfma_f32_16x16x32_bf16 v[118:121], v[168:171], v[196:199], v[118:121]
	v_mfma_f32_16x16x32_bf16 v[114:117], v[188:191], v[196:199], v[114:117]
	v_mfma_f32_16x16x32_bf16 v[102:105], v[168:171], v[204:207], v[102:105]
	v_mfma_f32_16x16x32_bf16 v[98:101], v[188:191], v[204:207], v[98:101]
	v_mfma_f32_16x16x32_bf16 v[86:89], v[168:171], v[212:215], v[86:89]
	v_mfma_f32_16x16x32_bf16 v[82:85], v[188:191], v[212:215], v[82:85]
	v_mfma_f32_16x16x32_bf16 v[70:73], v[168:171], v[220:223], v[70:73]
	v_mfma_f32_16x16x32_bf16 v[66:69], v[188:191], v[220:223], v[66:69]
	v_mfma_f32_16x16x32_bf16 v[118:121], v[184:187], v[200:203], v[118:121]
	v_mfma_f32_16x16x32_bf16 v[114:117], v[192:195], v[200:203], v[114:117]
	v_mfma_f32_16x16x32_bf16 v[102:105], v[184:187], v[208:211], v[102:105]
	v_mfma_f32_16x16x32_bf16 v[98:101], v[192:195], v[208:211], v[98:101]
	v_mfma_f32_16x16x32_bf16 v[86:89], v[184:187], v[216:219], v[86:89]
	v_mfma_f32_16x16x32_bf16 v[82:85], v[192:195], v[216:219], v[82:85]
	v_mfma_f32_16x16x32_bf16 v[70:73], v[184:187], v[224:227], v[70:73]
	v_mfma_f32_16x16x32_bf16 v[66:69], v[192:195], v[224:227], v[66:69]
	s_barrier
; #define PG8_STAGE(bufoff, gbase, voff) do { _Pragma("unroll") for (int _i = 0; _i < 2; ++_i) \
;         __builtin_amdgcn_global_load_lds((const unsigned*)((const char*)(gbase) + (voff)[_i]), (PG8_LAS unsigned*)(lds + (bufoff) + ldsw + _i * 8192), 16, 0, 0); } while (0)
; #define PG8_WAIT_V(n) asm volatile("s_waitcnt vmcnt(" #n ")" ::: "memory")
; #define PG8_WAIT_L(n) asm volatile("s_waitcnt lgkmcnt(" #n ")" ::: "memory")
; #define PG8_BAR __builtin_amdgcn_s_barrier()
; #define PG8_SCHED __builtin_amdgcn_sched_barrier(0)
; template <class Epi, class Sched, bool ALIGN_EPI = true, bool SP2 = true>
; __device__ __forceinline__ void gemm_phase(PG8_LAS unsigned char* lds, const int K  , const Sched& S, const Epi& E) {
;     ...
;             PG8_LDA(At, 1, 1); PG8_STAGE(PG8_SB(1, 0), b3, voffB); PG8_STAGE(PG8_SB(1, 1), b3 + hstep, voffB); PG8_STAGE(PG8_SA(1, 0), a3, voffA);
;             PG8_WAIT_V(8); PG8_WAIT_L(0); PG8_BAR; PG8_MMA(1, 0, At, B0); PG8_MMA(1, 1, At, B1); PG8_BAR; PG8_SCHED;
	s_setprio 0
	s_add_i32 s24, s68, s26
	v_lshl_add_u64 v[230:231], v[230:231], 0, s[4:5]
	s_mov_b32 m0, s24
	ds_read_b128 v[196:199], v178 offset:49152
	ds_read_b128 v[200:203], v178 offset:50176
	ds_read_b128 v[204:207], v178 offset:51200
	ds_read_b128 v[208:211], v178 offset:52224
	ds_read_b128 v[212:215], v178 offset:53248
	ds_read_b128 v[216:219], v178 offset:54272
	ds_read_b128 v[220:223], v178 offset:55296
	ds_read_b128 v[224:227], v178 offset:56320
	global_load_lds_dwordx4 v[230:231], off
	s_add_i32 m0, s24, 0x2000
	s_add_u32 s22, s22, 0x80080
	v_lshl_add_u64 v[230:231], v[232:233], 0, s[4:5]
	s_addc_u32 s23, s23, 0
	s_add_i32 s24, s69, s26
	global_load_lds_dwordx4 v[230:231], off
	v_lshl_add_u64 v[230:231], s[22:23], 0, v[150:151]
	s_mov_b32 m0, s24
	s_nop 0
	global_load_lds_dwordx4 v[230:231], off
	v_lshl_add_u64 v[230:231], s[22:23], 0, v[154:155]
	s_add_i32 m0, s24, 0x2000
	s_nop 0
	global_load_lds_dwordx4 v[230:231], off
	v_lshl_add_u64 v[230:231], v[234:235], 0, s[4:5]
	s_mov_b32 m0, s35
	s_nop 0
	global_load_lds_dwordx4 v[230:231], off
	v_lshl_add_u64 v[230:231], v[236:237], 0, s[4:5]
	s_mov_b32 m0, s36
	s_nop 0
	global_load_lds_dwordx4 v[230:231], off
	s_waitcnt vmcnt(8)
	s_waitcnt lgkmcnt(0)
	s_setprio 1
	s_barrier
	v_mfma_f32_16x16x32_bf16 v[62:65], v[130:133], v[196:199], v[62:65]
	v_mfma_f32_16x16x32_bf16 v[58:61], v[138:141], v[196:199], v[58:61]
	v_mfma_f32_16x16x32_bf16 v[46:49], v[130:133], v[204:207], v[46:49]
	v_mfma_f32_16x16x32_bf16 v[42:45], v[138:141], v[204:207], v[42:45]
	v_mfma_f32_16x16x32_bf16 v[30:33], v[130:133], v[212:215], v[30:33]
	v_mfma_f32_16x16x32_bf16 v[26:29], v[138:141], v[212:215], v[26:29]
	v_mfma_f32_16x16x32_bf16 v[14:17], v[130:133], v[220:223], v[14:17]
	v_mfma_f32_16x16x32_bf16 v[10:13], v[138:141], v[220:223], v[10:13]
	v_mfma_f32_16x16x32_bf16 v[62:65], v[134:137], v[200:203], v[62:65]
	v_mfma_f32_16x16x32_bf16 v[58:61], v[142:145], v[200:203], v[58:61]
	v_mfma_f32_16x16x32_bf16 v[46:49], v[134:137], v[208:211], v[46:49]
	v_mfma_f32_16x16x32_bf16 v[42:45], v[142:145], v[208:211], v[42:45]
	v_mfma_f32_16x16x32_bf16 v[30:33], v[134:137], v[216:219], v[30:33]
	v_mfma_f32_16x16x32_bf16 v[26:29], v[142:145], v[216:219], v[26:29]
	v_mfma_f32_16x16x32_bf16 v[14:17], v[134:137], v[224:227], v[14:17]
	v_mfma_f32_16x16x32_bf16 v[10:13], v[142:145], v[224:227], v[10:13]
	s_setprio 0
	s_setprio 1
	v_mfma_f32_16x16x32_bf16 v[54:57], v[168:171], v[196:199], v[54:57]
	v_mfma_f32_16x16x32_bf16 v[50:53], v[188:191], v[196:199], v[50:53]
	v_mfma_f32_16x16x32_bf16 v[38:41], v[168:171], v[204:207], v[38:41]
	v_mfma_f32_16x16x32_bf16 v[34:37], v[188:191], v[204:207], v[34:37]
	v_mfma_f32_16x16x32_bf16 v[22:25], v[168:171], v[212:215], v[22:25]
	v_mfma_f32_16x16x32_bf16 v[18:21], v[188:191], v[212:215], v[18:21]
	v_mfma_f32_16x16x32_bf16 v[6:9], v[168:171], v[220:223], v[6:9]
	v_mfma_f32_16x16x32_bf16 v[2:5], v[188:191], v[220:223], v[2:5]
	v_mfma_f32_16x16x32_bf16 v[54:57], v[184:187], v[200:203], v[54:57]
	v_mfma_f32_16x16x32_bf16 v[50:53], v[192:195], v[200:203], v[50:53]
	v_mfma_f32_16x16x32_bf16 v[38:41], v[184:187], v[208:211], v[38:41]
	v_mfma_f32_16x16x32_bf16 v[34:37], v[192:195], v[208:211], v[34:37]
	v_mfma_f32_16x16x32_bf16 v[22:25], v[184:187], v[216:219], v[22:25]
	v_mfma_f32_16x16x32_bf16 v[18:21], v[192:195], v[216:219], v[18:21]
	v_mfma_f32_16x16x32_bf16 v[6:9], v[184:187], v[224:227], v[6:9]
	v_mfma_f32_16x16x32_bf16 v[2:5], v[192:195], v[224:227], v[2:5]
	s_barrier
	s_setprio 0
	s_add_i32 s51, s51, 2
	s_add_u32 s0, s0, 0x100
	s_addc_u32 s1, s1, 0
	s_add_u32 s49, s49, 0x100
	s_addc_u32 s50, s50, 0
	s_cmp_gt_u32 s51, 29
	s_cbranch_scc0 .LBB0_1847
	s_and_b64 vcc, exec, s[8:9]
	s_cbranch_vccz .LBB0_1850
	s_barrier

; #define PG8_STAGE(bufoff, gbase, voff) do { _Pragma("unroll") for (int _i = 0; _i < 2; ++_i) \
;         __builtin_amdgcn_global_load_lds((const unsigned*)((const char*)(gbase) + (voff)[_i]), (PG8_LAS unsigned*)(lds + (bufoff) + ldsw + _i * 8192), 16, 0, 0); } while (0)
; #define PG8_WAIT_V(n) asm volatile("s_waitcnt vmcnt(" #n ")" ::: "memory")
; #define PG8_WAIT_L(n) asm volatile("s_waitcnt lgkmcnt(" #n ")" ::: "memory")
; #define PG8_BAR __builtin_amdgcn_s_barrier()
; #define PG8_SCHED __builtin_amdgcn_sched_barrier(0)
; template <class Epi, class Sched, bool ALIGN_EPI = true, bool SP2 = true>
; __device__ __forceinline__ void gemm_phase(PG8_LAS unsigned char* lds, const int K  , const Sched& S, const Epi& E) {
;     ...
;             const char* a1 = cA + (size_t)(t + 1) * kstep;
;             const char* a2 = last ? nA : cA + (size_t)(t + 2) * kstep; const char* b2 = last ? nB : cB + (size_t)(t + 2) * kstep;
;             const char* a3 = a2 + kstep; const char* b3 = b2 + kstep;
;             if constexpr (SP2) {
;             PG8_LDB(B0, 0, 0); PG8_LDB(B1, 0, 1); PG8_SCHED; PG8_LDA(At, 0, 0); PG8_STAGE(PG8_SA(1, 1), a1 + hstep, voffA);
;             PG8_WAIT_V(8); PG8_WAIT_L(0); PG8_BAR; PG8_MMA(0, 0, At, B0); PG8_MMA(0, 1, At, B1); PG8_BAR; PG8_SCHED;
;             PG8_LDA(At, 0, 1); PG8_STAGE(PG8_SB(0, 0), b2, voffB); PG8_STAGE(PG8_SB(0, 1), b2 + hstep, voffB); PG8_STAGE(PG8_SA(0, 0), a2, voffA);
;             PG8_WAIT_V(8); PG8_WAIT_L(0); PG8_BAR; PG8_MMA(1, 0, At, B0); PG8_MMA(1, 1, At, B1); PG8_BAR; PG8_SCHED;
.LBB0_2296:
	ds_read_b128 v[130:133], v203
	ds_read_b128 v[134:137], v203 offset:1024
	ds_read_b128 v[138:141], v203 offset:2048
	ds_read_b128 v[142:145], v203 offset:3072
	ds_read_b128 v[146:149], v204
	ds_read_b128 v[150:153], v204 offset:1024
	ds_read_b128 v[154:157], v204 offset:2048
	ds_read_b128 v[158:161], v204 offset:3072
	ds_read_b128 v[162:165], v205
	ds_read_b128 v[166:169], v205 offset:1024
	ds_read_b128 v[170:173], v205 offset:2048
	ds_read_b128 v[174:177], v205 offset:3072
	ds_read_b128 v[178:181], v205 offset:4096
	ds_read_b128 v[206:209], v205 offset:5120
	ds_read_b128 v[210:213], v205 offset:6144
	ds_read_b128 v[214:217], v205 offset:7168
	s_add_u32 s22, s20, 0xfff80080
	s_addc_u32 s23, s21, -1
	s_cmp_eq_u32 s54, 28
	s_cselect_b32 s25, s13, s23
	s_cselect_b32 s24, s50, s22
	s_cselect_b32 s23, s11, s53
	s_cselect_b32 s22, s51, s52
	s_add_i32 m0, s19, 0xc000
	v_lshl_add_u64 v[198:199], s[20:21], 0, v[190:191]
	global_load_lds_dwordx4 v[198:199], off
	v_lshl_add_u64 v[198:199], s[20:21], 0, v[192:193]
	s_add_i32 m0, s19, 0xe000
	s_nop 0
	global_load_lds_dwordx4 v[198:199], off
	s_waitcnt vmcnt(8)
	s_waitcnt lgkmcnt(0)
	s_setprio 1
	s_barrier
	v_mfma_f32_16x16x32_bf16 v[126:129], v[130:133], v[162:165], v[126:129]
	v_mfma_f32_16x16x32_bf16 v[122:125], v[138:141], v[162:165], v[122:125]
	v_mfma_f32_16x16x32_bf16 v[114:117], v[130:133], v[170:173], v[114:117]
	v_mfma_f32_16x16x32_bf16 v[106:109], v[138:141], v[170:173], v[106:109]
	v_mfma_f32_16x16x32_bf16 v[98:101], v[130:133], v[178:181], v[98:101]
	v_mfma_f32_16x16x32_bf16 v[90:93], v[138:141], v[178:181], v[90:93]
	v_mfma_f32_16x16x32_bf16 v[82:85], v[130:133], v[210:213], v[82:85]
	v_mfma_f32_16x16x32_bf16 v[74:77], v[138:141], v[210:213], v[74:77]
	v_mfma_f32_16x16x32_bf16 v[126:129], v[134:137], v[166:169], v[126:129]
	v_mfma_f32_16x16x32_bf16 v[122:125], v[142:145], v[166:169], v[122:125]
	v_mfma_f32_16x16x32_bf16 v[114:117], v[134:137], v[174:177], v[114:117]
	v_mfma_f32_16x16x32_bf16 v[106:109], v[142:145], v[174:177], v[106:109]
	v_mfma_f32_16x16x32_bf16 v[98:101], v[134:137], v[206:209], v[98:101]
	v_mfma_f32_16x16x32_bf16 v[90:93], v[142:145], v[206:209], v[90:93]
	v_mfma_f32_16x16x32_bf16 v[82:85], v[134:137], v[214:217], v[82:85]
	v_mfma_f32_16x16x32_bf16 v[74:77], v[142:145], v[214:217], v[74:77]
	s_setprio 0
	s_setprio 1
	v_mfma_f32_16x16x32_bf16 v[118:121], v[146:149], v[162:165], v[118:121]
	v_mfma_f32_16x16x32_bf16 v[110:113], v[154:157], v[162:165], v[110:113]
	v_mfma_f32_16x16x32_bf16 v[102:105], v[146:149], v[170:173], v[102:105]
	v_mfma_f32_16x16x32_bf16 v[94:97], v[154:157], v[170:173], v[94:97]
	v_mfma_f32_16x16x32_bf16 v[86:89], v[146:149], v[178:181], v[86:89]
	v_mfma_f32_16x16x32_bf16 v[78:81], v[154:157], v[178:181], v[78:81]
	v_mfma_f32_16x16x32_bf16 v[70:73], v[146:149], v[210:213], v[70:73]
	v_mfma_f32_16x16x32_bf16 v[66:69], v[154:157], v[210:213], v[66:69]
	v_mfma_f32_16x16x32_bf16 v[118:121], v[150:153], v[166:169], v[118:121]
	v_mfma_f32_16x16x32_bf16 v[110:113], v[158:161], v[166:169], v[110:113]
	v_mfma_f32_16x16x32_bf16 v[102:105], v[150:153], v[174:177], v[102:105]
	v_mfma_f32_16x16x32_bf16 v[94:97], v[158:161], v[174:177], v[94:97]
	v_mfma_f32_16x16x32_bf16 v[86:89], v[150:153], v[206:209], v[86:89]
	v_mfma_f32_16x16x32_bf16 v[78:81], v[158:161], v[206:209], v[78:81]
	v_mfma_f32_16x16x32_bf16 v[70:73], v[150:153], v[214:217], v[70:73]
	v_mfma_f32_16x16x32_bf16 v[66:69], v[158:161], v[214:217], v[66:69]
	s_barrier
	s_setprio 0
	s_add_i32 s55, s42, s29
	v_lshl_add_u64 v[198:199], s[22:23], 0, v[184:185]
	s_mov_b32 m0, s55
	ds_read_b128 v[162:165], v205 offset:16384
	ds_read_b128 v[166:169], v205 offset:17408
	ds_read_b128 v[170:173], v205 offset:18432
	ds_read_b128 v[174:177], v205 offset:19456
	ds_read_b128 v[178:181], v205 offset:20480
	ds_read_b128 v[206:209], v205 offset:21504
	ds_read_b128 v[210:213], v205 offset:22528
	ds_read_b128 v[214:217], v205 offset:23552
	global_load_lds_dwordx4 v[198:199], off
	s_add_i32 m0, s55, 0x2000
	s_add_u32 s56, s22, 0x80000
	v_lshl_add_u64 v[218:219], s[22:23], 0, v[188:189]
	s_addc_u32 s57, s23, 0
	s_add_i32 s55, s43, s29
	global_load_lds_dwordx4 v[218:219], off
	v_lshl_add_u64 v[220:221], s[56:57], 0, v[184:185]
	s_mov_b32 m0, s55
	v_lshl_add_u64 v[222:223], s[24:25], 0, v[186:187]
	global_load_lds_dwordx4 v[220:221], off
	v_lshl_add_u64 v[220:221], s[56:57], 0, v[188:189]
	s_add_i32 m0, s55, 0x2000
	s_nop 0
	global_load_lds_dwordx4 v[220:221], off
	v_lshl_add_u64 v[220:221], s[24:25], 0, v[182:183]
	s_mov_b32 m0, s19
	s_nop 0
	global_load_lds_dwordx4 v[220:221], off
	s_mov_b32 m0, s30
	s_nop 0
	global_load_lds_dwordx4 v[222:223], off
	s_waitcnt vmcnt(8)
	s_waitcnt lgkmcnt(0)
	s_setprio 1
	s_barrier
; #define PG8_STAGE(bufoff, gbase, voff) do { _Pragma("unroll") for (int _i = 0; _i < 2; ++_i) \
;         __builtin_amdgcn_global_load_lds((const unsigned*)((const char*)(gbase) + (voff)[_i]), (PG8_LAS unsigned*)(lds + (bufoff) + ldsw + _i * 8192), 16, 0, 0); } while (0)
; #define PG8_WAIT_V(n) asm volatile("s_waitcnt vmcnt(" #n ")" ::: "memory")
; #define PG8_WAIT_L(n) asm volatile("s_waitcnt lgkmcnt(" #n ")" ::: "memory")
; #define PG8_BAR __builtin_amdgcn_s_barrier()
; #define PG8_SCHED __builtin_amdgcn_sched_barrier(0)
; template <class Epi, class Sched, bool ALIGN_EPI = true, bool SP2 = true>
; __device__ __forceinline__ void gemm_phase(PG8_LAS unsigned char* lds, const int K  , const Sched& S, const Epi& E) {
;     ...
;             PG8_WAIT_V(8); PG8_WAIT_L(0); PG8_BAR; PG8_MMA(1, 0, At, B0); PG8_MMA(1, 1, At, B1); PG8_BAR; PG8_SCHED;
;             PG8_LDB(B0, 1, 0); PG8_LDB(B1, 1, 1); PG8_SCHED; PG8_LDA(At, 1, 0); PG8_STAGE(PG8_SA(0, 1), a2 + hstep, voffA);
;             PG8_WAIT_V(8); PG8_WAIT_L(0); PG8_BAR; PG8_MMA(0, 0, At, B0); PG8_MMA(0, 1, At, B1); PG8_BAR; PG8_SCHED;
	v_mfma_f32_16x16x32_bf16 v[62:65], v[130:133], v[162:165], v[62:65]
	v_mfma_f32_16x16x32_bf16 v[58:61], v[138:141], v[162:165], v[58:61]
	v_mfma_f32_16x16x32_bf16 v[50:53], v[130:133], v[170:173], v[50:53]
	v_mfma_f32_16x16x32_bf16 v[42:45], v[138:141], v[170:173], v[42:45]
	v_mfma_f32_16x16x32_bf16 v[34:37], v[130:133], v[178:181], v[34:37]
	v_mfma_f32_16x16x32_bf16 v[26:29], v[138:141], v[178:181], v[26:29]
	v_mfma_f32_16x16x32_bf16 v[18:21], v[130:133], v[210:213], v[18:21]
	v_mfma_f32_16x16x32_bf16 v[10:13], v[138:141], v[210:213], v[10:13]
	v_mfma_f32_16x16x32_bf16 v[62:65], v[134:137], v[166:169], v[62:65]
	v_mfma_f32_16x16x32_bf16 v[58:61], v[142:145], v[166:169], v[58:61]
	v_mfma_f32_16x16x32_bf16 v[50:53], v[134:137], v[174:177], v[50:53]
	v_mfma_f32_16x16x32_bf16 v[42:45], v[142:145], v[174:177], v[42:45]
	v_mfma_f32_16x16x32_bf16 v[34:37], v[134:137], v[206:209], v[34:37]
	v_mfma_f32_16x16x32_bf16 v[26:29], v[142:145], v[206:209], v[26:29]
	v_mfma_f32_16x16x32_bf16 v[18:21], v[134:137], v[214:217], v[18:21]
	v_mfma_f32_16x16x32_bf16 v[10:13], v[142:145], v[214:217], v[10:13]
	s_setprio 0
	s_setprio 1
	v_mfma_f32_16x16x32_bf16 v[54:57], v[146:149], v[162:165], v[54:57]
	v_mfma_f32_16x16x32_bf16 v[46:49], v[154:157], v[162:165], v[46:49]
	v_mfma_f32_16x16x32_bf16 v[38:41], v[146:149], v[170:173], v[38:41]
	v_mfma_f32_16x16x32_bf16 v[30:33], v[154:157], v[170:173], v[30:33]
	v_mfma_f32_16x16x32_bf16 v[22:25], v[146:149], v[178:181], v[22:25]
	v_mfma_f32_16x16x32_bf16 v[14:17], v[154:157], v[178:181], v[14:17]
	v_mfma_f32_16x16x32_bf16 v[6:9], v[146:149], v[210:213], v[6:9]
	v_mfma_f32_16x16x32_bf16 v[2:5], v[154:157], v[210:213], v[2:5]
	v_mfma_f32_16x16x32_bf16 v[54:57], v[150:153], v[166:169], v[54:57]
	v_mfma_f32_16x16x32_bf16 v[46:49], v[158:161], v[166:169], v[46:49]
	v_mfma_f32_16x16x32_bf16 v[38:41], v[150:153], v[174:177], v[38:41]
	v_mfma_f32_16x16x32_bf16 v[30:33], v[158:161], v[174:177], v[30:33]
	v_mfma_f32_16x16x32_bf16 v[22:25], v[150:153], v[206:209], v[22:25]
	v_mfma_f32_16x16x32_bf16 v[14:17], v[158:161], v[206:209], v[14:17]
	v_mfma_f32_16x16x32_bf16 v[6:9], v[150:153], v[214:217], v[6:9]
	v_mfma_f32_16x16x32_bf16 v[2:5], v[158:161], v[214:217], v[2:5]
	s_barrier
	s_setprio 0
	s_add_i32 s55, 0, 0x18000
	s_add_i32 s56, 0, 0x1c000
	v_add_u32_e32 v142, s55, v201
	v_add_u32_e32 v158, s56, v201
	ds_read_b128 v[130:133], v142
	ds_read_b128 v[134:137], v142 offset:1024
	ds_read_b128 v[138:141], v142 offset:2048
	ds_read_b128 v[142:145], v142 offset:3072
	ds_read_b128 v[146:149], v158
	ds_read_b128 v[150:153], v158 offset:1024
	ds_read_b128 v[154:157], v158 offset:2048
	ds_read_b128 v[158:161], v158 offset:3072
	ds_read_b128 v[162:165], v205 offset:32768
	ds_read_b128 v[166:169], v205 offset:33792
	ds_read_b128 v[170:173], v205 offset:34816
	ds_read_b128 v[174:177], v205 offset:35840
	ds_read_b128 v[178:181], v205 offset:36864
	ds_read_b128 v[206:209], v205 offset:37888
	ds_read_b128 v[210:213], v205 offset:38912
	ds_read_b128 v[214:217], v205 offset:39936
	s_add_u32 s24, s24, 0x80000
	s_addc_u32 s25, s25, 0
	s_mov_b32 m0, s31
	v_lshl_add_u64 v[224:225], s[24:25], 0, v[182:183]
	global_load_lds_dwordx4 v[224:225], off
	v_lshl_add_u64 v[224:225], s[24:25], 0, v[186:187]
	s_mov_b32 m0, s33
	s_nop 0
	global_load_lds_dwordx4 v[224:225], off
	s_waitcnt vmcnt(8)
	s_waitcnt lgkmcnt(0)
	s_setprio 1
	s_barrier
	v_mfma_f32_16x16x32_bf16 v[126:129], v[130:133], v[162:165], v[126:129]
	v_mfma_f32_16x16x32_bf16 v[122:125], v[138:141], v[162:165], v[122:125]
	v_mfma_f32_16x16x32_bf16 v[114:117], v[130:133], v[170:173], v[114:117]
	v_mfma_f32_16x16x32_bf16 v[106:109], v[138:141], v[170:173], v[106:109]
	v_mfma_f32_16x16x32_bf16 v[98:101], v[130:133], v[178:181], v[98:101]
	v_mfma_f32_16x16x32_bf16 v[90:93], v[138:141], v[178:181], v[90:93]
	v_mfma_f32_16x16x32_bf16 v[82:85], v[130:133], v[210:213], v[82:85]
	v_mfma_f32_16x16x32_bf16 v[74:77], v[138:141], v[210:213], v[74:77]
	v_mfma_f32_16x16x32_bf16 v[126:129], v[134:137], v[166:169], v[126:129]
	v_mfma_f32_16x16x32_bf16 v[122:125], v[142:145], v[166:169], v[122:125]
	v_mfma_f32_16x16x32_bf16 v[114:117], v[134:137], v[174:177], v[114:117]
	v_mfma_f32_16x16x32_bf16 v[106:109], v[142:145], v[174:177], v[106:109]
	v_mfma_f32_16x16x32_bf16 v[98:101], v[134:137], v[206:209], v[98:101]
	v_mfma_f32_16x16x32_bf16 v[90:93], v[142:145], v[206:209], v[90:93]
	v_mfma_f32_16x16x32_bf16 v[82:85], v[134:137], v[214:217], v[82:85]
	v_mfma_f32_16x16x32_bf16 v[74:77], v[142:145], v[214:217], v[74:77]
	s_setprio 0
	s_setprio 1
	v_mfma_f32_16x16x32_bf16 v[118:121], v[146:149], v[162:165], v[118:121]
	v_mfma_f32_16x16x32_bf16 v[110:113], v[154:157], v[162:165], v[110:113]
	v_mfma_f32_16x16x32_bf16 v[102:105], v[146:149], v[170:173], v[102:105]
	v_mfma_f32_16x16x32_bf16 v[94:97], v[154:157], v[170:173], v[94:97]
	v_mfma_f32_16x16x32_bf16 v[86:89], v[146:149], v[178:181], v[86:89]
	v_mfma_f32_16x16x32_bf16 v[78:81], v[154:157], v[178:181], v[78:81]
	v_mfma_f32_16x16x32_bf16 v[70:73], v[146:149], v[210:213], v[70:73]
	v_mfma_f32_16x16x32_bf16 v[66:69], v[154:157], v[210:213], v[66:69]
	v_mfma_f32_16x16x32_bf16 v[118:121], v[150:153], v[166:169], v[118:121]
	v_mfma_f32_16x16x32_bf16 v[110:113], v[158:161], v[166:169], v[110:113]
	v_mfma_f32_16x16x32_bf16 v[102:105], v[150:153], v[174:177], v[102:105]
	v_mfma_f32_16x16x32_bf16 v[94:97], v[158:161], v[174:177], v[94:97]
	v_mfma_f32_16x16x32_bf16 v[86:89], v[150:153], v[206:209], v[86:89]
	v_mfma_f32_16x16x32_bf16 v[78:81], v[158:161], v[206:209], v[78:81]
	v_mfma_f32_16x16x32_bf16 v[70:73], v[150:153], v[214:217], v[70:73]
	v_mfma_f32_16x16x32_bf16 v[66:69], v[158:161], v[214:217], v[66:69]
	s_barrier
; #define PG8_STAGE(bufoff, gbase, voff) do { _Pragma("unroll") for (int _i = 0; _i < 2; ++_i) \
;         __builtin_amdgcn_global_load_lds((const unsigned*)((const char*)(gbase) + (voff)[_i]), (PG8_LAS unsigned*)(lds + (bufoff) + ldsw + _i * 8192), 16, 0, 0); } while (0)
; #define PG8_WAIT_V(n) asm volatile("s_waitcnt vmcnt(" #n ")" ::: "memory")
; #define PG8_WAIT_L(n) asm volatile("s_waitcnt lgkmcnt(" #n ")" ::: "memory")
; #define PG8_BAR __builtin_amdgcn_s_barrier()
; #define PG8_SCHED __builtin_amdgcn_sched_barrier(0)
;     __device__ __forceinline__ int nt(const pg8::Unit& u) const { return u.kind == 0 ? ntiles : q_nt(u.kind - 1); }
; template <class Epi, class Sched, bool ALIGN_EPI = true, bool SP2 = true>
; __device__ __forceinline__ void gemm_phase(PG8_LAS unsigned char* lds, const int K  , const Sched& S, const Epi& E) {
;     ...
;         for (int t = 0; t < nt; t += 2) {
;             const bool last = (t == nt - 2);
;             const char* a1 = cA + (size_t)(t + 1) * kstep;
;             const char* a2 = last ? nA : cA + (size_t)(t + 2) * kstep; const char* b2 = last ? nB : cB + (size_t)(t + 2) * kstep;
;     ...
;             PG8_LDA(At, 1, 1); PG8_STAGE(PG8_SB(1, 0), b3, voffB); PG8_STAGE(PG8_SB(1, 1), b3 + hstep, voffB); PG8_STAGE(PG8_SA(1, 0), a3, voffA);
;             PG8_WAIT_V(8); PG8_WAIT_L(0); PG8_BAR; PG8_MMA(1, 0, At, B0); PG8_MMA(1, 1, At, B1); PG8_BAR; PG8_SCHED;
	s_setprio 0
	s_add_i32 s24, s55, s29
	v_lshl_add_u64 v[198:199], v[198:199], 0, s[6:7]
	s_mov_b32 m0, s24
	ds_read_b128 v[162:165], v205 offset:49152
	ds_read_b128 v[166:169], v205 offset:50176
	ds_read_b128 v[170:173], v205 offset:51200
	ds_read_b128 v[174:177], v205 offset:52224
	ds_read_b128 v[178:181], v205 offset:53248
	ds_read_b128 v[206:209], v205 offset:54272
	ds_read_b128 v[210:213], v205 offset:55296
	ds_read_b128 v[214:217], v205 offset:56320
	global_load_lds_dwordx4 v[198:199], off
	s_add_i32 m0, s24, 0x2000
	s_add_u32 s22, s22, 0x80080
	v_lshl_add_u64 v[198:199], v[218:219], 0, s[6:7]
	s_addc_u32 s23, s23, 0
	s_add_i32 s24, s56, s29
	global_load_lds_dwordx4 v[198:199], off
	v_lshl_add_u64 v[198:199], s[22:23], 0, v[184:185]
	s_mov_b32 m0, s24
	s_nop 0
	global_load_lds_dwordx4 v[198:199], off
	v_lshl_add_u64 v[198:199], s[22:23], 0, v[188:189]
	s_add_i32 m0, s24, 0x2000
	s_nop 0
	global_load_lds_dwordx4 v[198:199], off
	v_lshl_add_u64 v[198:199], v[220:221], 0, s[6:7]
	s_mov_b32 m0, s38
	s_nop 0
	global_load_lds_dwordx4 v[198:199], off
	v_lshl_add_u64 v[198:199], v[222:223], 0, s[6:7]
	s_mov_b32 m0, s39
	s_nop 0
	global_load_lds_dwordx4 v[198:199], off
	s_waitcnt vmcnt(8)
	s_waitcnt lgkmcnt(0)
	s_setprio 1
	s_barrier
	v_mfma_f32_16x16x32_bf16 v[62:65], v[130:133], v[162:165], v[62:65]
	v_mfma_f32_16x16x32_bf16 v[58:61], v[138:141], v[162:165], v[58:61]
	v_mfma_f32_16x16x32_bf16 v[50:53], v[130:133], v[170:173], v[50:53]
	v_mfma_f32_16x16x32_bf16 v[42:45], v[138:141], v[170:173], v[42:45]
	v_mfma_f32_16x16x32_bf16 v[34:37], v[130:133], v[178:181], v[34:37]
	v_mfma_f32_16x16x32_bf16 v[26:29], v[138:141], v[178:181], v[26:29]
	v_mfma_f32_16x16x32_bf16 v[18:21], v[130:133], v[210:213], v[18:21]
	v_mfma_f32_16x16x32_bf16 v[10:13], v[138:141], v[210:213], v[10:13]
	v_mfma_f32_16x16x32_bf16 v[62:65], v[134:137], v[166:169], v[62:65]
	v_mfma_f32_16x16x32_bf16 v[58:61], v[142:145], v[166:169], v[58:61]
	v_mfma_f32_16x16x32_bf16 v[50:53], v[134:137], v[174:177], v[50:53]
	v_mfma_f32_16x16x32_bf16 v[42:45], v[142:145], v[174:177], v[42:45]
	v_mfma_f32_16x16x32_bf16 v[34:37], v[134:137], v[206:209], v[34:37]
	v_mfma_f32_16x16x32_bf16 v[26:29], v[142:145], v[206:209], v[26:29]
	v_mfma_f32_16x16x32_bf16 v[18:21], v[134:137], v[214:217], v[18:21]
	v_mfma_f32_16x16x32_bf16 v[10:13], v[142:145], v[214:217], v[10:13]
	s_setprio 0
	s_setprio 1
	v_mfma_f32_16x16x32_bf16 v[54:57], v[146:149], v[162:165], v[54:57]
	v_mfma_f32_16x16x32_bf16 v[46:49], v[154:157], v[162:165], v[46:49]
	v_mfma_f32_16x16x32_bf16 v[38:41], v[146:149], v[170:173], v[38:41]
	v_mfma_f32_16x16x32_bf16 v[30:33], v[154:157], v[170:173], v[30:33]
	v_mfma_f32_16x16x32_bf16 v[22:25], v[146:149], v[178:181], v[22:25]
	v_mfma_f32_16x16x32_bf16 v[14:17], v[154:157], v[178:181], v[14:17]
	v_mfma_f32_16x16x32_bf16 v[6:9], v[146:149], v[210:213], v[6:9]
	v_mfma_f32_16x16x32_bf16 v[2:5], v[154:157], v[210:213], v[2:5]
	v_mfma_f32_16x16x32_bf16 v[54:57], v[150:153], v[166:169], v[54:57]
	v_mfma_f32_16x16x32_bf16 v[46:49], v[158:161], v[166:169], v[46:49]
	v_mfma_f32_16x16x32_bf16 v[38:41], v[150:153], v[174:177], v[38:41]
	v_mfma_f32_16x16x32_bf16 v[30:33], v[158:161], v[174:177], v[30:33]
	v_mfma_f32_16x16x32_bf16 v[22:25], v[150:153], v[206:209], v[22:25]
	v_mfma_f32_16x16x32_bf16 v[14:17], v[158:161], v[206:209], v[14:17]
	v_mfma_f32_16x16x32_bf16 v[6:9], v[150:153], v[214:217], v[6:9]
	v_mfma_f32_16x16x32_bf16 v[2:5], v[158:161], v[214:217], v[2:5]
	s_barrier
	s_setprio 0
	s_add_i32 s54, s54, 2
	s_add_u32 s20, s20, 0x100
	s_addc_u32 s21, s21, 0
	s_add_u32 s52, s52, 0x100
	s_addc_u32 s53, s53, 0
	s_cmp_gt_u32 s54, 29
	s_cbranch_scc0 .LBB0_2296
	s_and_b64 vcc, exec, s[8:9]
	s_cbranch_vccz .LBB0_2299
	s_barrier

; #define PG8_STAGE(bufoff, gbase, voff) do { _Pragma("unroll") for (int _i = 0; _i < 2; ++_i) \
;         __builtin_amdgcn_global_load_lds((const unsigned*)((const char*)(gbase) + (voff)[_i]), (PG8_LAS unsigned*)(lds + (bufoff) + ldsw + _i * 8192), 16, 0, 0); } while (0)
; #define PG8_WAIT_V(n) asm volatile("s_waitcnt vmcnt(" #n ")" ::: "memory")
; #define PG8_WAIT_L(n) asm volatile("s_waitcnt lgkmcnt(" #n ")" ::: "memory")
; #define PG8_BAR __builtin_amdgcn_s_barrier()
; #define PG8_SCHED __builtin_amdgcn_sched_barrier(0)
; template <class Epi, class Sched, bool ALIGN_EPI = true, bool SP2 = true>
; __device__ __forceinline__ void gemm_phase(PG8_LAS unsigned char* lds, const int K  , const Sched& S, const Epi& E) {
;     ...
;             const char* a1 = cA + (size_t)(t + 1) * kstep;
;             const char* a2 = last ? nA : cA + (size_t)(t + 2) * kstep; const char* b2 = last ? nB : cB + (size_t)(t + 2) * kstep;
;             const char* a3 = a2 + kstep; const char* b3 = b2 + kstep;
;             if constexpr (SP2) {
;             PG8_LDB(B0, 0, 0); PG8_LDB(B1, 0, 1); PG8_SCHED; PG8_LDA(At, 0, 0); PG8_STAGE(PG8_SA(1, 1), a1 + hstep, voffA);
;             PG8_WAIT_V(8); PG8_WAIT_L(0); PG8_BAR; PG8_MMA(0, 0, At, B0); PG8_MMA(0, 1, At, B1); PG8_BAR; PG8_SCHED;
;             PG8_LDA(At, 0, 1); PG8_STAGE(PG8_SB(0, 0), b2, voffB); PG8_STAGE(PG8_SB(0, 1), b2 + hstep, voffB); PG8_STAGE(PG8_SA(0, 0), a2, voffA);
;             PG8_WAIT_V(8); PG8_WAIT_L(0); PG8_BAR; PG8_MMA(1, 0, At, B0); PG8_MMA(1, 1, At, B1); PG8_BAR; PG8_SCHED;
.LBB0_2433:
	ds_read_b128 v[146:149], v152
	ds_read_b128 v[158:161], v152 offset:1024
	ds_read_b128 v[162:165], v152 offset:2048
	ds_read_b128 v[166:169], v152 offset:3072
	ds_read_b128 v[170:173], v153
	ds_read_b128 v[174:177], v153 offset:1024
	ds_read_b128 v[178:181], v153 offset:2048
	ds_read_b128 v[182:185], v153 offset:3072
	ds_read_b128 v[186:189], v154
	ds_read_b128 v[190:193], v154 offset:1024
	ds_read_b128 v[194:197], v154 offset:2048
	ds_read_b128 v[198:201], v154 offset:3072
	ds_read_b128 v[202:205], v154 offset:4096
	ds_read_b128 v[206:209], v154 offset:5120
	ds_read_b128 v[210:213], v154 offset:6144
	ds_read_b128 v[214:217], v154 offset:7168
	s_add_u32 s22, s20, 0xfff80080
	s_addc_u32 s23, s21, -1
	s_cmp_eq_u32 s48, 28
	s_cselect_b32 s25, s13, s23
	s_cselect_b32 s24, s44, s22
	s_cselect_b32 s23, s11, s47
	s_cselect_b32 s22, s45, s46
	s_add_i32 m0, s19, 0xc000
	v_lshl_add_u64 v[218:219], s[20:21], 0, v[138:139]
	global_load_lds_dwordx4 v[218:219], off
	v_lshl_add_u64 v[218:219], s[20:21], 0, v[140:141]
	s_add_i32 m0, s19, 0xe000
	s_nop 0
	global_load_lds_dwordx4 v[218:219], off
	s_waitcnt vmcnt(8)
	s_waitcnt lgkmcnt(0)
	s_setprio 1
	s_barrier
	v_mfma_f32_16x16x32_bf16 v[126:129], v[146:149], v[186:189], v[126:129]
	v_mfma_f32_16x16x32_bf16 v[118:121], v[162:165], v[186:189], v[118:121]
	v_mfma_f32_16x16x32_bf16 v[110:113], v[146:149], v[194:197], v[110:113]
	v_mfma_f32_16x16x32_bf16 v[102:105], v[162:165], v[194:197], v[102:105]
	v_mfma_f32_16x16x32_bf16 v[94:97], v[146:149], v[202:205], v[94:97]
	v_mfma_f32_16x16x32_bf16 v[86:89], v[162:165], v[202:205], v[86:89]
	v_mfma_f32_16x16x32_bf16 v[78:81], v[146:149], v[210:213], v[78:81]
	v_mfma_f32_16x16x32_bf16 v[70:73], v[162:165], v[210:213], v[70:73]
	v_mfma_f32_16x16x32_bf16 v[126:129], v[158:161], v[190:193], v[126:129]
	v_mfma_f32_16x16x32_bf16 v[118:121], v[166:169], v[190:193], v[118:121]
	v_mfma_f32_16x16x32_bf16 v[110:113], v[158:161], v[198:201], v[110:113]
	v_mfma_f32_16x16x32_bf16 v[102:105], v[166:169], v[198:201], v[102:105]
	v_mfma_f32_16x16x32_bf16 v[94:97], v[158:161], v[206:209], v[94:97]
	v_mfma_f32_16x16x32_bf16 v[86:89], v[166:169], v[206:209], v[86:89]
	v_mfma_f32_16x16x32_bf16 v[78:81], v[158:161], v[214:217], v[78:81]
	v_mfma_f32_16x16x32_bf16 v[70:73], v[166:169], v[214:217], v[70:73]
	s_setprio 0
	s_setprio 1
	v_mfma_f32_16x16x32_bf16 v[122:125], v[170:173], v[186:189], v[122:125]
	v_mfma_f32_16x16x32_bf16 v[114:117], v[178:181], v[186:189], v[114:117]
	v_mfma_f32_16x16x32_bf16 v[106:109], v[170:173], v[194:197], v[106:109]
	v_mfma_f32_16x16x32_bf16 v[98:101], v[178:181], v[194:197], v[98:101]
	v_mfma_f32_16x16x32_bf16 v[90:93], v[170:173], v[202:205], v[90:93]
	v_mfma_f32_16x16x32_bf16 v[82:85], v[178:181], v[202:205], v[82:85]
	v_mfma_f32_16x16x32_bf16 v[74:77], v[170:173], v[210:213], v[74:77]
	v_mfma_f32_16x16x32_bf16 v[66:69], v[178:181], v[210:213], v[66:69]
	v_mfma_f32_16x16x32_bf16 v[122:125], v[174:177], v[190:193], v[122:125]
	v_mfma_f32_16x16x32_bf16 v[114:117], v[182:185], v[190:193], v[114:117]
	v_mfma_f32_16x16x32_bf16 v[106:109], v[174:177], v[198:201], v[106:109]
	v_mfma_f32_16x16x32_bf16 v[98:101], v[182:185], v[198:201], v[98:101]
	v_mfma_f32_16x16x32_bf16 v[90:93], v[174:177], v[206:209], v[90:93]
	v_mfma_f32_16x16x32_bf16 v[82:85], v[182:185], v[206:209], v[82:85]
	v_mfma_f32_16x16x32_bf16 v[74:77], v[174:177], v[214:217], v[74:77]
	v_mfma_f32_16x16x32_bf16 v[66:69], v[182:185], v[214:217], v[66:69]
	s_barrier
	s_setprio 0
	s_add_i32 s49, s39, s28
	v_lshl_add_u64 v[218:219], s[22:23], 0, v[134:135]
	s_mov_b32 m0, s49
	ds_read_b128 v[186:189], v154 offset:16384
	ds_read_b128 v[190:193], v154 offset:17408
	ds_read_b128 v[194:197], v154 offset:18432
	ds_read_b128 v[198:201], v154 offset:19456
	ds_read_b128 v[202:205], v154 offset:20480
	ds_read_b128 v[206:209], v154 offset:21504
	ds_read_b128 v[210:213], v154 offset:22528
	ds_read_b128 v[214:217], v154 offset:23552
	global_load_lds_dwordx4 v[218:219], off
	s_add_i32 m0, s49, 0x2000
	s_add_u32 s50, s22, 0x80000
	v_lshl_add_u64 v[220:221], s[22:23], 0, v[130:131]
	s_addc_u32 s51, s23, 0
	s_add_i32 s49, s40, s28
	global_load_lds_dwordx4 v[220:221], off
	v_lshl_add_u64 v[222:223], s[50:51], 0, v[134:135]
	s_mov_b32 m0, s49
	v_lshl_add_u64 v[224:225], s[24:25], 0, v[132:133]
	global_load_lds_dwordx4 v[222:223], off
	v_lshl_add_u64 v[222:223], s[50:51], 0, v[130:131]
	s_add_i32 m0, s49, 0x2000
	s_nop 0
	global_load_lds_dwordx4 v[222:223], off
	v_lshl_add_u64 v[222:223], s[24:25], 0, v[136:137]
	s_mov_b32 m0, s19
	s_nop 0
	global_load_lds_dwordx4 v[222:223], off
	s_mov_b32 m0, s31
	s_nop 0
	global_load_lds_dwordx4 v[224:225], off
	s_waitcnt vmcnt(8)
	s_waitcnt lgkmcnt(0)
	s_setprio 1
	s_barrier
; #define PG8_STAGE(bufoff, gbase, voff) do { _Pragma("unroll") for (int _i = 0; _i < 2; ++_i) \
;         __builtin_amdgcn_global_load_lds((const unsigned*)((const char*)(gbase) + (voff)[_i]), (PG8_LAS unsigned*)(lds + (bufoff) + ldsw + _i * 8192), 16, 0, 0); } while (0)
; #define PG8_WAIT_V(n) asm volatile("s_waitcnt vmcnt(" #n ")" ::: "memory")
; #define PG8_WAIT_L(n) asm volatile("s_waitcnt lgkmcnt(" #n ")" ::: "memory")
; #define PG8_BAR __builtin_amdgcn_s_barrier()
; #define PG8_SCHED __builtin_amdgcn_sched_barrier(0)
; template <class Epi, class Sched, bool ALIGN_EPI = true, bool SP2 = true>
; __device__ __forceinline__ void gemm_phase(PG8_LAS unsigned char* lds, const int K  , const Sched& S, const Epi& E) {
;     ...
;             PG8_WAIT_V(8); PG8_WAIT_L(0); PG8_BAR; PG8_MMA(1, 0, At, B0); PG8_MMA(1, 1, At, B1); PG8_BAR; PG8_SCHED;
;             PG8_LDB(B0, 1, 0); PG8_LDB(B1, 1, 1); PG8_SCHED; PG8_LDA(At, 1, 0); PG8_STAGE(PG8_SA(0, 1), a2 + hstep, voffA);
;             PG8_WAIT_V(8); PG8_WAIT_L(0); PG8_BAR; PG8_MMA(0, 0, At, B0); PG8_MMA(0, 1, At, B1); PG8_BAR; PG8_SCHED;
	v_mfma_f32_16x16x32_bf16 v[62:65], v[146:149], v[186:189], v[62:65]
	v_mfma_f32_16x16x32_bf16 v[54:57], v[162:165], v[186:189], v[54:57]
	v_mfma_f32_16x16x32_bf16 v[46:49], v[146:149], v[194:197], v[46:49]
	v_mfma_f32_16x16x32_bf16 v[38:41], v[162:165], v[194:197], v[38:41]
	v_mfma_f32_16x16x32_bf16 v[30:33], v[146:149], v[202:205], v[30:33]
	v_mfma_f32_16x16x32_bf16 v[22:25], v[162:165], v[202:205], v[22:25]
	v_mfma_f32_16x16x32_bf16 v[14:17], v[146:149], v[210:213], v[14:17]
	v_mfma_f32_16x16x32_bf16 v[6:9], v[162:165], v[210:213], v[6:9]
	v_mfma_f32_16x16x32_bf16 v[62:65], v[158:161], v[190:193], v[62:65]
	v_mfma_f32_16x16x32_bf16 v[54:57], v[166:169], v[190:193], v[54:57]
	v_mfma_f32_16x16x32_bf16 v[46:49], v[158:161], v[198:201], v[46:49]
	v_mfma_f32_16x16x32_bf16 v[38:41], v[166:169], v[198:201], v[38:41]
	v_mfma_f32_16x16x32_bf16 v[30:33], v[158:161], v[206:209], v[30:33]
	v_mfma_f32_16x16x32_bf16 v[22:25], v[166:169], v[206:209], v[22:25]
	v_mfma_f32_16x16x32_bf16 v[14:17], v[158:161], v[214:217], v[14:17]
	v_mfma_f32_16x16x32_bf16 v[6:9], v[166:169], v[214:217], v[6:9]
	s_setprio 0
	s_setprio 1
	v_mfma_f32_16x16x32_bf16 v[58:61], v[170:173], v[186:189], v[58:61]
	v_mfma_f32_16x16x32_bf16 v[50:53], v[178:181], v[186:189], v[50:53]
	v_mfma_f32_16x16x32_bf16 v[42:45], v[170:173], v[194:197], v[42:45]
	v_mfma_f32_16x16x32_bf16 v[34:37], v[178:181], v[194:197], v[34:37]
	v_mfma_f32_16x16x32_bf16 v[26:29], v[170:173], v[202:205], v[26:29]
	v_mfma_f32_16x16x32_bf16 v[18:21], v[178:181], v[202:205], v[18:21]
	v_mfma_f32_16x16x32_bf16 v[10:13], v[170:173], v[210:213], v[10:13]
	v_mfma_f32_16x16x32_bf16 v[2:5], v[178:181], v[210:213], v[2:5]
	v_mfma_f32_16x16x32_bf16 v[58:61], v[174:177], v[190:193], v[58:61]
	v_mfma_f32_16x16x32_bf16 v[50:53], v[182:185], v[190:193], v[50:53]
	v_mfma_f32_16x16x32_bf16 v[42:45], v[174:177], v[198:201], v[42:45]
	v_mfma_f32_16x16x32_bf16 v[34:37], v[182:185], v[198:201], v[34:37]
	v_mfma_f32_16x16x32_bf16 v[26:29], v[174:177], v[206:209], v[26:29]
	v_mfma_f32_16x16x32_bf16 v[18:21], v[182:185], v[206:209], v[18:21]
	v_mfma_f32_16x16x32_bf16 v[10:13], v[174:177], v[214:217], v[10:13]
	v_mfma_f32_16x16x32_bf16 v[2:5], v[182:185], v[214:217], v[2:5]
	s_barrier
	s_setprio 0
	s_add_i32 s49, 0, 0x18000
	v_add_u32_e32 v157, s49, v150
	s_add_i32 s50, 0, 0x1c000
	ds_read_b128 v[146:149], v157
	ds_read_b128 v[158:161], v157 offset:1024
	ds_read_b128 v[162:165], v157 offset:2048
	ds_read_b128 v[166:169], v157 offset:3072
	v_add_u32_e32 v157, s50, v150
	ds_read_b128 v[170:173], v157
	ds_read_b128 v[174:177], v157 offset:1024
	ds_read_b128 v[178:181], v157 offset:2048
	ds_read_b128 v[182:185], v157 offset:3072
	ds_read_b128 v[186:189], v154 offset:32768
	ds_read_b128 v[190:193], v154 offset:33792
	ds_read_b128 v[194:197], v154 offset:34816
	ds_read_b128 v[198:201], v154 offset:35840
	ds_read_b128 v[202:205], v154 offset:36864
	ds_read_b128 v[206:209], v154 offset:37888
	ds_read_b128 v[210:213], v154 offset:38912
	ds_read_b128 v[214:217], v154 offset:39936
	s_add_u32 s24, s24, 0x80000
	s_addc_u32 s25, s25, 0
	s_mov_b32 m0, s33
	v_lshl_add_u64 v[226:227], s[24:25], 0, v[136:137]
	global_load_lds_dwordx4 v[226:227], off
	v_lshl_add_u64 v[226:227], s[24:25], 0, v[132:133]
	s_mov_b32 m0, s34
	s_nop 0
	global_load_lds_dwordx4 v[226:227], off
	s_waitcnt vmcnt(8)
	s_waitcnt lgkmcnt(0)
	s_setprio 1
	s_barrier
	v_mfma_f32_16x16x32_bf16 v[126:129], v[146:149], v[186:189], v[126:129]
	v_mfma_f32_16x16x32_bf16 v[118:121], v[162:165], v[186:189], v[118:121]
	v_mfma_f32_16x16x32_bf16 v[110:113], v[146:149], v[194:197], v[110:113]
	v_mfma_f32_16x16x32_bf16 v[102:105], v[162:165], v[194:197], v[102:105]
	v_mfma_f32_16x16x32_bf16 v[94:97], v[146:149], v[202:205], v[94:97]
	v_mfma_f32_16x16x32_bf16 v[86:89], v[162:165], v[202:205], v[86:89]
	v_mfma_f32_16x16x32_bf16 v[78:81], v[146:149], v[210:213], v[78:81]
	v_mfma_f32_16x16x32_bf16 v[70:73], v[162:165], v[210:213], v[70:73]
	v_mfma_f32_16x16x32_bf16 v[126:129], v[158:161], v[190:193], v[126:129]
	v_mfma_f32_16x16x32_bf16 v[118:121], v[166:169], v[190:193], v[118:121]
	v_mfma_f32_16x16x32_bf16 v[110:113], v[158:161], v[198:201], v[110:113]
	v_mfma_f32_16x16x32_bf16 v[102:105], v[166:169], v[198:201], v[102:105]
	v_mfma_f32_16x16x32_bf16 v[94:97], v[158:161], v[206:209], v[94:97]
	v_mfma_f32_16x16x32_bf16 v[86:89], v[166:169], v[206:209], v[86:89]
	v_mfma_f32_16x16x32_bf16 v[78:81], v[158:161], v[214:217], v[78:81]
	v_mfma_f32_16x16x32_bf16 v[70:73], v[166:169], v[214:217], v[70:73]
	s_setprio 0
	s_setprio 1
	v_mfma_f32_16x16x32_bf16 v[122:125], v[170:173], v[186:189], v[122:125]
	v_mfma_f32_16x16x32_bf16 v[114:117], v[178:181], v[186:189], v[114:117]
	v_mfma_f32_16x16x32_bf16 v[106:109], v[170:173], v[194:197], v[106:109]
	v_mfma_f32_16x16x32_bf16 v[98:101], v[178:181], v[194:197], v[98:101]
	v_mfma_f32_16x16x32_bf16 v[90:93], v[170:173], v[202:205], v[90:93]
	v_mfma_f32_16x16x32_bf16 v[82:85], v[178:181], v[202:205], v[82:85]
	v_mfma_f32_16x16x32_bf16 v[74:77], v[170:173], v[210:213], v[74:77]
	v_mfma_f32_16x16x32_bf16 v[66:69], v[178:181], v[210:213], v[66:69]
	v_mfma_f32_16x16x32_bf16 v[122:125], v[174:177], v[190:193], v[122:125]
	v_mfma_f32_16x16x32_bf16 v[114:117], v[182:185], v[190:193], v[114:117]
	v_mfma_f32_16x16x32_bf16 v[106:109], v[174:177], v[198:201], v[106:109]
	v_mfma_f32_16x16x32_bf16 v[98:101], v[182:185], v[198:201], v[98:101]
	v_mfma_f32_16x16x32_bf16 v[90:93], v[174:177], v[206:209], v[90:93]
	v_mfma_f32_16x16x32_bf16 v[82:85], v[182:185], v[206:209], v[82:85]
	v_mfma_f32_16x16x32_bf16 v[74:77], v[174:177], v[214:217], v[74:77]
	v_mfma_f32_16x16x32_bf16 v[66:69], v[182:185], v[214:217], v[66:69]
	s_barrier
; #define PG8_STAGE(bufoff, gbase, voff) do { _Pragma("unroll") for (int _i = 0; _i < 2; ++_i) \
;         __builtin_amdgcn_global_load_lds((const unsigned*)((const char*)(gbase) + (voff)[_i]), (PG8_LAS unsigned*)(lds + (bufoff) + ldsw + _i * 8192), 16, 0, 0); } while (0)
; #define PG8_WAIT_V(n) asm volatile("s_waitcnt vmcnt(" #n ")" ::: "memory")
; #define PG8_WAIT_L(n) asm volatile("s_waitcnt lgkmcnt(" #n ")" ::: "memory")
; #define PG8_BAR __builtin_amdgcn_s_barrier()
; #define PG8_SCHED __builtin_amdgcn_sched_barrier(0)
;     __device__ __forceinline__ int nt(const pg8::Unit& u) const { return u.kind == 0 ? ntiles : q_nt(u.kind - 1); }
; template <class Epi, class Sched, bool ALIGN_EPI = true, bool SP2 = true>
; __device__ __forceinline__ void gemm_phase(PG8_LAS unsigned char* lds, const int K  , const Sched& S, const Epi& E) {
;     ...
;         for (int t = 0; t < nt; t += 2) {
;             const bool last = (t == nt - 2);
;             const char* a1 = cA + (size_t)(t + 1) * kstep;
;             const char* a2 = last ? nA : cA + (size_t)(t + 2) * kstep; const char* b2 = last ? nB : cB + (size_t)(t + 2) * kstep;
;     ...
;             PG8_LDA(At, 1, 1); PG8_STAGE(PG8_SB(1, 0), b3, voffB); PG8_STAGE(PG8_SB(1, 1), b3 + hstep, voffB); PG8_STAGE(PG8_SA(1, 0), a3, voffA);
;             PG8_WAIT_V(8); PG8_WAIT_L(0); PG8_BAR; PG8_MMA(1, 0, At, B0); PG8_MMA(1, 1, At, B1); PG8_BAR; PG8_SCHED;
	s_setprio 0
	s_add_i32 s24, s49, s28
	v_lshl_add_u64 v[218:219], v[218:219], 0, s[6:7]
	s_mov_b32 m0, s24
	ds_read_b128 v[186:189], v154 offset:49152
	ds_read_b128 v[190:193], v154 offset:50176
	ds_read_b128 v[194:197], v154 offset:51200
	ds_read_b128 v[198:201], v154 offset:52224
	ds_read_b128 v[202:205], v154 offset:53248
	ds_read_b128 v[206:209], v154 offset:54272
	ds_read_b128 v[210:213], v154 offset:55296
	ds_read_b128 v[214:217], v154 offset:56320
	global_load_lds_dwordx4 v[218:219], off
	s_add_i32 m0, s24, 0x2000
	s_add_u32 s22, s22, 0x80080
	v_lshl_add_u64 v[218:219], v[220:221], 0, s[6:7]
	s_addc_u32 s23, s23, 0
	s_add_i32 s24, s50, s28
	global_load_lds_dwordx4 v[218:219], off
	v_lshl_add_u64 v[218:219], s[22:23], 0, v[134:135]
	s_mov_b32 m0, s24
	s_nop 0
	global_load_lds_dwordx4 v[218:219], off
	v_lshl_add_u64 v[218:219], s[22:23], 0, v[130:131]
	s_add_i32 m0, s24, 0x2000
	s_nop 0
	global_load_lds_dwordx4 v[218:219], off
	v_lshl_add_u64 v[218:219], v[222:223], 0, s[6:7]
	s_mov_b32 m0, s36
	s_nop 0
	global_load_lds_dwordx4 v[218:219], off
	v_lshl_add_u64 v[218:219], v[224:225], 0, s[6:7]
	s_mov_b32 m0, s37
	s_nop 0
	global_load_lds_dwordx4 v[218:219], off
	s_waitcnt vmcnt(8)
	s_waitcnt lgkmcnt(0)
	s_setprio 1
	s_barrier
	v_mfma_f32_16x16x32_bf16 v[62:65], v[146:149], v[186:189], v[62:65]
	v_mfma_f32_16x16x32_bf16 v[54:57], v[162:165], v[186:189], v[54:57]
	v_mfma_f32_16x16x32_bf16 v[46:49], v[146:149], v[194:197], v[46:49]
	v_mfma_f32_16x16x32_bf16 v[38:41], v[162:165], v[194:197], v[38:41]
	v_mfma_f32_16x16x32_bf16 v[30:33], v[146:149], v[202:205], v[30:33]
	v_mfma_f32_16x16x32_bf16 v[22:25], v[162:165], v[202:205], v[22:25]
	v_mfma_f32_16x16x32_bf16 v[14:17], v[146:149], v[210:213], v[14:17]
	v_mfma_f32_16x16x32_bf16 v[6:9], v[162:165], v[210:213], v[6:9]
	v_mfma_f32_16x16x32_bf16 v[62:65], v[158:161], v[190:193], v[62:65]
	v_mfma_f32_16x16x32_bf16 v[54:57], v[166:169], v[190:193], v[54:57]
	v_mfma_f32_16x16x32_bf16 v[46:49], v[158:161], v[198:201], v[46:49]
	v_mfma_f32_16x16x32_bf16 v[38:41], v[166:169], v[198:201], v[38:41]
	v_mfma_f32_16x16x32_bf16 v[30:33], v[158:161], v[206:209], v[30:33]
	v_mfma_f32_16x16x32_bf16 v[22:25], v[166:169], v[206:209], v[22:25]
	v_mfma_f32_16x16x32_bf16 v[14:17], v[158:161], v[214:217], v[14:17]
	v_mfma_f32_16x16x32_bf16 v[6:9], v[166:169], v[214:217], v[6:9]
	s_setprio 0
	s_setprio 1
	v_mfma_f32_16x16x32_bf16 v[58:61], v[170:173], v[186:189], v[58:61]
	v_mfma_f32_16x16x32_bf16 v[50:53], v[178:181], v[186:189], v[50:53]
	v_mfma_f32_16x16x32_bf16 v[42:45], v[170:173], v[194:197], v[42:45]
	v_mfma_f32_16x16x32_bf16 v[34:37], v[178:181], v[194:197], v[34:37]
	v_mfma_f32_16x16x32_bf16 v[26:29], v[170:173], v[202:205], v[26:29]
	v_mfma_f32_16x16x32_bf16 v[18:21], v[178:181], v[202:205], v[18:21]
	v_mfma_f32_16x16x32_bf16 v[10:13], v[170:173], v[210:213], v[10:13]
	v_mfma_f32_16x16x32_bf16 v[2:5], v[178:181], v[210:213], v[2:5]
	v_mfma_f32_16x16x32_bf16 v[58:61], v[174:177], v[190:193], v[58:61]
	v_mfma_f32_16x16x32_bf16 v[50:53], v[182:185], v[190:193], v[50:53]
	v_mfma_f32_16x16x32_bf16 v[42:45], v[174:177], v[198:201], v[42:45]
	v_mfma_f32_16x16x32_bf16 v[34:37], v[182:185], v[198:201], v[34:37]
	v_mfma_f32_16x16x32_bf16 v[26:29], v[174:177], v[206:209], v[26:29]
	v_mfma_f32_16x16x32_bf16 v[18:21], v[182:185], v[206:209], v[18:21]
	v_mfma_f32_16x16x32_bf16 v[10:13], v[174:177], v[214:217], v[10:13]
	v_mfma_f32_16x16x32_bf16 v[2:5], v[182:185], v[214:217], v[2:5]
	s_barrier
	s_setprio 0
	s_add_i32 s48, s48, 2
	s_add_u32 s20, s20, 0x100
	s_addc_u32 s21, s21, 0
	s_add_u32 s46, s46, 0x100
	s_addc_u32 s47, s47, 0
	s_cmp_gt_u32 s48, 29
	s_cbranch_scc0 .LBB0_2433
	s_and_b64 vcc, exec, s[8:9]
	s_cbranch_vccz .LBB0_2436
	s_barrier

; #define PG8_STAGE(bufoff, gbase, voff) do { _Pragma("unroll") for (int _i = 0; _i < 2; ++_i) \
;         __builtin_amdgcn_global_load_lds((const unsigned*)((const char*)(gbase) + (voff)[_i]), (PG8_LAS unsigned*)(lds + (bufoff) + ldsw + _i * 8192), 16, 0, 0); } while (0)
; #define PG8_WAIT_V(n) asm volatile("s_waitcnt vmcnt(" #n ")" ::: "memory")
; #define PG8_WAIT_L(n) asm volatile("s_waitcnt lgkmcnt(" #n ")" ::: "memory")
; #define PG8_BAR __builtin_amdgcn_s_barrier()
; #define PG8_SCHED __builtin_amdgcn_sched_barrier(0)
; template <class Epi, class Sched, bool ALIGN_EPI = true, bool SP2 = true>
; __device__ __forceinline__ void gemm_phase(PG8_LAS unsigned char* lds, const int K  , const Sched& S, const Epi& E) {
;     ...
;             const char* a1 = cA + (size_t)(t + 1) * kstep;
;             const char* a2 = last ? nA : cA + (size_t)(t + 2) * kstep; const char* b2 = last ? nB : cB + (size_t)(t + 2) * kstep;
;             const char* a3 = a2 + kstep; const char* b3 = b2 + kstep;
;             if constexpr (SP2) {
;             PG8_LDB(B0, 0, 0); PG8_LDB(B1, 0, 1); PG8_SCHED; PG8_LDA(At, 0, 0); PG8_STAGE(PG8_SA(1, 1), a1 + hstep, voffA);
;             PG8_WAIT_V(8); PG8_WAIT_L(0); PG8_BAR; PG8_MMA(0, 0, At, B0); PG8_MMA(0, 1, At, B1); PG8_BAR; PG8_SCHED;
;             PG8_LDA(At, 0, 1); PG8_STAGE(PG8_SB(0, 0), b2, voffB); PG8_STAGE(PG8_SB(0, 1), b2 + hstep, voffB); PG8_STAGE(PG8_SA(0, 0), a2, voffA);
;             PG8_WAIT_V(8); PG8_WAIT_L(0); PG8_BAR; PG8_MMA(1, 0, At, B0); PG8_MMA(1, 1, At, B1); PG8_BAR; PG8_SCHED;
.LBB0_2516:
	ds_read_b128 v[16:19], v206
	ds_read_b128 v[20:23], v206 offset:1024
	ds_read_b128 v[24:27], v206 offset:2048
	ds_read_b128 v[28:31], v206 offset:3072
	ds_read_b128 v[0:3], v207
	ds_read_b128 v[4:7], v207 offset:1024
	ds_read_b128 v[8:11], v207 offset:2048
	ds_read_b128 v[12:15], v207 offset:3072
	ds_read_b128 v[160:163], v208
	ds_read_b128 v[164:167], v208 offset:1024
	ds_read_b128 v[184:187], v208 offset:2048
	ds_read_b128 v[188:191], v208 offset:3072
	ds_read_b128 v[192:195], v208 offset:4096
	ds_read_b128 v[196:199], v208 offset:5120
	ds_read_b128 v[210:213], v208 offset:6144
	ds_read_b128 v[214:217], v208 offset:7168
	s_add_u32 s18, s16, 0xfff50080
	s_addc_u32 s19, s17, -1
	s_cmp_eq_u32 s57, 40
	s_cselect_b32 s21, s7, s19
	s_cselect_b32 s20, s6, s18
	s_cselect_b32 s19, s15, s56
	s_cselect_b32 s18, s14, s55
	s_add_i32 m0, s25, 0xc000
	v_lshl_add_u64 v[200:201], s[16:17], 0, v[176:177]
	global_load_lds_dwordx4 v[200:201], off
	v_lshl_add_u64 v[200:201], s[16:17], 0, v[178:179]
	s_add_i32 m0, s25, 0xe000
	s_nop 0
	global_load_lds_dwordx4 v[200:201], off
	s_waitcnt vmcnt(8)
	s_waitcnt lgkmcnt(0)
	s_setprio 1
	s_barrier
	v_mfma_scale_f32_16x16x128_f8f6f4 v[156:159], v[16:23], v[160:167], v[156:159], v202, v202 op_sel_hi:[0,0,0]
	v_mfma_scale_f32_16x16x128_f8f6f4 v[152:155], v[24:31], v[160:167], v[152:155], v202, v202 op_sel_hi:[0,0,0]
	v_mfma_scale_f32_16x16x128_f8f6f4 v[140:143], v[16:23], v[184:191], v[140:143], v202, v202 op_sel_hi:[0,0,0]
	v_mfma_scale_f32_16x16x128_f8f6f4 v[136:139], v[24:31], v[184:191], v[136:139], v202, v202 op_sel_hi:[0,0,0]
	v_mfma_scale_f32_16x16x128_f8f6f4 v[124:127], v[16:23], v[192:199], v[124:127], v202, v202 op_sel_hi:[0,0,0]
	v_mfma_scale_f32_16x16x128_f8f6f4 v[120:123], v[24:31], v[192:199], v[120:123], v202, v202 op_sel_hi:[0,0,0]
	v_mfma_scale_f32_16x16x128_f8f6f4 v[108:111], v[16:23], v[210:217], v[108:111], v202, v202 op_sel_hi:[0,0,0]
	v_mfma_scale_f32_16x16x128_f8f6f4 v[104:107], v[24:31], v[210:217], v[104:107], v202, v202 op_sel_hi:[0,0,0]
	s_setprio 0
	s_setprio 1
	v_mfma_scale_f32_16x16x128_f8f6f4 v[148:151], v[0:7], v[160:167], v[148:151], v202, v202 op_sel_hi:[0,0,0]
	v_mfma_scale_f32_16x16x128_f8f6f4 v[144:147], v[8:15], v[160:167], v[144:147], v202, v202 op_sel_hi:[0,0,0]
	v_mfma_scale_f32_16x16x128_f8f6f4 v[132:135], v[0:7], v[184:191], v[132:135], v202, v202 op_sel_hi:[0,0,0]
	v_mfma_scale_f32_16x16x128_f8f6f4 v[128:131], v[8:15], v[184:191], v[128:131], v202, v202 op_sel_hi:[0,0,0]
	v_mfma_scale_f32_16x16x128_f8f6f4 v[116:119], v[0:7], v[192:199], v[116:119], v202, v202 op_sel_hi:[0,0,0]
	v_mfma_scale_f32_16x16x128_f8f6f4 v[112:115], v[8:15], v[192:199], v[112:115], v202, v202 op_sel_hi:[0,0,0]
	v_mfma_scale_f32_16x16x128_f8f6f4 v[100:103], v[0:7], v[210:217], v[100:103], v202, v202 op_sel_hi:[0,0,0]
	v_mfma_scale_f32_16x16x128_f8f6f4 v[96:99], v[8:15], v[210:217], v[96:99], v202, v202 op_sel_hi:[0,0,0]
	s_barrier
	s_setprio 0
	s_add_i32 s58, s38, s24
	v_lshl_add_u64 v[160:161], s[18:19], 0, v[170:171]
	s_mov_b32 m0, s58
	ds_read_b128 v[184:187], v208 offset:16384
	ds_read_b128 v[188:191], v208 offset:17408
	ds_read_b128 v[192:195], v208 offset:18432
	ds_read_b128 v[196:199], v208 offset:19456
	ds_read_b128 v[210:213], v208 offset:20480
	ds_read_b128 v[214:217], v208 offset:21504
	ds_read_b128 v[218:221], v208 offset:22528
	ds_read_b128 v[222:225], v208 offset:23552
	global_load_lds_dwordx4 v[160:161], off
	s_add_i32 m0, s58, 0x2000
	s_add_u32 s58, s18, 0xb0000
	v_lshl_add_u64 v[162:163], s[18:19], 0, v[174:175]
	s_addc_u32 s59, s19, 0
	s_add_i32 s60, s39, s24
	global_load_lds_dwordx4 v[162:163], off
	v_lshl_add_u64 v[164:165], s[58:59], 0, v[170:171]
	s_mov_b32 m0, s60
	v_lshl_add_u64 v[166:167], s[20:21], 0, v[172:173]
	global_load_lds_dwordx4 v[164:165], off
	v_lshl_add_u64 v[164:165], s[58:59], 0, v[174:175]
	s_add_i32 m0, s60, 0x2000
	s_nop 0
	global_load_lds_dwordx4 v[164:165], off
	v_lshl_add_u64 v[164:165], s[20:21], 0, v[168:169]
	s_mov_b32 m0, s25
	s_nop 0
	global_load_lds_dwordx4 v[164:165], off
	s_mov_b32 m0, s26
	s_nop 0
	global_load_lds_dwordx4 v[166:167], off
	s_waitcnt vmcnt(8)
	s_waitcnt lgkmcnt(0)
	s_setprio 1
	s_barrier
	v_mfma_scale_f32_16x16x128_f8f6f4 v[92:95], v[16:23], v[184:191], v[92:95], v202, v202 op_sel_hi:[0,0,0]
	v_mfma_scale_f32_16x16x128_f8f6f4 v[88:91], v[24:31], v[184:191], v[88:91], v202, v202 op_sel_hi:[0,0,0]
	v_mfma_scale_f32_16x16x128_f8f6f4 v[76:79], v[16:23], v[192:199], v[76:79], v202, v202 op_sel_hi:[0,0,0]
	v_mfma_scale_f32_16x16x128_f8f6f4 v[72:75], v[24:31], v[192:199], v[72:75], v202, v202 op_sel_hi:[0,0,0]
	v_mfma_scale_f32_16x16x128_f8f6f4 v[60:63], v[16:23], v[210:217], v[60:63], v202, v202 op_sel_hi:[0,0,0]
	v_mfma_scale_f32_16x16x128_f8f6f4 v[56:59], v[24:31], v[210:217], v[56:59], v202, v202 op_sel_hi:[0,0,0]
	v_mfma_scale_f32_16x16x128_f8f6f4 v[44:47], v[16:23], v[218:225], v[44:47], v202, v202 op_sel_hi:[0,0,0]
	v_mfma_scale_f32_16x16x128_f8f6f4 v[40:43], v[24:31], v[218:225], v[40:43], v202, v202 op_sel_hi:[0,0,0]
	s_setprio 0
	s_setprio 1
	v_mfma_scale_f32_16x16x128_f8f6f4 v[84:87], v[0:7], v[184:191], v[84:87], v202, v202 op_sel_hi:[0,0,0]
	v_mfma_scale_f32_16x16x128_f8f6f4 v[80:83], v[8:15], v[184:191], v[80:83], v202, v202 op_sel_hi:[0,0,0]
	v_mfma_scale_f32_16x16x128_f8f6f4 v[68:71], v[0:7], v[192:199], v[68:71], v202, v202 op_sel_hi:[0,0,0]
	v_mfma_scale_f32_16x16x128_f8f6f4 v[64:67], v[8:15], v[192:199], v[64:67], v202, v202 op_sel_hi:[0,0,0]
	v_mfma_scale_f32_16x16x128_f8f6f4 v[52:55], v[0:7], v[210:217], v[52:55], v202, v202 op_sel_hi:[0,0,0]
	v_mfma_scale_f32_16x16x128_f8f6f4 v[48:51], v[8:15], v[210:217], v[48:51], v202, v202 op_sel_hi:[0,0,0]
	v_mfma_scale_f32_16x16x128_f8f6f4 v[36:39], v[0:7], v[218:225], v[36:39], v202, v202 op_sel_hi:[0,0,0]
	v_mfma_scale_f32_16x16x128_f8f6f4 v[32:35], v[8:15], v[218:225], v[32:35], v202, v202 op_sel_hi:[0,0,0]
	s_barrier
; #define PG8_STAGE(bufoff, gbase, voff) do { _Pragma("unroll") for (int _i = 0; _i < 2; ++_i) \
;         __builtin_amdgcn_global_load_lds((const unsigned*)((const char*)(gbase) + (voff)[_i]), (PG8_LAS unsigned*)(lds + (bufoff) + ldsw + _i * 8192), 16, 0, 0); } while (0)
; #define PG8_WAIT_V(n) asm volatile("s_waitcnt vmcnt(" #n ")" ::: "memory")
; #define PG8_WAIT_L(n) asm volatile("s_waitcnt lgkmcnt(" #n ")" ::: "memory")
; #define PG8_BAR __builtin_amdgcn_s_barrier()
; #define PG8_SCHED __builtin_amdgcn_sched_barrier(0)
; template <class Epi, class Sched, bool ALIGN_EPI = true, bool SP2 = true>
; __device__ __forceinline__ void gemm_phase(PG8_LAS unsigned char* lds, const int K  , const Sched& S, const Epi& E) {
;     ...
;             PG8_WAIT_V(8); PG8_WAIT_L(0); PG8_BAR; PG8_MMA(1, 0, At, B0); PG8_MMA(1, 1, At, B1); PG8_BAR; PG8_SCHED;
;             PG8_LDB(B0, 1, 0); PG8_LDB(B1, 1, 1); PG8_SCHED; PG8_LDA(At, 1, 0); PG8_STAGE(PG8_SA(0, 1), a2 + hstep, voffA);
;             PG8_WAIT_V(8); PG8_WAIT_L(0); PG8_BAR; PG8_MMA(0, 0, At, B0); PG8_MMA(0, 1, At, B1); PG8_BAR; PG8_SCHED;
;             PG8_LDA(At, 1, 1); PG8_STAGE(PG8_SB(1, 0), b3, voffB); PG8_STAGE(PG8_SB(1, 1), b3 + hstep, voffB); PG8_STAGE(PG8_SA(1, 0), a3, voffA);
;             PG8_WAIT_V(8); PG8_WAIT_L(0); PG8_BAR; PG8_MMA(1, 0, At, B0); PG8_MMA(1, 1, At, B1); PG8_BAR; PG8_SCHED;
;     ...
;         if constexpr (Epi::FP8) asm volatile("s_nop 15\n\ts_nop 15\n\ts_nop 15\n\ts_nop 15\n\ts_nop 15" ::: "memory");
	s_setprio 0
	s_add_i32 s58, 0, 0x18000
	s_add_i32 s59, 0, 0x1c000
	v_add_u32_e32 v12, s58, v204
	v_add_u32_e32 v28, s59, v204
	ds_read_b128 v[0:3], v12
	ds_read_b128 v[4:7], v12 offset:1024
	ds_read_b128 v[8:11], v12 offset:2048
	ds_read_b128 v[12:15], v12 offset:3072
	ds_read_b128 v[16:19], v28
	ds_read_b128 v[20:23], v28 offset:1024
	ds_read_b128 v[24:27], v28 offset:2048
	ds_read_b128 v[28:31], v28 offset:3072
	ds_read_b128 v[184:187], v208 offset:32768
	ds_read_b128 v[188:191], v208 offset:33792
	ds_read_b128 v[192:195], v208 offset:34816
	ds_read_b128 v[196:199], v208 offset:35840
	ds_read_b128 v[210:213], v208 offset:36864
	ds_read_b128 v[214:217], v208 offset:37888
	ds_read_b128 v[218:221], v208 offset:38912
	ds_read_b128 v[222:225], v208 offset:39936
	s_add_u32 s20, s20, 0xb0000
	s_addc_u32 s21, s21, 0
	s_mov_b32 m0, s27
	v_lshl_add_u64 v[200:201], s[20:21], 0, v[168:169]
	global_load_lds_dwordx4 v[200:201], off
	v_lshl_add_u64 v[200:201], s[20:21], 0, v[172:173]
	s_mov_b32 m0, s28
	s_nop 0
	global_load_lds_dwordx4 v[200:201], off
	s_waitcnt vmcnt(8)
	s_waitcnt lgkmcnt(0)
	s_setprio 1
	s_barrier
	v_mfma_scale_f32_16x16x128_f8f6f4 v[156:159], v[0:7], v[184:191], v[156:159], v202, v202 op_sel_hi:[0,0,0]
	v_mfma_scale_f32_16x16x128_f8f6f4 v[152:155], v[8:15], v[184:191], v[152:155], v202, v202 op_sel_hi:[0,0,0]
	v_mfma_scale_f32_16x16x128_f8f6f4 v[140:143], v[0:7], v[192:199], v[140:143], v202, v202 op_sel_hi:[0,0,0]
	v_mfma_scale_f32_16x16x128_f8f6f4 v[136:139], v[8:15], v[192:199], v[136:139], v202, v202 op_sel_hi:[0,0,0]
	v_mfma_scale_f32_16x16x128_f8f6f4 v[124:127], v[0:7], v[210:217], v[124:127], v202, v202 op_sel_hi:[0,0,0]
	v_mfma_scale_f32_16x16x128_f8f6f4 v[120:123], v[8:15], v[210:217], v[120:123], v202, v202 op_sel_hi:[0,0,0]
	v_mfma_scale_f32_16x16x128_f8f6f4 v[108:111], v[0:7], v[218:225], v[108:111], v202, v202 op_sel_hi:[0,0,0]
	v_mfma_scale_f32_16x16x128_f8f6f4 v[104:107], v[8:15], v[218:225], v[104:107], v202, v202 op_sel_hi:[0,0,0]
	s_setprio 0
	s_setprio 1
	v_mfma_scale_f32_16x16x128_f8f6f4 v[148:151], v[16:23], v[184:191], v[148:151], v202, v202 op_sel_hi:[0,0,0]
	v_mfma_scale_f32_16x16x128_f8f6f4 v[144:147], v[24:31], v[184:191], v[144:147], v202, v202 op_sel_hi:[0,0,0]
	v_mfma_scale_f32_16x16x128_f8f6f4 v[132:135], v[16:23], v[192:199], v[132:135], v202, v202 op_sel_hi:[0,0,0]
	v_mfma_scale_f32_16x16x128_f8f6f4 v[128:131], v[24:31], v[192:199], v[128:131], v202, v202 op_sel_hi:[0,0,0]
	v_mfma_scale_f32_16x16x128_f8f6f4 v[116:119], v[16:23], v[210:217], v[116:119], v202, v202 op_sel_hi:[0,0,0]
	v_mfma_scale_f32_16x16x128_f8f6f4 v[112:115], v[24:31], v[210:217], v[112:115], v202, v202 op_sel_hi:[0,0,0]
	v_mfma_scale_f32_16x16x128_f8f6f4 v[100:103], v[16:23], v[218:225], v[100:103], v202, v202 op_sel_hi:[0,0,0]
	v_mfma_scale_f32_16x16x128_f8f6f4 v[96:99], v[24:31], v[218:225], v[96:99], v202, v202 op_sel_hi:[0,0,0]
	s_barrier
	s_setprio 0
	s_add_i32 s20, s58, s24
	v_lshl_add_u64 v[160:161], v[160:161], 0, s[8:9]
	s_mov_b32 m0, s20
	ds_read_b128 v[184:187], v208 offset:49152
	ds_read_b128 v[188:191], v208 offset:50176
	ds_read_b128 v[192:195], v208 offset:51200
	ds_read_b128 v[196:199], v208 offset:52224
	ds_read_b128 v[210:213], v208 offset:53248
	ds_read_b128 v[214:217], v208 offset:54272
	ds_read_b128 v[218:221], v208 offset:55296
	ds_read_b128 v[222:225], v208 offset:56320
	global_load_lds_dwordx4 v[160:161], off
	s_add_i32 m0, s20, 0x2000
	s_add_u32 s18, s18, 0xb0080
	v_lshl_add_u64 v[160:161], v[162:163], 0, s[8:9]
	s_addc_u32 s19, s19, 0
	s_add_i32 s20, s59, s24
	global_load_lds_dwordx4 v[160:161], off
	v_lshl_add_u64 v[160:161], s[18:19], 0, v[170:171]
	s_mov_b32 m0, s20
	s_nop 0
	global_load_lds_dwordx4 v[160:161], off
	v_lshl_add_u64 v[160:161], s[18:19], 0, v[174:175]
	s_add_i32 m0, s20, 0x2000
	s_nop 0
	global_load_lds_dwordx4 v[160:161], off
	v_lshl_add_u64 v[160:161], v[164:165], 0, s[8:9]
	s_mov_b32 m0, s35
	s_nop 0
	global_load_lds_dwordx4 v[160:161], off
	v_lshl_add_u64 v[160:161], v[166:167], 0, s[8:9]
	s_mov_b32 m0, s36
	s_nop 0
	global_load_lds_dwordx4 v[160:161], off
	s_waitcnt vmcnt(8)
	s_waitcnt lgkmcnt(0)
	s_setprio 1
	s_barrier
	v_mfma_scale_f32_16x16x128_f8f6f4 v[92:95], v[0:7], v[184:191], v[92:95], v202, v202 op_sel_hi:[0,0,0]
	v_mfma_scale_f32_16x16x128_f8f6f4 v[88:91], v[8:15], v[184:191], v[88:91], v202, v202 op_sel_hi:[0,0,0]
	v_mfma_scale_f32_16x16x128_f8f6f4 v[76:79], v[0:7], v[192:199], v[76:79], v202, v202 op_sel_hi:[0,0,0]
	v_mfma_scale_f32_16x16x128_f8f6f4 v[72:75], v[8:15], v[192:199], v[72:75], v202, v202 op_sel_hi:[0,0,0]
	v_mfma_scale_f32_16x16x128_f8f6f4 v[60:63], v[0:7], v[210:217], v[60:63], v202, v202 op_sel_hi:[0,0,0]
	v_mfma_scale_f32_16x16x128_f8f6f4 v[56:59], v[8:15], v[210:217], v[56:59], v202, v202 op_sel_hi:[0,0,0]
	v_mfma_scale_f32_16x16x128_f8f6f4 v[44:47], v[0:7], v[218:225], v[44:47], v202, v202 op_sel_hi:[0,0,0]
	v_mfma_scale_f32_16x16x128_f8f6f4 v[40:43], v[8:15], v[218:225], v[40:43], v202, v202 op_sel_hi:[0,0,0]
	s_setprio 0
	s_setprio 1
	v_mfma_scale_f32_16x16x128_f8f6f4 v[84:87], v[16:23], v[184:191], v[84:87], v202, v202 op_sel_hi:[0,0,0]
	v_mfma_scale_f32_16x16x128_f8f6f4 v[80:83], v[24:31], v[184:191], v[80:83], v202, v202 op_sel_hi:[0,0,0]
	v_mfma_scale_f32_16x16x128_f8f6f4 v[68:71], v[16:23], v[192:199], v[68:71], v202, v202 op_sel_hi:[0,0,0]
	v_mfma_scale_f32_16x16x128_f8f6f4 v[64:67], v[24:31], v[192:199], v[64:67], v202, v202 op_sel_hi:[0,0,0]
	v_mfma_scale_f32_16x16x128_f8f6f4 v[52:55], v[16:23], v[210:217], v[52:55], v202, v202 op_sel_hi:[0,0,0]
	v_mfma_scale_f32_16x16x128_f8f6f4 v[48:51], v[24:31], v[210:217], v[48:51], v202, v202 op_sel_hi:[0,0,0]
	v_mfma_scale_f32_16x16x128_f8f6f4 v[36:39], v[16:23], v[218:225], v[36:39], v202, v202 op_sel_hi:[0,0,0]
	v_mfma_scale_f32_16x16x128_f8f6f4 v[32:35], v[24:31], v[218:225], v[32:35], v202, v202 op_sel_hi:[0,0,0]
	s_barrier
	s_setprio 0
	s_add_i32 s57, s57, 2
	s_add_u32 s16, s16, 0x100
	s_addc_u32 s17, s17, 0
	s_add_u32 s55, s55, 0x100
	s_addc_u32 s56, s56, 0
	s_cmp_gt_u32 s57, 41
	s_cbranch_scc0 .LBB0_2516
	s_nop 15
	s_nop 15
	s_nop 15
	s_nop 15
	s_nop 15
	s_and_b64 vcc, exec, s[10:11]
	s_cbranch_vccz .LBB0_2519
	s_barrier
